# K-loop back-edge pointer increments and trip test hoisted above the closing barrier of the last phase (7 GEMM loops), on v32
# baseline (speedup 1.0000x reference)
; #define PG8_STAGE(bufoff, gbase, voff) do { _Pragma("unroll") for (int _i = 0; _i < 2; ++_i) \
;         __builtin_amdgcn_global_load_lds((const unsigned*)((const char*)(gbase) + (voff)[_i]), (LAS unsigned*)(lds + (bufoff) + ldsw + _i * 8192), 16, 0, 0); } while (0)
; #define PG8_LDA(dst, b, h) do { _Pragma("unroll") for (int m = 0; m < 4; ++m) _Pragma("unroll") for (int k = 0; k < 2; ++k) dst[m][k] = *(const LAS bf16x8*)(lds + PG8_SA(b, h) + aoff + m * 2048 + k * 1024); } while (0)
; #define PG8_LDB(dst, b, h) do { _Pragma("unroll") for (int n = 0; n < 2; ++n) _Pragma("unroll") for (int k = 0; k < 2; ++k) dst[n][k] = *(const LAS bf16x8*)(lds + PG8_SB(b, h) + boff + n * 2048 + k * 1024); } while (0)
; #define PG8_MMA(ai, bj, At, Bt) do { __builtin_amdgcn_s_setprio(1); _Pragma("unroll") for (int m = 0; m < 4; ++m) _Pragma("unroll") for (int n = 0; n < 2; ++n) _Pragma("unroll") for (int k = 0; k < 2; ++k) \
;         acc[ai][bj][m][n] = __builtin_amdgcn_mfma_f32_16x16x32_bf16(Bt[n][k], At[m][k], acc[ai][bj][m][n], 0, 0, 0); __builtin_amdgcn_s_setprio(0); } while (0)
; #define PG8_WAIT_V(n) asm volatile("s_waitcnt vmcnt(" #n ")" ::: "memory")
; #define PG8_WAIT_L(n) asm volatile("s_waitcnt lgkmcnt(" #n ")" ::: "memory")
; #define PG8_BAR __builtin_amdgcn_s_barrier()
; #define PG8_SCHED __builtin_amdgcn_sched_barrier(0)
; template <class Epi>
; __device__ __forceinline__ void gemm_phase(LAS unsigned char* lds, const Gemm g, const StaticOrder& S, const Epi& E) {
;     ...
;         for (int t = 0; t < nt; t += 2) {
;             const bool last = (t == nt - 2);
;             const char* a1 = cA + (size_t)(t + 1) * kstep;
;             const char* a2 = last ? nA : cA + (size_t)(t + 2) * kstep; const char* b2 = last ? nB : cB + (size_t)(t + 2) * kstep;
;             const char* a3 = a2 + kstep; const char* b3 = b2 + kstep;
;             PG8_LDB(B0, 0, 0); PG8_LDB(B1, 0, 1); PG8_SCHED; PG8_LDA(At, 0, 0); PG8_STAGE(PG8_SA(1, 1), a1 + hstepA, voffA);
;             PG8_WAIT_V(8); PG8_WAIT_L(0); PG8_BAR; PG8_MMA(0, 0, At, B0); PG8_MMA(0, 1, At, B1); PG8_BAR; PG8_SCHED;
;             PG8_LDA(At, 0, 1); PG8_STAGE(PG8_SB(0, 0), b2, voffB); PG8_STAGE(PG8_SB(0, 1), b2 + hstepB, voffB); PG8_STAGE(PG8_SA(0, 0), a2, voffA);
.LBB0_245:
	ds_read_b128 v[152:155], v148
	ds_read_b128 v[156:159], v148 offset:1024
	ds_read_b128 v[160:163], v148 offset:2048
	ds_read_b128 v[164:167], v148 offset:3072
	ds_read_b128 v[168:171], v149
	ds_read_b128 v[172:175], v149 offset:1024
	ds_read_b128 v[176:179], v149 offset:2048
	ds_read_b128 v[180:183], v149 offset:3072
	s_add_i32 s64, s26, 2
	s_add_u32 s27, s24, 0xfff80080
	s_addc_u32 s30, s25, -1
	s_cmp_eq_u32 s54, s26
	s_cselect_b32 s26, s61, s62
	s_cselect_b32 s31, s15, s30
	s_cselect_b32 s30, s17, s27
	s_cselect_b32 s27, s60, s63
	v_lshl_add_u64 v[220:221], s[24:25], 0, v[138:139]
	s_add_i32 m0, s44, 0xc000
	ds_read_b128 v[184:187], v150
	ds_read_b128 v[188:191], v150 offset:1024
	ds_read_b128 v[192:195], v150 offset:2048
	ds_read_b128 v[196:199], v150 offset:3072
	ds_read_b128 v[200:203], v150 offset:4096
	ds_read_b128 v[208:211], v150 offset:5120
	ds_read_b128 v[212:215], v150 offset:6144
	ds_read_b128 v[216:219], v150 offset:7168
	global_load_lds_dwordx4 v[220:221], off
	v_lshl_add_u64 v[220:221], s[24:25], 0, v[140:141]
	s_add_i32 m0, s44, 0xe000
	s_nop 0
	global_load_lds_dwordx4 v[220:221], off
	s_waitcnt vmcnt(8)
	s_waitcnt lgkmcnt(0)
	s_barrier
	s_setprio 1
	s_waitcnt lgkmcnt(0)
	v_mfma_f32_16x16x32_bf16 v[120:123], v[152:155], v[184:187], v[120:123]
	v_mfma_f32_16x16x32_bf16 v[120:123], v[156:159], v[188:191], v[120:123]
	v_mfma_f32_16x16x32_bf16 v[116:119], v[164:167], v[188:191], v[116:119]
	v_mfma_f32_16x16x32_bf16 v[116:119], v[160:163], v[184:187], v[116:119]
	v_mfma_f32_16x16x32_bf16 v[124:127], v[168:171], v[184:187], v[124:127]
	v_mfma_f32_16x16x32_bf16 v[124:127], v[172:175], v[188:191], v[124:127]
	v_mfma_f32_16x16x32_bf16 v[112:115], v[180:183], v[188:191], v[112:115]
	v_mfma_f32_16x16x32_bf16 v[112:115], v[176:179], v[184:187], v[112:115]
	v_mfma_f32_16x16x32_bf16 v[96:99], v[176:179], v[192:195], v[96:99]
	v_mfma_f32_16x16x32_bf16 v[96:99], v[180:183], v[196:199], v[96:99]
	v_mfma_f32_16x16x32_bf16 v[104:107], v[172:175], v[196:199], v[104:107]
	v_mfma_f32_16x16x32_bf16 v[104:107], v[168:171], v[192:195], v[104:107]
	v_mfma_f32_16x16x32_bf16 v[100:103], v[160:163], v[192:195], v[100:103]
	v_mfma_f32_16x16x32_bf16 v[100:103], v[164:167], v[196:199], v[100:103]
	v_mfma_f32_16x16x32_bf16 v[108:111], v[156:159], v[196:199], v[108:111]
	v_mfma_f32_16x16x32_bf16 v[108:111], v[152:155], v[192:195], v[108:111]
	s_setprio 0
	s_setprio 1
	v_mfma_f32_16x16x32_bf16 v[92:95], v[152:155], v[200:203], v[92:95]
	v_mfma_f32_16x16x32_bf16 v[92:95], v[156:159], v[208:211], v[92:95]
	v_mfma_f32_16x16x32_bf16 v[84:87], v[164:167], v[208:211], v[84:87]
	v_mfma_f32_16x16x32_bf16 v[84:87], v[160:163], v[200:203], v[84:87]
	v_mfma_f32_16x16x32_bf16 v[88:91], v[168:171], v[200:203], v[88:91]
	v_mfma_f32_16x16x32_bf16 v[88:91], v[172:175], v[208:211], v[88:91]
	v_mfma_f32_16x16x32_bf16 v[80:83], v[180:183], v[208:211], v[80:83]
	v_mfma_f32_16x16x32_bf16 v[80:83], v[176:179], v[200:203], v[80:83]
	v_mfma_f32_16x16x32_bf16 v[64:67], v[176:179], v[212:215], v[64:67]
	v_mfma_f32_16x16x32_bf16 v[64:67], v[180:183], v[216:219], v[64:67]
	v_mfma_f32_16x16x32_bf16 v[72:75], v[172:175], v[216:219], v[72:75]
	v_mfma_f32_16x16x32_bf16 v[72:75], v[168:171], v[212:215], v[72:75]
	v_mfma_f32_16x16x32_bf16 v[68:71], v[160:163], v[212:215], v[68:71]
	v_mfma_f32_16x16x32_bf16 v[68:71], v[164:167], v[216:219], v[68:71]
	v_mfma_f32_16x16x32_bf16 v[76:79], v[156:159], v[216:219], v[76:79]
	v_mfma_f32_16x16x32_bf16 v[76:79], v[152:155], v[212:215], v[76:79]
	s_setprio 0
	s_barrier
	s_add_i32 s65, s57, s33
	v_lshl_add_u64 v[220:221], s[26:27], 0, v[132:133]
	s_mov_b32 m0, s65
	ds_read_b128 v[184:187], v150 offset:16384
	ds_read_b128 v[188:191], v150 offset:17408
	ds_read_b128 v[192:195], v150 offset:18432
	ds_read_b128 v[196:199], v150 offset:19456
	ds_read_b128 v[200:203], v150 offset:20480
	ds_read_b128 v[208:211], v150 offset:21504
	ds_read_b128 v[212:215], v150 offset:22528
	ds_read_b128 v[216:219], v150 offset:23552
	global_load_lds_dwordx4 v[220:221], off
	s_add_i32 m0, s65, 0x2000
	s_add_u32 s66, s26, 0x80000
	v_lshl_add_u64 v[222:223], s[26:27], 0, v[128:129]
	s_addc_u32 s67, s27, 0
	s_add_i32 s65, s58, s33
	global_load_lds_dwordx4 v[222:223], off
	v_lshl_add_u64 v[224:225], s[66:67], 0, v[132:133]
	s_mov_b32 m0, s65
	v_lshl_add_u64 v[226:227], s[30:31], 0, v[130:131]
	global_load_lds_dwordx4 v[224:225], off
	v_lshl_add_u64 v[224:225], s[66:67], 0, v[128:129]
	s_add_i32 m0, s65, 0x2000
	s_nop 0
	global_load_lds_dwordx4 v[224:225], off
	v_lshl_add_u64 v[224:225], s[30:31], 0, v[134:135]
	s_mov_b32 m0, s44
	s_nop 0
	global_load_lds_dwordx4 v[224:225], off
	s_mov_b32 m0, s45
	s_nop 0
	global_load_lds_dwordx4 v[226:227], off
	s_waitcnt vmcnt(8)
	s_waitcnt lgkmcnt(0)
	s_barrier
; #define PG8_STAGE(bufoff, gbase, voff) do { _Pragma("unroll") for (int _i = 0; _i < 2; ++_i) \
;         __builtin_amdgcn_global_load_lds((const unsigned*)((const char*)(gbase) + (voff)[_i]), (LAS unsigned*)(lds + (bufoff) + ldsw + _i * 8192), 16, 0, 0); } while (0)
; #define PG8_LDA(dst, b, h) do { _Pragma("unroll") for (int m = 0; m < 4; ++m) _Pragma("unroll") for (int k = 0; k < 2; ++k) dst[m][k] = *(const LAS bf16x8*)(lds + PG8_SA(b, h) + aoff + m * 2048 + k * 1024); } while (0)
; #define PG8_LDB(dst, b, h) do { _Pragma("unroll") for (int n = 0; n < 2; ++n) _Pragma("unroll") for (int k = 0; k < 2; ++k) dst[n][k] = *(const LAS bf16x8*)(lds + PG8_SB(b, h) + boff + n * 2048 + k * 1024); } while (0)
; #define PG8_MMA(ai, bj, At, Bt) do { __builtin_amdgcn_s_setprio(1); _Pragma("unroll") for (int m = 0; m < 4; ++m) _Pragma("unroll") for (int n = 0; n < 2; ++n) _Pragma("unroll") for (int k = 0; k < 2; ++k) \
;         acc[ai][bj][m][n] = __builtin_amdgcn_mfma_f32_16x16x32_bf16(Bt[n][k], At[m][k], acc[ai][bj][m][n], 0, 0, 0); __builtin_amdgcn_s_setprio(0); } while (0)
; #define PG8_WAIT_V(n) asm volatile("s_waitcnt vmcnt(" #n ")" ::: "memory")
; #define PG8_WAIT_L(n) asm volatile("s_waitcnt lgkmcnt(" #n ")" ::: "memory")
; #define PG8_BAR __builtin_amdgcn_s_barrier()
; #define PG8_SCHED __builtin_amdgcn_sched_barrier(0)
; template <class Epi>
; __device__ __forceinline__ void gemm_phase(LAS unsigned char* lds, const Gemm g, const StaticOrder& S, const Epi& E) {
;     ...
;             PG8_WAIT_V(8); PG8_WAIT_L(0); PG8_BAR; PG8_MMA(1, 0, At, B0); PG8_MMA(1, 1, At, B1); PG8_BAR; PG8_SCHED;
;             PG8_LDB(B0, 1, 0); PG8_LDB(B1, 1, 1); PG8_SCHED; PG8_LDA(At, 1, 0); PG8_STAGE(PG8_SA(0, 1), a2 + hstepA, voffA);
;             PG8_WAIT_V(8); PG8_WAIT_L(0); PG8_BAR; PG8_MMA(0, 0, At, B0); PG8_MMA(0, 1, At, B1); PG8_BAR; PG8_SCHED;
	s_setprio 1
	s_waitcnt lgkmcnt(0)
	v_mfma_f32_16x16x32_bf16 v[60:63], v[152:155], v[184:187], v[60:63]
	v_mfma_f32_16x16x32_bf16 v[60:63], v[156:159], v[188:191], v[60:63]
	v_mfma_f32_16x16x32_bf16 v[52:55], v[164:167], v[188:191], v[52:55]
	v_mfma_f32_16x16x32_bf16 v[52:55], v[160:163], v[184:187], v[52:55]
	v_mfma_f32_16x16x32_bf16 v[56:59], v[168:171], v[184:187], v[56:59]
	v_mfma_f32_16x16x32_bf16 v[56:59], v[172:175], v[188:191], v[56:59]
	v_mfma_f32_16x16x32_bf16 v[48:51], v[180:183], v[188:191], v[48:51]
	v_mfma_f32_16x16x32_bf16 v[48:51], v[176:179], v[184:187], v[48:51]
	v_mfma_f32_16x16x32_bf16 v[32:35], v[176:179], v[192:195], v[32:35]
	v_mfma_f32_16x16x32_bf16 v[32:35], v[180:183], v[196:199], v[32:35]
	v_mfma_f32_16x16x32_bf16 v[40:43], v[172:175], v[196:199], v[40:43]
	v_mfma_f32_16x16x32_bf16 v[40:43], v[168:171], v[192:195], v[40:43]
	v_mfma_f32_16x16x32_bf16 v[36:39], v[160:163], v[192:195], v[36:39]
	v_mfma_f32_16x16x32_bf16 v[36:39], v[164:167], v[196:199], v[36:39]
	v_mfma_f32_16x16x32_bf16 v[44:47], v[156:159], v[196:199], v[44:47]
	v_mfma_f32_16x16x32_bf16 v[44:47], v[152:155], v[192:195], v[44:47]
	s_setprio 0
	s_setprio 1
	v_mfma_f32_16x16x32_bf16 v[28:31], v[152:155], v[200:203], v[28:31]
	v_mfma_f32_16x16x32_bf16 v[28:31], v[156:159], v[208:211], v[28:31]
	v_mfma_f32_16x16x32_bf16 v[20:23], v[164:167], v[208:211], v[20:23]
	v_mfma_f32_16x16x32_bf16 v[20:23], v[160:163], v[200:203], v[20:23]
	v_mfma_f32_16x16x32_bf16 v[24:27], v[168:171], v[200:203], v[24:27]
	v_mfma_f32_16x16x32_bf16 v[24:27], v[172:175], v[208:211], v[24:27]
	v_mfma_f32_16x16x32_bf16 v[16:19], v[180:183], v[208:211], v[16:19]
	v_mfma_f32_16x16x32_bf16 v[16:19], v[176:179], v[200:203], v[16:19]
	v_mfma_f32_16x16x32_bf16 v[0:3], v[176:179], v[212:215], v[0:3]
	v_mfma_f32_16x16x32_bf16 v[0:3], v[180:183], v[216:219], v[0:3]
	v_mfma_f32_16x16x32_bf16 v[8:11], v[172:175], v[216:219], v[8:11]
	v_mfma_f32_16x16x32_bf16 v[8:11], v[168:171], v[212:215], v[8:11]
	v_mfma_f32_16x16x32_bf16 v[4:7], v[160:163], v[212:215], v[4:7]
	v_mfma_f32_16x16x32_bf16 v[4:7], v[164:167], v[216:219], v[4:7]
	v_mfma_f32_16x16x32_bf16 v[12:15], v[156:159], v[216:219], v[12:15]
	v_mfma_f32_16x16x32_bf16 v[12:15], v[152:155], v[212:215], v[12:15]
	s_setprio 0
	s_barrier
	s_add_i32 s65, 0, 0x18000
	v_add_u32_e32 v151, s65, v146
	s_add_i32 s66, 0, 0x1c000
	ds_read_b128 v[152:155], v151
	ds_read_b128 v[156:159], v151 offset:1024
	ds_read_b128 v[160:163], v151 offset:2048
	ds_read_b128 v[164:167], v151 offset:3072
	v_add_u32_e32 v151, s66, v146
	ds_read_b128 v[168:171], v151
	ds_read_b128 v[172:175], v151 offset:1024
	ds_read_b128 v[176:179], v151 offset:2048
	ds_read_b128 v[180:183], v151 offset:3072
	s_add_u32 s30, s30, 0x80000
	s_addc_u32 s31, s31, 0
	s_mov_b32 m0, s46
	v_lshl_add_u64 v[230:231], s[30:31], 0, v[134:135]
	ds_read_b128 v[184:187], v150 offset:32768
	ds_read_b128 v[188:191], v150 offset:33792
	ds_read_b128 v[192:195], v150 offset:34816
	ds_read_b128 v[196:199], v150 offset:35840
	ds_read_b128 v[200:203], v150 offset:36864
	ds_read_b128 v[208:211], v150 offset:37888
	ds_read_b128 v[212:215], v150 offset:38912
	ds_read_b128 v[216:219], v150 offset:39936
	global_load_lds_dwordx4 v[230:231], off
	v_lshl_add_u64 v[230:231], s[30:31], 0, v[130:131]
	s_mov_b32 m0, s47
	s_nop 0
	global_load_lds_dwordx4 v[230:231], off
	s_waitcnt vmcnt(8)
	s_waitcnt lgkmcnt(0)
	s_barrier
	s_setprio 1
	s_waitcnt lgkmcnt(0)
	v_mfma_f32_16x16x32_bf16 v[120:123], v[152:155], v[184:187], v[120:123]
	v_mfma_f32_16x16x32_bf16 v[120:123], v[156:159], v[188:191], v[120:123]
	v_mfma_f32_16x16x32_bf16 v[116:119], v[164:167], v[188:191], v[116:119]
	v_mfma_f32_16x16x32_bf16 v[116:119], v[160:163], v[184:187], v[116:119]
	v_mfma_f32_16x16x32_bf16 v[124:127], v[168:171], v[184:187], v[124:127]
	v_mfma_f32_16x16x32_bf16 v[124:127], v[172:175], v[188:191], v[124:127]
	v_mfma_f32_16x16x32_bf16 v[112:115], v[180:183], v[188:191], v[112:115]
	v_mfma_f32_16x16x32_bf16 v[112:115], v[176:179], v[184:187], v[112:115]
	v_mfma_f32_16x16x32_bf16 v[96:99], v[176:179], v[192:195], v[96:99]
	v_mfma_f32_16x16x32_bf16 v[96:99], v[180:183], v[196:199], v[96:99]
	v_mfma_f32_16x16x32_bf16 v[104:107], v[172:175], v[196:199], v[104:107]
	v_mfma_f32_16x16x32_bf16 v[104:107], v[168:171], v[192:195], v[104:107]
	v_mfma_f32_16x16x32_bf16 v[100:103], v[160:163], v[192:195], v[100:103]
	v_mfma_f32_16x16x32_bf16 v[100:103], v[164:167], v[196:199], v[100:103]
	v_mfma_f32_16x16x32_bf16 v[108:111], v[156:159], v[196:199], v[108:111]
	v_mfma_f32_16x16x32_bf16 v[108:111], v[152:155], v[192:195], v[108:111]
	s_setprio 0
	s_setprio 1
	v_mfma_f32_16x16x32_bf16 v[92:95], v[152:155], v[200:203], v[92:95]
	v_mfma_f32_16x16x32_bf16 v[92:95], v[156:159], v[208:211], v[92:95]
	v_mfma_f32_16x16x32_bf16 v[84:87], v[164:167], v[208:211], v[84:87]
	v_mfma_f32_16x16x32_bf16 v[84:87], v[160:163], v[200:203], v[84:87]
	v_mfma_f32_16x16x32_bf16 v[88:91], v[168:171], v[200:203], v[88:91]
	v_mfma_f32_16x16x32_bf16 v[88:91], v[172:175], v[208:211], v[88:91]
	v_mfma_f32_16x16x32_bf16 v[80:83], v[180:183], v[208:211], v[80:83]
	v_mfma_f32_16x16x32_bf16 v[80:83], v[176:179], v[200:203], v[80:83]
	v_mfma_f32_16x16x32_bf16 v[64:67], v[176:179], v[212:215], v[64:67]
	v_mfma_f32_16x16x32_bf16 v[64:67], v[180:183], v[216:219], v[64:67]
	v_mfma_f32_16x16x32_bf16 v[72:75], v[172:175], v[216:219], v[72:75]
	v_mfma_f32_16x16x32_bf16 v[72:75], v[168:171], v[212:215], v[72:75]
	v_mfma_f32_16x16x32_bf16 v[68:71], v[160:163], v[212:215], v[68:71]
	v_mfma_f32_16x16x32_bf16 v[68:71], v[164:167], v[216:219], v[68:71]
	v_mfma_f32_16x16x32_bf16 v[76:79], v[156:159], v[216:219], v[76:79]
	v_mfma_f32_16x16x32_bf16 v[76:79], v[152:155], v[212:215], v[76:79]
	s_setprio 0
	s_barrier
; #define PG8_STAGE(bufoff, gbase, voff) do { _Pragma("unroll") for (int _i = 0; _i < 2; ++_i) \
;         __builtin_amdgcn_global_load_lds((const unsigned*)((const char*)(gbase) + (voff)[_i]), (LAS unsigned*)(lds + (bufoff) + ldsw + _i * 8192), 16, 0, 0); } while (0)
; #define PG8_LDA(dst, b, h) do { _Pragma("unroll") for (int m = 0; m < 4; ++m) _Pragma("unroll") for (int k = 0; k < 2; ++k) dst[m][k] = *(const LAS bf16x8*)(lds + PG8_SA(b, h) + aoff + m * 2048 + k * 1024); } while (0)
; #define PG8_MMA(ai, bj, At, Bt) do { __builtin_amdgcn_s_setprio(1); _Pragma("unroll") for (int m = 0; m < 4; ++m) _Pragma("unroll") for (int n = 0; n < 2; ++n) _Pragma("unroll") for (int k = 0; k < 2; ++k) \
;         acc[ai][bj][m][n] = __builtin_amdgcn_mfma_f32_16x16x32_bf16(Bt[n][k], At[m][k], acc[ai][bj][m][n], 0, 0, 0); __builtin_amdgcn_s_setprio(0); } while (0)
; #define PG8_WAIT_V(n) asm volatile("s_waitcnt vmcnt(" #n ")" ::: "memory")
; #define PG8_WAIT_L(n) asm volatile("s_waitcnt lgkmcnt(" #n ")" ::: "memory")
; #define PG8_BAR __builtin_amdgcn_s_barrier()
; #define PG8_SCHED __builtin_amdgcn_sched_barrier(0)
; template <class Epi>
; __device__ __forceinline__ void gemm_phase(LAS unsigned char* lds, const Gemm g, const StaticOrder& S, const Epi& E) {
;     ...
;             PG8_LDA(At, 1, 1); PG8_STAGE(PG8_SB(1, 0), b3, voffB); PG8_STAGE(PG8_SB(1, 1), b3 + hstepB, voffB); PG8_STAGE(PG8_SA(1, 0), a3, voffA);
;             PG8_WAIT_V(8); PG8_WAIT_L(0); PG8_BAR; PG8_MMA(1, 0, At, B0); PG8_MMA(1, 1, At, B1); PG8_BAR; PG8_SCHED;
;         }
	s_add_i32 s30, s65, s33
	v_lshl_add_u64 v[220:221], v[220:221], 0, s[8:9]
	s_mov_b32 m0, s30
	ds_read_b128 v[184:187], v150 offset:49152
	ds_read_b128 v[188:191], v150 offset:50176
	ds_read_b128 v[192:195], v150 offset:51200
	ds_read_b128 v[196:199], v150 offset:52224
	ds_read_b128 v[200:203], v150 offset:53248
	ds_read_b128 v[208:211], v150 offset:54272
	ds_read_b128 v[212:215], v150 offset:55296
	ds_read_b128 v[216:219], v150 offset:56320
	global_load_lds_dwordx4 v[220:221], off
	s_add_i32 m0, s30, 0x2000
	s_add_u32 s26, s26, 0x80080
	v_lshl_add_u64 v[220:221], v[222:223], 0, s[8:9]
	s_addc_u32 s27, s27, 0
	s_add_i32 s30, s66, s33
	global_load_lds_dwordx4 v[220:221], off
	v_lshl_add_u64 v[220:221], s[26:27], 0, v[132:133]
	s_mov_b32 m0, s30
	s_nop 0
	global_load_lds_dwordx4 v[220:221], off
	v_lshl_add_u64 v[220:221], s[26:27], 0, v[128:129]
	s_add_i32 m0, s30, 0x2000
	s_nop 0
	global_load_lds_dwordx4 v[220:221], off
	v_lshl_add_u64 v[220:221], v[224:225], 0, s[8:9]
	s_mov_b32 m0, s52
	s_nop 0
	global_load_lds_dwordx4 v[220:221], off
	v_lshl_add_u64 v[220:221], v[226:227], 0, s[8:9]
	s_mov_b32 m0, s53
	s_nop 0
	global_load_lds_dwordx4 v[220:221], off
	s_waitcnt vmcnt(8)
	s_waitcnt lgkmcnt(0)
	s_barrier
	s_setprio 1
	s_waitcnt lgkmcnt(0)
	v_mfma_f32_16x16x32_bf16 v[60:63], v[152:155], v[184:187], v[60:63]
	v_mfma_f32_16x16x32_bf16 v[60:63], v[156:159], v[188:191], v[60:63]
	v_mfma_f32_16x16x32_bf16 v[52:55], v[164:167], v[188:191], v[52:55]
	v_mfma_f32_16x16x32_bf16 v[52:55], v[160:163], v[184:187], v[52:55]
	v_mfma_f32_16x16x32_bf16 v[56:59], v[168:171], v[184:187], v[56:59]
	v_mfma_f32_16x16x32_bf16 v[56:59], v[172:175], v[188:191], v[56:59]
	v_mfma_f32_16x16x32_bf16 v[48:51], v[180:183], v[188:191], v[48:51]
	v_mfma_f32_16x16x32_bf16 v[48:51], v[176:179], v[184:187], v[48:51]
	v_mfma_f32_16x16x32_bf16 v[32:35], v[176:179], v[192:195], v[32:35]
	v_mfma_f32_16x16x32_bf16 v[32:35], v[180:183], v[196:199], v[32:35]
	v_mfma_f32_16x16x32_bf16 v[40:43], v[172:175], v[196:199], v[40:43]
	v_mfma_f32_16x16x32_bf16 v[40:43], v[168:171], v[192:195], v[40:43]
	v_mfma_f32_16x16x32_bf16 v[36:39], v[160:163], v[192:195], v[36:39]
	v_mfma_f32_16x16x32_bf16 v[36:39], v[164:167], v[196:199], v[36:39]
	v_mfma_f32_16x16x32_bf16 v[44:47], v[156:159], v[196:199], v[44:47]
	v_mfma_f32_16x16x32_bf16 v[44:47], v[152:155], v[192:195], v[44:47]
	s_setprio 0
	s_setprio 1
	v_mfma_f32_16x16x32_bf16 v[28:31], v[152:155], v[200:203], v[28:31]
	v_mfma_f32_16x16x32_bf16 v[28:31], v[156:159], v[208:211], v[28:31]
	v_mfma_f32_16x16x32_bf16 v[20:23], v[164:167], v[208:211], v[20:23]
	v_mfma_f32_16x16x32_bf16 v[20:23], v[160:163], v[200:203], v[20:23]
	v_mfma_f32_16x16x32_bf16 v[24:27], v[168:171], v[200:203], v[24:27]
	v_mfma_f32_16x16x32_bf16 v[24:27], v[172:175], v[208:211], v[24:27]
	v_mfma_f32_16x16x32_bf16 v[16:19], v[180:183], v[208:211], v[16:19]
	v_mfma_f32_16x16x32_bf16 v[16:19], v[176:179], v[200:203], v[16:19]
	v_mfma_f32_16x16x32_bf16 v[0:3], v[176:179], v[212:215], v[0:3]
	v_mfma_f32_16x16x32_bf16 v[0:3], v[180:183], v[216:219], v[0:3]
	v_mfma_f32_16x16x32_bf16 v[8:11], v[172:175], v[216:219], v[8:11]
	v_mfma_f32_16x16x32_bf16 v[8:11], v[168:171], v[212:215], v[8:11]
	v_mfma_f32_16x16x32_bf16 v[4:7], v[160:163], v[212:215], v[4:7]
	v_mfma_f32_16x16x32_bf16 v[4:7], v[164:167], v[216:219], v[4:7]
	v_mfma_f32_16x16x32_bf16 v[12:15], v[156:159], v[216:219], v[12:15]
	v_mfma_f32_16x16x32_bf16 v[12:15], v[152:155], v[212:215], v[12:15]
	s_add_u32 s24, s24, 0x100
	s_addc_u32 s25, s25, 0
	s_add_u32 s62, s62, 0x100
	s_addc_u32 s63, s63, 0
	s_cmp_ge_i32 s64, s49
	s_mov_b32 s26, s64
	s_setprio 0
	s_barrier
	s_cbranch_scc0 .LBB0_245

; #define PG8_STAGE(bufoff, gbase, voff) do { _Pragma("unroll") for (int _i = 0; _i < 2; ++_i) \
;         __builtin_amdgcn_global_load_lds((const unsigned*)((const char*)(gbase) + (voff)[_i]), (LAS unsigned*)(lds + (bufoff) + ldsw + _i * 8192), 16, 0, 0); } while (0)
; #define PG8_LDA(dst, b, h) do { _Pragma("unroll") for (int m = 0; m < 4; ++m) _Pragma("unroll") for (int k = 0; k < 2; ++k) dst[m][k] = *(const LAS bf16x8*)(lds + PG8_SA(b, h) + aoff + m * 2048 + k * 1024); } while (0)
; #define PG8_LDB(dst, b, h) do { _Pragma("unroll") for (int n = 0; n < 2; ++n) _Pragma("unroll") for (int k = 0; k < 2; ++k) dst[n][k] = *(const LAS bf16x8*)(lds + PG8_SB(b, h) + boff + n * 2048 + k * 1024); } while (0)
; #define PG8_MMA(ai, bj, At, Bt) do { __builtin_amdgcn_s_setprio(1); _Pragma("unroll") for (int m = 0; m < 4; ++m) _Pragma("unroll") for (int n = 0; n < 2; ++n) _Pragma("unroll") for (int k = 0; k < 2; ++k) \
;         acc[ai][bj][m][n] = __builtin_amdgcn_mfma_f32_16x16x32_bf16(Bt[n][k], At[m][k], acc[ai][bj][m][n], 0, 0, 0); __builtin_amdgcn_s_setprio(0); } while (0)
; #define PG8_WAIT_V(n) asm volatile("s_waitcnt vmcnt(" #n ")" ::: "memory")
; #define PG8_WAIT_L(n) asm volatile("s_waitcnt lgkmcnt(" #n ")" ::: "memory")
; #define PG8_BAR __builtin_amdgcn_s_barrier()
; #define PG8_SCHED __builtin_amdgcn_sched_barrier(0)
; template <class Epi>
; __device__ __forceinline__ void gemm_phase(LAS unsigned char* lds, const Gemm g, const StaticOrder& S, const Epi& E) {
;     ...
;         for (int t = 0; t < nt; t += 2) {
;             const bool last = (t == nt - 2);
;             const char* a1 = cA + (size_t)(t + 1) * kstep;
;             const char* a2 = last ? nA : cA + (size_t)(t + 2) * kstep; const char* b2 = last ? nB : cB + (size_t)(t + 2) * kstep;
;             const char* a3 = a2 + kstep; const char* b3 = b2 + kstep;
;             PG8_LDB(B0, 0, 0); PG8_LDB(B1, 0, 1); PG8_SCHED; PG8_LDA(At, 0, 0); PG8_STAGE(PG8_SA(1, 1), a1 + hstepA, voffA);
;             PG8_WAIT_V(8); PG8_WAIT_L(0); PG8_BAR; PG8_MMA(0, 0, At, B0); PG8_MMA(0, 1, At, B1); PG8_BAR; PG8_SCHED;
;             PG8_LDA(At, 0, 1); PG8_STAGE(PG8_SB(0, 0), b2, voffB); PG8_STAGE(PG8_SB(0, 1), b2 + hstepB, voffB); PG8_STAGE(PG8_SA(0, 0), a2, voffA);
.LBB0_541:
	ds_read_b128 v[148:151], v155
	ds_read_b128 v[160:163], v155 offset:1024
	ds_read_b128 v[164:167], v155 offset:2048
	ds_read_b128 v[168:171], v155 offset:3072
	ds_read_b128 v[172:175], v156
	ds_read_b128 v[176:179], v156 offset:1024
	ds_read_b128 v[180:183], v156 offset:2048
	ds_read_b128 v[184:187], v156 offset:3072
	s_add_i32 s35, s26, 2
	s_add_u32 s27, s8, 0xfff80080
	s_addc_u32 s30, s9, -1
	s_cmp_eq_u32 s49, s26
	s_cselect_b32 s26, s21, s33
	s_cselect_b32 s31, s1, s30
	s_cselect_b32 s30, s5, s27
	s_cselect_b32 s27, s19, s34
	v_lshl_add_u64 v[224:225], s[8:9], 0, v[140:141]
	s_add_i32 m0, s39, 0xc000
	ds_read_b128 v[188:191], v157
	ds_read_b128 v[192:195], v157 offset:1024
	ds_read_b128 v[196:199], v157 offset:2048
	ds_read_b128 v[200:203], v157 offset:3072
	ds_read_b128 v[208:211], v157 offset:4096
	ds_read_b128 v[212:215], v157 offset:5120
	ds_read_b128 v[216:219], v157 offset:6144
	ds_read_b128 v[220:223], v157 offset:7168
	global_load_lds_dwordx4 v[224:225], off
	v_lshl_add_u64 v[224:225], s[8:9], 0, v[142:143]
	s_add_i32 m0, s39, 0xe000
	s_nop 0
	global_load_lds_dwordx4 v[224:225], off
	s_waitcnt vmcnt(8)
	s_waitcnt lgkmcnt(0)
	s_barrier
	s_setprio 1
	s_waitcnt lgkmcnt(0)
	v_mfma_f32_16x16x32_bf16 v[120:123], v[148:151], v[188:191], v[120:123]
	v_mfma_f32_16x16x32_bf16 v[120:123], v[160:163], v[192:195], v[120:123]
	v_mfma_f32_16x16x32_bf16 v[124:127], v[168:171], v[192:195], v[124:127]
	v_mfma_f32_16x16x32_bf16 v[124:127], v[164:167], v[188:191], v[124:127]
	v_mfma_f32_16x16x32_bf16 v[116:119], v[172:175], v[188:191], v[116:119]
	v_mfma_f32_16x16x32_bf16 v[116:119], v[176:179], v[192:195], v[116:119]
	v_mfma_f32_16x16x32_bf16 v[112:115], v[184:187], v[192:195], v[112:115]
	v_mfma_f32_16x16x32_bf16 v[112:115], v[180:183], v[188:191], v[112:115]
	v_mfma_f32_16x16x32_bf16 v[96:99], v[180:183], v[196:199], v[96:99]
	v_mfma_f32_16x16x32_bf16 v[96:99], v[184:187], v[200:203], v[96:99]
	v_mfma_f32_16x16x32_bf16 v[100:103], v[176:179], v[200:203], v[100:103]
	v_mfma_f32_16x16x32_bf16 v[100:103], v[172:175], v[196:199], v[100:103]
	v_mfma_f32_16x16x32_bf16 v[104:107], v[164:167], v[196:199], v[104:107]
	v_mfma_f32_16x16x32_bf16 v[104:107], v[168:171], v[200:203], v[104:107]
	v_mfma_f32_16x16x32_bf16 v[108:111], v[160:163], v[200:203], v[108:111]
	v_mfma_f32_16x16x32_bf16 v[108:111], v[148:151], v[196:199], v[108:111]
	s_setprio 0
	s_setprio 1
	v_mfma_f32_16x16x32_bf16 v[92:95], v[148:151], v[208:211], v[92:95]
	v_mfma_f32_16x16x32_bf16 v[92:95], v[160:163], v[212:215], v[92:95]
	v_mfma_f32_16x16x32_bf16 v[88:91], v[168:171], v[212:215], v[88:91]
	v_mfma_f32_16x16x32_bf16 v[88:91], v[164:167], v[208:211], v[88:91]
	v_mfma_f32_16x16x32_bf16 v[84:87], v[172:175], v[208:211], v[84:87]
	v_mfma_f32_16x16x32_bf16 v[84:87], v[176:179], v[212:215], v[84:87]
	v_mfma_f32_16x16x32_bf16 v[80:83], v[184:187], v[212:215], v[80:83]
	v_mfma_f32_16x16x32_bf16 v[80:83], v[180:183], v[208:211], v[80:83]
	v_mfma_f32_16x16x32_bf16 v[64:67], v[180:183], v[216:219], v[64:67]
	v_mfma_f32_16x16x32_bf16 v[64:67], v[184:187], v[220:223], v[64:67]
	v_mfma_f32_16x16x32_bf16 v[68:71], v[176:179], v[220:223], v[68:71]
	v_mfma_f32_16x16x32_bf16 v[68:71], v[172:175], v[216:219], v[68:71]
	v_mfma_f32_16x16x32_bf16 v[72:75], v[164:167], v[216:219], v[72:75]
	v_mfma_f32_16x16x32_bf16 v[72:75], v[168:171], v[220:223], v[72:75]
	v_mfma_f32_16x16x32_bf16 v[76:79], v[160:163], v[220:223], v[76:79]
	v_mfma_f32_16x16x32_bf16 v[76:79], v[148:151], v[216:219], v[76:79]
	s_setprio 0
	s_barrier
	s_add_i32 s58, s54, s38
	v_lshl_add_u64 v[224:225], s[26:27], 0, v[130:131]
	s_mov_b32 m0, s58
	ds_read_b128 v[188:191], v157 offset:16384
	ds_read_b128 v[192:195], v157 offset:17408
	ds_read_b128 v[196:199], v157 offset:18432
	ds_read_b128 v[200:203], v157 offset:19456
	ds_read_b128 v[208:211], v157 offset:20480
	ds_read_b128 v[212:215], v157 offset:21504
	ds_read_b128 v[216:219], v157 offset:22528
	ds_read_b128 v[220:223], v157 offset:23552
	global_load_lds_dwordx4 v[224:225], off
	s_add_i32 m0, s58, 0x2000
	s_add_u32 s58, s26, 0x80000
	v_lshl_add_u64 v[226:227], s[26:27], 0, v[134:135]
	s_addc_u32 s59, s27, 0
	s_add_i32 s60, s55, s38
	global_load_lds_dwordx4 v[226:227], off
	v_lshl_add_u64 v[230:231], s[58:59], 0, v[130:131]
	s_mov_b32 m0, s60
	v_lshl_add_u64 v[232:233], s[30:31], 0, v[132:133]
	global_load_lds_dwordx4 v[230:231], off
	v_lshl_add_u64 v[230:231], s[58:59], 0, v[134:135]
	s_add_i32 m0, s60, 0x2000
	s_nop 0
	global_load_lds_dwordx4 v[230:231], off
	v_lshl_add_u64 v[230:231], s[30:31], 0, v[128:129]
	s_mov_b32 m0, s39
	s_nop 0
	global_load_lds_dwordx4 v[230:231], off
	s_mov_b32 m0, s40
	s_nop 0
	global_load_lds_dwordx4 v[232:233], off
	s_waitcnt vmcnt(8)
	s_waitcnt lgkmcnt(0)
	s_barrier
; #define PG8_STAGE(bufoff, gbase, voff) do { _Pragma("unroll") for (int _i = 0; _i < 2; ++_i) \
;         __builtin_amdgcn_global_load_lds((const unsigned*)((const char*)(gbase) + (voff)[_i]), (LAS unsigned*)(lds + (bufoff) + ldsw + _i * 8192), 16, 0, 0); } while (0)
; #define PG8_LDA(dst, b, h) do { _Pragma("unroll") for (int m = 0; m < 4; ++m) _Pragma("unroll") for (int k = 0; k < 2; ++k) dst[m][k] = *(const LAS bf16x8*)(lds + PG8_SA(b, h) + aoff + m * 2048 + k * 1024); } while (0)
; #define PG8_LDB(dst, b, h) do { _Pragma("unroll") for (int n = 0; n < 2; ++n) _Pragma("unroll") for (int k = 0; k < 2; ++k) dst[n][k] = *(const LAS bf16x8*)(lds + PG8_SB(b, h) + boff + n * 2048 + k * 1024); } while (0)
; #define PG8_MMA(ai, bj, At, Bt) do { __builtin_amdgcn_s_setprio(1); _Pragma("unroll") for (int m = 0; m < 4; ++m) _Pragma("unroll") for (int n = 0; n < 2; ++n) _Pragma("unroll") for (int k = 0; k < 2; ++k) \
;         acc[ai][bj][m][n] = __builtin_amdgcn_mfma_f32_16x16x32_bf16(Bt[n][k], At[m][k], acc[ai][bj][m][n], 0, 0, 0); __builtin_amdgcn_s_setprio(0); } while (0)
; #define PG8_WAIT_V(n) asm volatile("s_waitcnt vmcnt(" #n ")" ::: "memory")
; #define PG8_WAIT_L(n) asm volatile("s_waitcnt lgkmcnt(" #n ")" ::: "memory")
; #define PG8_BAR __builtin_amdgcn_s_barrier()
; #define PG8_SCHED __builtin_amdgcn_sched_barrier(0)
; template <class Epi>
; __device__ __forceinline__ void gemm_phase(LAS unsigned char* lds, const Gemm g, const StaticOrder& S, const Epi& E) {
;     ...
;             PG8_WAIT_V(8); PG8_WAIT_L(0); PG8_BAR; PG8_MMA(1, 0, At, B0); PG8_MMA(1, 1, At, B1); PG8_BAR; PG8_SCHED;
;             PG8_LDB(B0, 1, 0); PG8_LDB(B1, 1, 1); PG8_SCHED; PG8_LDA(At, 1, 0); PG8_STAGE(PG8_SA(0, 1), a2 + hstepA, voffA);
;             PG8_WAIT_V(8); PG8_WAIT_L(0); PG8_BAR; PG8_MMA(0, 0, At, B0); PG8_MMA(0, 1, At, B1); PG8_BAR; PG8_SCHED;
	s_setprio 1
	s_waitcnt lgkmcnt(0)
	v_mfma_f32_16x16x32_bf16 v[60:63], v[148:151], v[188:191], v[60:63]
	v_mfma_f32_16x16x32_bf16 v[60:63], v[160:163], v[192:195], v[60:63]
	v_mfma_f32_16x16x32_bf16 v[56:59], v[168:171], v[192:195], v[56:59]
	v_mfma_f32_16x16x32_bf16 v[56:59], v[164:167], v[188:191], v[56:59]
	v_mfma_f32_16x16x32_bf16 v[52:55], v[172:175], v[188:191], v[52:55]
	v_mfma_f32_16x16x32_bf16 v[52:55], v[176:179], v[192:195], v[52:55]
	v_mfma_f32_16x16x32_bf16 v[48:51], v[184:187], v[192:195], v[48:51]
	v_mfma_f32_16x16x32_bf16 v[48:51], v[180:183], v[188:191], v[48:51]
	v_mfma_f32_16x16x32_bf16 v[32:35], v[180:183], v[196:199], v[32:35]
	v_mfma_f32_16x16x32_bf16 v[32:35], v[184:187], v[200:203], v[32:35]
	v_mfma_f32_16x16x32_bf16 v[36:39], v[176:179], v[200:203], v[36:39]
	v_mfma_f32_16x16x32_bf16 v[36:39], v[172:175], v[196:199], v[36:39]
	v_mfma_f32_16x16x32_bf16 v[40:43], v[164:167], v[196:199], v[40:43]
	v_mfma_f32_16x16x32_bf16 v[40:43], v[168:171], v[200:203], v[40:43]
	v_mfma_f32_16x16x32_bf16 v[44:47], v[160:163], v[200:203], v[44:47]
	v_mfma_f32_16x16x32_bf16 v[44:47], v[148:151], v[196:199], v[44:47]
	s_setprio 0
	s_setprio 1
	v_mfma_f32_16x16x32_bf16 v[28:31], v[148:151], v[208:211], v[28:31]
	v_mfma_f32_16x16x32_bf16 v[28:31], v[160:163], v[212:215], v[28:31]
	v_mfma_f32_16x16x32_bf16 v[24:27], v[168:171], v[212:215], v[24:27]
	v_mfma_f32_16x16x32_bf16 v[24:27], v[164:167], v[208:211], v[24:27]
	v_mfma_f32_16x16x32_bf16 v[20:23], v[172:175], v[208:211], v[20:23]
	v_mfma_f32_16x16x32_bf16 v[20:23], v[176:179], v[212:215], v[20:23]
	v_mfma_f32_16x16x32_bf16 v[16:19], v[184:187], v[212:215], v[16:19]
	v_mfma_f32_16x16x32_bf16 v[16:19], v[180:183], v[208:211], v[16:19]
	v_mfma_f32_16x16x32_bf16 v[0:3], v[180:183], v[216:219], v[0:3]
	v_mfma_f32_16x16x32_bf16 v[0:3], v[184:187], v[220:223], v[0:3]
	v_mfma_f32_16x16x32_bf16 v[4:7], v[176:179], v[220:223], v[4:7]
	v_mfma_f32_16x16x32_bf16 v[4:7], v[172:175], v[216:219], v[4:7]
	v_mfma_f32_16x16x32_bf16 v[8:11], v[164:167], v[216:219], v[8:11]
	v_mfma_f32_16x16x32_bf16 v[8:11], v[168:171], v[220:223], v[8:11]
	v_mfma_f32_16x16x32_bf16 v[12:15], v[160:163], v[220:223], v[12:15]
	v_mfma_f32_16x16x32_bf16 v[12:15], v[148:151], v[216:219], v[12:15]
	s_setprio 0
	s_barrier
	s_add_i32 s58, 0, 0x18000
	v_add_u32_e32 v136, s58, v154
	s_add_i32 s59, 0, 0x1c000
	ds_read_b128 v[148:151], v136
	ds_read_b128 v[160:163], v136 offset:1024
	ds_read_b128 v[164:167], v136 offset:2048
	ds_read_b128 v[168:171], v136 offset:3072
	v_add_u32_e32 v136, s59, v154
	ds_read_b128 v[172:175], v136
	ds_read_b128 v[176:179], v136 offset:1024
	ds_read_b128 v[180:183], v136 offset:2048
	ds_read_b128 v[184:187], v136 offset:3072
	s_add_u32 s30, s30, 0x80000
	s_addc_u32 s31, s31, 0
	s_mov_b32 m0, s41
	v_lshl_add_u64 v[234:235], s[30:31], 0, v[128:129]
	ds_read_b128 v[188:191], v157 offset:32768
	ds_read_b128 v[192:195], v157 offset:33792
	ds_read_b128 v[196:199], v157 offset:34816
	ds_read_b128 v[200:203], v157 offset:35840
	ds_read_b128 v[208:211], v157 offset:36864
	ds_read_b128 v[212:215], v157 offset:37888
	ds_read_b128 v[216:219], v157 offset:38912
	ds_read_b128 v[220:223], v157 offset:39936
	global_load_lds_dwordx4 v[234:235], off
	v_lshl_add_u64 v[234:235], s[30:31], 0, v[132:133]
	s_mov_b32 m0, s42
	s_nop 0
	global_load_lds_dwordx4 v[234:235], off
	s_waitcnt vmcnt(8)
	s_waitcnt lgkmcnt(0)
	s_barrier
	s_setprio 1
	s_waitcnt lgkmcnt(0)
	v_mfma_f32_16x16x32_bf16 v[120:123], v[148:151], v[188:191], v[120:123]
	v_mfma_f32_16x16x32_bf16 v[120:123], v[160:163], v[192:195], v[120:123]
	v_mfma_f32_16x16x32_bf16 v[124:127], v[168:171], v[192:195], v[124:127]
	v_mfma_f32_16x16x32_bf16 v[124:127], v[164:167], v[188:191], v[124:127]
	v_mfma_f32_16x16x32_bf16 v[116:119], v[172:175], v[188:191], v[116:119]
	v_mfma_f32_16x16x32_bf16 v[116:119], v[176:179], v[192:195], v[116:119]
	v_mfma_f32_16x16x32_bf16 v[112:115], v[184:187], v[192:195], v[112:115]
	v_mfma_f32_16x16x32_bf16 v[112:115], v[180:183], v[188:191], v[112:115]
	v_mfma_f32_16x16x32_bf16 v[96:99], v[180:183], v[196:199], v[96:99]
	v_mfma_f32_16x16x32_bf16 v[96:99], v[184:187], v[200:203], v[96:99]
	v_mfma_f32_16x16x32_bf16 v[100:103], v[176:179], v[200:203], v[100:103]
	v_mfma_f32_16x16x32_bf16 v[100:103], v[172:175], v[196:199], v[100:103]
	v_mfma_f32_16x16x32_bf16 v[104:107], v[164:167], v[196:199], v[104:107]
	v_mfma_f32_16x16x32_bf16 v[104:107], v[168:171], v[200:203], v[104:107]
	v_mfma_f32_16x16x32_bf16 v[108:111], v[160:163], v[200:203], v[108:111]
	v_mfma_f32_16x16x32_bf16 v[108:111], v[148:151], v[196:199], v[108:111]
	s_setprio 0
	s_setprio 1
	v_mfma_f32_16x16x32_bf16 v[92:95], v[148:151], v[208:211], v[92:95]
	v_mfma_f32_16x16x32_bf16 v[92:95], v[160:163], v[212:215], v[92:95]
	v_mfma_f32_16x16x32_bf16 v[88:91], v[168:171], v[212:215], v[88:91]
	v_mfma_f32_16x16x32_bf16 v[88:91], v[164:167], v[208:211], v[88:91]
	v_mfma_f32_16x16x32_bf16 v[84:87], v[172:175], v[208:211], v[84:87]
	v_mfma_f32_16x16x32_bf16 v[84:87], v[176:179], v[212:215], v[84:87]
	v_mfma_f32_16x16x32_bf16 v[80:83], v[184:187], v[212:215], v[80:83]
	v_mfma_f32_16x16x32_bf16 v[80:83], v[180:183], v[208:211], v[80:83]
	v_mfma_f32_16x16x32_bf16 v[64:67], v[180:183], v[216:219], v[64:67]
	v_mfma_f32_16x16x32_bf16 v[64:67], v[184:187], v[220:223], v[64:67]
	v_mfma_f32_16x16x32_bf16 v[68:71], v[176:179], v[220:223], v[68:71]
	v_mfma_f32_16x16x32_bf16 v[68:71], v[172:175], v[216:219], v[68:71]
	v_mfma_f32_16x16x32_bf16 v[72:75], v[164:167], v[216:219], v[72:75]
	v_mfma_f32_16x16x32_bf16 v[72:75], v[168:171], v[220:223], v[72:75]
	v_mfma_f32_16x16x32_bf16 v[76:79], v[160:163], v[220:223], v[76:79]
	v_mfma_f32_16x16x32_bf16 v[76:79], v[148:151], v[216:219], v[76:79]
	s_setprio 0
	s_barrier
; #define PG8_STAGE(bufoff, gbase, voff) do { _Pragma("unroll") for (int _i = 0; _i < 2; ++_i) \
;         __builtin_amdgcn_global_load_lds((const unsigned*)((const char*)(gbase) + (voff)[_i]), (LAS unsigned*)(lds + (bufoff) + ldsw + _i * 8192), 16, 0, 0); } while (0)
; #define PG8_LDA(dst, b, h) do { _Pragma("unroll") for (int m = 0; m < 4; ++m) _Pragma("unroll") for (int k = 0; k < 2; ++k) dst[m][k] = *(const LAS bf16x8*)(lds + PG8_SA(b, h) + aoff + m * 2048 + k * 1024); } while (0)
; #define PG8_MMA(ai, bj, At, Bt) do { __builtin_amdgcn_s_setprio(1); _Pragma("unroll") for (int m = 0; m < 4; ++m) _Pragma("unroll") for (int n = 0; n < 2; ++n) _Pragma("unroll") for (int k = 0; k < 2; ++k) \
;         acc[ai][bj][m][n] = __builtin_amdgcn_mfma_f32_16x16x32_bf16(Bt[n][k], At[m][k], acc[ai][bj][m][n], 0, 0, 0); __builtin_amdgcn_s_setprio(0); } while (0)
; #define PG8_WAIT_V(n) asm volatile("s_waitcnt vmcnt(" #n ")" ::: "memory")
; #define PG8_WAIT_L(n) asm volatile("s_waitcnt lgkmcnt(" #n ")" ::: "memory")
; #define PG8_BAR __builtin_amdgcn_s_barrier()
; #define PG8_SCHED __builtin_amdgcn_sched_barrier(0)
; template <class Epi>
; __device__ __forceinline__ void gemm_phase(LAS unsigned char* lds, const Gemm g, const StaticOrder& S, const Epi& E) {
;     ...
;             PG8_LDA(At, 1, 1); PG8_STAGE(PG8_SB(1, 0), b3, voffB); PG8_STAGE(PG8_SB(1, 1), b3 + hstepB, voffB); PG8_STAGE(PG8_SA(1, 0), a3, voffA);
;             PG8_WAIT_V(8); PG8_WAIT_L(0); PG8_BAR; PG8_MMA(1, 0, At, B0); PG8_MMA(1, 1, At, B1); PG8_BAR; PG8_SCHED;
;         }
	s_add_i32 s30, s58, s38
	v_lshl_add_u64 v[224:225], v[224:225], 0, s[12:13]
	s_mov_b32 m0, s30
	ds_read_b128 v[188:191], v157 offset:49152
	ds_read_b128 v[192:195], v157 offset:50176
	ds_read_b128 v[196:199], v157 offset:51200
	ds_read_b128 v[200:203], v157 offset:52224
	ds_read_b128 v[208:211], v157 offset:53248
	ds_read_b128 v[212:215], v157 offset:54272
	ds_read_b128 v[216:219], v157 offset:55296
	ds_read_b128 v[220:223], v157 offset:56320
	global_load_lds_dwordx4 v[224:225], off
	s_add_i32 m0, s30, 0x2000
	s_add_u32 s26, s26, 0x80080
	v_lshl_add_u64 v[224:225], v[226:227], 0, s[12:13]
	s_addc_u32 s27, s27, 0
	s_add_i32 s30, s59, s38
	global_load_lds_dwordx4 v[224:225], off
	v_lshl_add_u64 v[224:225], s[26:27], 0, v[130:131]
	s_mov_b32 m0, s30
	s_nop 0
	global_load_lds_dwordx4 v[224:225], off
	v_lshl_add_u64 v[224:225], s[26:27], 0, v[134:135]
	s_add_i32 m0, s30, 0x2000
	s_nop 0
	global_load_lds_dwordx4 v[224:225], off
	v_lshl_add_u64 v[224:225], v[230:231], 0, s[12:13]
	s_mov_b32 m0, s47
	s_nop 0
	global_load_lds_dwordx4 v[224:225], off
	v_lshl_add_u64 v[224:225], v[232:233], 0, s[12:13]
	s_mov_b32 m0, s48
	s_nop 0
	global_load_lds_dwordx4 v[224:225], off
	s_waitcnt vmcnt(8)
	s_waitcnt lgkmcnt(0)
	s_barrier
	s_setprio 1
	s_waitcnt lgkmcnt(0)
	v_mfma_f32_16x16x32_bf16 v[60:63], v[148:151], v[188:191], v[60:63]
	v_mfma_f32_16x16x32_bf16 v[60:63], v[160:163], v[192:195], v[60:63]
	v_mfma_f32_16x16x32_bf16 v[56:59], v[168:171], v[192:195], v[56:59]
	v_mfma_f32_16x16x32_bf16 v[56:59], v[164:167], v[188:191], v[56:59]
	v_mfma_f32_16x16x32_bf16 v[52:55], v[172:175], v[188:191], v[52:55]
	v_mfma_f32_16x16x32_bf16 v[52:55], v[176:179], v[192:195], v[52:55]
	v_mfma_f32_16x16x32_bf16 v[48:51], v[184:187], v[192:195], v[48:51]
	v_mfma_f32_16x16x32_bf16 v[48:51], v[180:183], v[188:191], v[48:51]
	v_mfma_f32_16x16x32_bf16 v[32:35], v[180:183], v[196:199], v[32:35]
	v_mfma_f32_16x16x32_bf16 v[32:35], v[184:187], v[200:203], v[32:35]
	v_mfma_f32_16x16x32_bf16 v[36:39], v[176:179], v[200:203], v[36:39]
	v_mfma_f32_16x16x32_bf16 v[36:39], v[172:175], v[196:199], v[36:39]
	v_mfma_f32_16x16x32_bf16 v[40:43], v[164:167], v[196:199], v[40:43]
	v_mfma_f32_16x16x32_bf16 v[40:43], v[168:171], v[200:203], v[40:43]
	v_mfma_f32_16x16x32_bf16 v[44:47], v[160:163], v[200:203], v[44:47]
	v_mfma_f32_16x16x32_bf16 v[44:47], v[148:151], v[196:199], v[44:47]
	s_setprio 0
	s_setprio 1
	v_mfma_f32_16x16x32_bf16 v[28:31], v[148:151], v[208:211], v[28:31]
	v_mfma_f32_16x16x32_bf16 v[28:31], v[160:163], v[212:215], v[28:31]
	v_mfma_f32_16x16x32_bf16 v[24:27], v[168:171], v[212:215], v[24:27]
	v_mfma_f32_16x16x32_bf16 v[24:27], v[164:167], v[208:211], v[24:27]
	v_mfma_f32_16x16x32_bf16 v[20:23], v[172:175], v[208:211], v[20:23]
	v_mfma_f32_16x16x32_bf16 v[20:23], v[176:179], v[212:215], v[20:23]
	v_mfma_f32_16x16x32_bf16 v[16:19], v[184:187], v[212:215], v[16:19]
	v_mfma_f32_16x16x32_bf16 v[16:19], v[180:183], v[208:211], v[16:19]
	v_mfma_f32_16x16x32_bf16 v[0:3], v[180:183], v[216:219], v[0:3]
	v_mfma_f32_16x16x32_bf16 v[0:3], v[184:187], v[220:223], v[0:3]
	v_mfma_f32_16x16x32_bf16 v[4:7], v[176:179], v[220:223], v[4:7]
	v_mfma_f32_16x16x32_bf16 v[4:7], v[172:175], v[216:219], v[4:7]
	v_mfma_f32_16x16x32_bf16 v[8:11], v[164:167], v[216:219], v[8:11]
	v_mfma_f32_16x16x32_bf16 v[8:11], v[168:171], v[220:223], v[8:11]
	v_mfma_f32_16x16x32_bf16 v[12:15], v[160:163], v[220:223], v[12:15]
	v_mfma_f32_16x16x32_bf16 v[12:15], v[148:151], v[216:219], v[12:15]
	s_add_u32 s8, s8, 0x100
	s_addc_u32 s9, s9, 0
	s_add_u32 s33, s33, 0x100
	s_addc_u32 s34, s34, 0
	s_cmp_ge_i32 s35, s44
	s_mov_b32 s26, s35
	s_setprio 0
	s_barrier
	s_cbranch_scc0 .LBB0_541

; #define PG8_STAGE(bufoff, gbase, voff) do { _Pragma("unroll") for (int _i = 0; _i < 2; ++_i) \
;         __builtin_amdgcn_global_load_lds((const unsigned*)((const char*)(gbase) + (voff)[_i]), (LAS unsigned*)(lds + (bufoff) + ldsw + _i * 8192), 16, 0, 0); } while (0)
; #define PG8_LDA(dst, b, h) do { _Pragma("unroll") for (int m = 0; m < 4; ++m) _Pragma("unroll") for (int k = 0; k < 2; ++k) dst[m][k] = *(const LAS bf16x8*)(lds + PG8_SA(b, h) + aoff + m * 2048 + k * 1024); } while (0)
; #define PG8_LDB(dst, b, h) do { _Pragma("unroll") for (int n = 0; n < 2; ++n) _Pragma("unroll") for (int k = 0; k < 2; ++k) dst[n][k] = *(const LAS bf16x8*)(lds + PG8_SB(b, h) + boff + n * 2048 + k * 1024); } while (0)
; #define PG8_MMA(ai, bj, At, Bt) do { __builtin_amdgcn_s_setprio(1); _Pragma("unroll") for (int m = 0; m < 4; ++m) _Pragma("unroll") for (int n = 0; n < 2; ++n) _Pragma("unroll") for (int k = 0; k < 2; ++k) \
;         acc[ai][bj][m][n] = __builtin_amdgcn_mfma_f32_16x16x32_bf16(Bt[n][k], At[m][k], acc[ai][bj][m][n], 0, 0, 0); __builtin_amdgcn_s_setprio(0); } while (0)
; #define PG8_WAIT_V(n) asm volatile("s_waitcnt vmcnt(" #n ")" ::: "memory")
; #define PG8_WAIT_L(n) asm volatile("s_waitcnt lgkmcnt(" #n ")" ::: "memory")
; #define PG8_BAR __builtin_amdgcn_s_barrier()
; #define PG8_SCHED __builtin_amdgcn_sched_barrier(0)
; template <class Epi>
; __device__ __forceinline__ void gemm_phase(LAS unsigned char* lds, const Gemm g, const StaticOrder& S, const Epi& E) {
;     ...
;         for (int t = 0; t < nt; t += 2) {
;             const bool last = (t == nt - 2);
;             const char* a1 = cA + (size_t)(t + 1) * kstep;
;             const char* a2 = last ? nA : cA + (size_t)(t + 2) * kstep; const char* b2 = last ? nB : cB + (size_t)(t + 2) * kstep;
;             const char* a3 = a2 + kstep; const char* b3 = b2 + kstep;
;             PG8_LDB(B0, 0, 0); PG8_LDB(B1, 0, 1); PG8_SCHED; PG8_LDA(At, 0, 0); PG8_STAGE(PG8_SA(1, 1), a1 + hstepA, voffA);
;             PG8_WAIT_V(8); PG8_WAIT_L(0); PG8_BAR; PG8_MMA(0, 0, At, B0); PG8_MMA(0, 1, At, B1); PG8_BAR; PG8_SCHED;
;             PG8_LDA(At, 0, 1); PG8_STAGE(PG8_SB(0, 0), b2, voffB); PG8_STAGE(PG8_SB(0, 1), b2 + hstepB, voffB); PG8_STAGE(PG8_SA(0, 0), a2, voffA);
.LBB0_912:
	ds_read_b128 v[96:99], v230
	ds_read_b128 v[100:103], v230 offset:1024
	ds_read_b128 v[104:107], v230 offset:2048
	ds_read_b128 v[116:119], v230 offset:3072
	ds_read_b128 v[120:123], v231
	ds_read_b128 v[124:127], v231 offset:1024
	ds_read_b128 v[136:139], v231 offset:2048
	ds_read_b128 v[148:151], v231 offset:3072
	s_add_i32 s56, s24, 2
	s_add_u32 s25, s4, 0xfffc0080
	s_addc_u32 s26, s5, -1
	s_cmp_eq_u32 s44, s24
	s_cselect_b32 s24, s53, s54
	s_cselect_b32 s27, s17, s26
	s_cselect_b32 s26, s19, s25
	s_cselect_b32 s25, s33, s55
	v_lshl_add_u64 v[192:193], s[4:5], 0, v[220:221]
	s_add_i32 m0, s31, 0xc000
	ds_read_b128 v[160:163], v232
	ds_read_b128 v[164:167], v232 offset:1024
	ds_read_b128 v[168:171], v232 offset:2048
	ds_read_b128 v[172:175], v232 offset:3072
	ds_read_b128 v[176:179], v232 offset:4096
	ds_read_b128 v[180:183], v232 offset:5120
	ds_read_b128 v[184:187], v232 offset:6144
	ds_read_b128 v[188:191], v232 offset:7168
	global_load_lds_dwordx4 v[192:193], off
	v_lshl_add_u64 v[192:193], s[4:5], 0, v[222:223]
	s_add_i32 m0, s31, 0xe000
	s_nop 0
	global_load_lds_dwordx4 v[192:193], off
	s_waitcnt vmcnt(8)
	s_waitcnt lgkmcnt(0)
	s_barrier
	s_setprio 1
	s_waitcnt lgkmcnt(0)
	v_mfma_f32_16x16x32_bf16 v[156:159], v[96:99], v[160:163], v[156:159]
	v_mfma_f32_16x16x32_bf16 v[156:159], v[100:103], v[164:167], v[156:159]
	v_mfma_f32_16x16x32_bf16 v[152:155], v[116:119], v[164:167], v[152:155]
	v_mfma_f32_16x16x32_bf16 v[152:155], v[104:107], v[160:163], v[152:155]
	v_mfma_f32_16x16x32_bf16 v[144:147], v[120:123], v[160:163], v[144:147]
	v_mfma_f32_16x16x32_bf16 v[144:147], v[124:127], v[164:167], v[144:147]
	v_mfma_f32_16x16x32_bf16 v[140:143], v[148:151], v[164:167], v[140:143]
	v_mfma_f32_16x16x32_bf16 v[140:143], v[136:139], v[160:163], v[140:143]
	v_mfma_f32_16x16x32_bf16 v[108:111], v[136:139], v[168:171], v[108:111]
	v_mfma_f32_16x16x32_bf16 v[108:111], v[148:151], v[172:175], v[108:111]
	v_mfma_f32_16x16x32_bf16 v[112:115], v[124:127], v[172:175], v[112:115]
	v_mfma_f32_16x16x32_bf16 v[112:115], v[120:123], v[168:171], v[112:115]
	v_mfma_f32_16x16x32_bf16 v[128:131], v[104:107], v[168:171], v[128:131]
	v_mfma_f32_16x16x32_bf16 v[128:131], v[116:119], v[172:175], v[128:131]
	v_mfma_f32_16x16x32_bf16 v[132:135], v[100:103], v[172:175], v[132:135]
	v_mfma_f32_16x16x32_bf16 v[132:135], v[96:99], v[168:171], v[132:135]
	s_setprio 0
	s_setprio 1
	v_mfma_f32_16x16x32_bf16 v[92:95], v[96:99], v[176:179], v[92:95]
	v_mfma_f32_16x16x32_bf16 v[92:95], v[100:103], v[180:183], v[92:95]
	v_mfma_f32_16x16x32_bf16 v[88:91], v[116:119], v[180:183], v[88:91]
	v_mfma_f32_16x16x32_bf16 v[88:91], v[104:107], v[176:179], v[88:91]
	v_mfma_f32_16x16x32_bf16 v[84:87], v[120:123], v[176:179], v[84:87]
	v_mfma_f32_16x16x32_bf16 v[84:87], v[124:127], v[180:183], v[84:87]
	v_mfma_f32_16x16x32_bf16 v[80:83], v[148:151], v[180:183], v[80:83]
	v_mfma_f32_16x16x32_bf16 v[80:83], v[136:139], v[176:179], v[80:83]
	v_mfma_f32_16x16x32_bf16 v[64:67], v[136:139], v[184:187], v[64:67]
	v_mfma_f32_16x16x32_bf16 v[64:67], v[148:151], v[188:191], v[64:67]
	v_mfma_f32_16x16x32_bf16 v[68:71], v[124:127], v[188:191], v[68:71]
	v_mfma_f32_16x16x32_bf16 v[68:71], v[120:123], v[184:187], v[68:71]
	v_mfma_f32_16x16x32_bf16 v[72:75], v[104:107], v[184:187], v[72:75]
	v_mfma_f32_16x16x32_bf16 v[72:75], v[116:119], v[188:191], v[72:75]
	v_mfma_f32_16x16x32_bf16 v[76:79], v[100:103], v[188:191], v[76:79]
	v_mfma_f32_16x16x32_bf16 v[76:79], v[96:99], v[184:187], v[76:79]
	s_setprio 0
	s_barrier
	s_add_i32 s57, s47, s30
	v_lshl_add_u64 v[192:193], s[24:25], 0, v[210:211]
	s_mov_b32 m0, s57
	ds_read_b128 v[160:163], v232 offset:16384
	ds_read_b128 v[164:167], v232 offset:17408
	ds_read_b128 v[168:171], v232 offset:18432
	ds_read_b128 v[172:175], v232 offset:19456
	ds_read_b128 v[176:179], v232 offset:20480
	ds_read_b128 v[180:183], v232 offset:21504
	ds_read_b128 v[184:187], v232 offset:22528
	ds_read_b128 v[188:191], v232 offset:23552
	global_load_lds_dwordx4 v[192:193], off
	s_add_i32 m0, s57, 0x2000
	s_add_u32 s58, s24, 0x40000
	v_lshl_add_u64 v[194:195], s[24:25], 0, v[214:215]
	s_addc_u32 s59, s25, 0
	s_add_i32 s57, s48, s30
	global_load_lds_dwordx4 v[194:195], off
	v_lshl_add_u64 v[196:197], s[58:59], 0, v[210:211]
	s_mov_b32 m0, s57
	v_lshl_add_u64 v[198:199], s[26:27], 0, v[212:213]
	global_load_lds_dwordx4 v[196:197], off
	v_lshl_add_u64 v[196:197], s[58:59], 0, v[214:215]
	s_add_i32 m0, s57, 0x2000
	s_nop 0
	global_load_lds_dwordx4 v[196:197], off
	v_lshl_add_u64 v[196:197], s[26:27], 0, v[208:209]
	s_mov_b32 m0, s31
	s_nop 0
	global_load_lds_dwordx4 v[196:197], off
	s_mov_b32 m0, s34
	s_nop 0
	global_load_lds_dwordx4 v[198:199], off
	s_waitcnt vmcnt(8)
	s_waitcnt lgkmcnt(0)
	s_barrier
; #define PG8_STAGE(bufoff, gbase, voff) do { _Pragma("unroll") for (int _i = 0; _i < 2; ++_i) \
;         __builtin_amdgcn_global_load_lds((const unsigned*)((const char*)(gbase) + (voff)[_i]), (LAS unsigned*)(lds + (bufoff) + ldsw + _i * 8192), 16, 0, 0); } while (0)
; #define PG8_LDA(dst, b, h) do { _Pragma("unroll") for (int m = 0; m < 4; ++m) _Pragma("unroll") for (int k = 0; k < 2; ++k) dst[m][k] = *(const LAS bf16x8*)(lds + PG8_SA(b, h) + aoff + m * 2048 + k * 1024); } while (0)
; #define PG8_LDB(dst, b, h) do { _Pragma("unroll") for (int n = 0; n < 2; ++n) _Pragma("unroll") for (int k = 0; k < 2; ++k) dst[n][k] = *(const LAS bf16x8*)(lds + PG8_SB(b, h) + boff + n * 2048 + k * 1024); } while (0)
; #define PG8_MMA(ai, bj, At, Bt) do { __builtin_amdgcn_s_setprio(1); _Pragma("unroll") for (int m = 0; m < 4; ++m) _Pragma("unroll") for (int n = 0; n < 2; ++n) _Pragma("unroll") for (int k = 0; k < 2; ++k) \
;         acc[ai][bj][m][n] = __builtin_amdgcn_mfma_f32_16x16x32_bf16(Bt[n][k], At[m][k], acc[ai][bj][m][n], 0, 0, 0); __builtin_amdgcn_s_setprio(0); } while (0)
; #define PG8_WAIT_V(n) asm volatile("s_waitcnt vmcnt(" #n ")" ::: "memory")
; #define PG8_WAIT_L(n) asm volatile("s_waitcnt lgkmcnt(" #n ")" ::: "memory")
; #define PG8_BAR __builtin_amdgcn_s_barrier()
; #define PG8_SCHED __builtin_amdgcn_sched_barrier(0)
; template <class Epi>
; __device__ __forceinline__ void gemm_phase(LAS unsigned char* lds, const Gemm g, const StaticOrder& S, const Epi& E) {
;     ...
;             PG8_WAIT_V(8); PG8_WAIT_L(0); PG8_BAR; PG8_MMA(1, 0, At, B0); PG8_MMA(1, 1, At, B1); PG8_BAR; PG8_SCHED;
;             PG8_LDB(B0, 1, 0); PG8_LDB(B1, 1, 1); PG8_SCHED; PG8_LDA(At, 1, 0); PG8_STAGE(PG8_SA(0, 1), a2 + hstepA, voffA);
;             PG8_WAIT_V(8); PG8_WAIT_L(0); PG8_BAR; PG8_MMA(0, 0, At, B0); PG8_MMA(0, 1, At, B1); PG8_BAR; PG8_SCHED;
	s_setprio 1
	s_waitcnt lgkmcnt(0)
	v_mfma_f32_16x16x32_bf16 v[60:63], v[96:99], v[160:163], v[60:63]
	v_mfma_f32_16x16x32_bf16 v[60:63], v[100:103], v[164:167], v[60:63]
	v_mfma_f32_16x16x32_bf16 v[56:59], v[116:119], v[164:167], v[56:59]
	v_mfma_f32_16x16x32_bf16 v[56:59], v[104:107], v[160:163], v[56:59]
	v_mfma_f32_16x16x32_bf16 v[52:55], v[120:123], v[160:163], v[52:55]
	v_mfma_f32_16x16x32_bf16 v[52:55], v[124:127], v[164:167], v[52:55]
	v_mfma_f32_16x16x32_bf16 v[48:51], v[148:151], v[164:167], v[48:51]
	v_mfma_f32_16x16x32_bf16 v[48:51], v[136:139], v[160:163], v[48:51]
	v_mfma_f32_16x16x32_bf16 v[32:35], v[136:139], v[168:171], v[32:35]
	v_mfma_f32_16x16x32_bf16 v[32:35], v[148:151], v[172:175], v[32:35]
	v_mfma_f32_16x16x32_bf16 v[36:39], v[124:127], v[172:175], v[36:39]
	v_mfma_f32_16x16x32_bf16 v[36:39], v[120:123], v[168:171], v[36:39]
	v_mfma_f32_16x16x32_bf16 v[40:43], v[104:107], v[168:171], v[40:43]
	v_mfma_f32_16x16x32_bf16 v[40:43], v[116:119], v[172:175], v[40:43]
	v_mfma_f32_16x16x32_bf16 v[44:47], v[100:103], v[172:175], v[44:47]
	v_mfma_f32_16x16x32_bf16 v[44:47], v[96:99], v[168:171], v[44:47]
	s_setprio 0
	s_setprio 1
	v_mfma_f32_16x16x32_bf16 v[28:31], v[96:99], v[176:179], v[28:31]
	v_mfma_f32_16x16x32_bf16 v[28:31], v[100:103], v[180:183], v[28:31]
	v_mfma_f32_16x16x32_bf16 v[24:27], v[116:119], v[180:183], v[24:27]
	v_mfma_f32_16x16x32_bf16 v[24:27], v[104:107], v[176:179], v[24:27]
	v_mfma_f32_16x16x32_bf16 v[20:23], v[120:123], v[176:179], v[20:23]
	v_mfma_f32_16x16x32_bf16 v[20:23], v[124:127], v[180:183], v[20:23]
	v_mfma_f32_16x16x32_bf16 v[16:19], v[148:151], v[180:183], v[16:19]
	v_mfma_f32_16x16x32_bf16 v[16:19], v[136:139], v[176:179], v[16:19]
	v_mfma_f32_16x16x32_bf16 v[0:3], v[136:139], v[184:187], v[0:3]
	v_mfma_f32_16x16x32_bf16 v[0:3], v[148:151], v[188:191], v[0:3]
	v_mfma_f32_16x16x32_bf16 v[4:7], v[124:127], v[188:191], v[4:7]
	v_mfma_f32_16x16x32_bf16 v[4:7], v[120:123], v[184:187], v[4:7]
	v_mfma_f32_16x16x32_bf16 v[8:11], v[104:107], v[184:187], v[8:11]
	v_mfma_f32_16x16x32_bf16 v[8:11], v[116:119], v[188:191], v[8:11]
	v_mfma_f32_16x16x32_bf16 v[12:15], v[100:103], v[188:191], v[12:15]
	v_mfma_f32_16x16x32_bf16 v[12:15], v[96:99], v[184:187], v[12:15]
	s_setprio 0
	s_barrier
	s_add_i32 s57, 0, 0x18000
	s_add_i32 s58, 0, 0x1c000
	v_add_u32_e32 v116, s57, v229
	v_add_u32_e32 v148, s58, v229
	ds_read_b128 v[96:99], v116
	ds_read_b128 v[100:103], v116 offset:1024
	ds_read_b128 v[104:107], v116 offset:2048
	ds_read_b128 v[116:119], v116 offset:3072
	ds_read_b128 v[120:123], v148
	ds_read_b128 v[124:127], v148 offset:1024
	ds_read_b128 v[136:139], v148 offset:2048
	ds_read_b128 v[148:151], v148 offset:3072
	s_add_u32 s26, s26, 0x40000
	s_addc_u32 s27, s27, 0
	s_mov_b32 m0, s35
	v_lshl_add_u64 v[200:201], s[26:27], 0, v[208:209]
	ds_read_b128 v[160:163], v232 offset:32768
	ds_read_b128 v[164:167], v232 offset:33792
	ds_read_b128 v[168:171], v232 offset:34816
	ds_read_b128 v[172:175], v232 offset:35840
	ds_read_b128 v[176:179], v232 offset:36864
	ds_read_b128 v[180:183], v232 offset:37888
	ds_read_b128 v[184:187], v232 offset:38912
	ds_read_b128 v[188:191], v232 offset:39936
	global_load_lds_dwordx4 v[200:201], off
	v_lshl_add_u64 v[200:201], s[26:27], 0, v[212:213]
	s_mov_b32 m0, s36
	s_nop 0
	global_load_lds_dwordx4 v[200:201], off
	s_waitcnt vmcnt(8)
	s_waitcnt lgkmcnt(0)
	s_barrier
	s_setprio 1
	s_waitcnt lgkmcnt(0)
	v_mfma_f32_16x16x32_bf16 v[156:159], v[96:99], v[160:163], v[156:159]
	v_mfma_f32_16x16x32_bf16 v[156:159], v[100:103], v[164:167], v[156:159]
	v_mfma_f32_16x16x32_bf16 v[152:155], v[116:119], v[164:167], v[152:155]
	v_mfma_f32_16x16x32_bf16 v[152:155], v[104:107], v[160:163], v[152:155]
	v_mfma_f32_16x16x32_bf16 v[144:147], v[120:123], v[160:163], v[144:147]
	v_mfma_f32_16x16x32_bf16 v[144:147], v[124:127], v[164:167], v[144:147]
	v_mfma_f32_16x16x32_bf16 v[140:143], v[148:151], v[164:167], v[140:143]
	v_mfma_f32_16x16x32_bf16 v[140:143], v[136:139], v[160:163], v[140:143]
	v_mfma_f32_16x16x32_bf16 v[108:111], v[136:139], v[168:171], v[108:111]
	v_mfma_f32_16x16x32_bf16 v[108:111], v[148:151], v[172:175], v[108:111]
	v_mfma_f32_16x16x32_bf16 v[112:115], v[124:127], v[172:175], v[112:115]
	v_mfma_f32_16x16x32_bf16 v[112:115], v[120:123], v[168:171], v[112:115]
	v_mfma_f32_16x16x32_bf16 v[128:131], v[104:107], v[168:171], v[128:131]
	v_mfma_f32_16x16x32_bf16 v[128:131], v[116:119], v[172:175], v[128:131]
	v_mfma_f32_16x16x32_bf16 v[132:135], v[100:103], v[172:175], v[132:135]
	v_mfma_f32_16x16x32_bf16 v[132:135], v[96:99], v[168:171], v[132:135]
	s_setprio 0
	s_setprio 1
	v_mfma_f32_16x16x32_bf16 v[92:95], v[96:99], v[176:179], v[92:95]
	v_mfma_f32_16x16x32_bf16 v[92:95], v[100:103], v[180:183], v[92:95]
	v_mfma_f32_16x16x32_bf16 v[88:91], v[116:119], v[180:183], v[88:91]
	v_mfma_f32_16x16x32_bf16 v[88:91], v[104:107], v[176:179], v[88:91]
	v_mfma_f32_16x16x32_bf16 v[84:87], v[120:123], v[176:179], v[84:87]
	v_mfma_f32_16x16x32_bf16 v[84:87], v[124:127], v[180:183], v[84:87]
	v_mfma_f32_16x16x32_bf16 v[80:83], v[148:151], v[180:183], v[80:83]
	v_mfma_f32_16x16x32_bf16 v[80:83], v[136:139], v[176:179], v[80:83]
	v_mfma_f32_16x16x32_bf16 v[64:67], v[136:139], v[184:187], v[64:67]
	v_mfma_f32_16x16x32_bf16 v[64:67], v[148:151], v[188:191], v[64:67]
	v_mfma_f32_16x16x32_bf16 v[68:71], v[124:127], v[188:191], v[68:71]
	v_mfma_f32_16x16x32_bf16 v[68:71], v[120:123], v[184:187], v[68:71]
	v_mfma_f32_16x16x32_bf16 v[72:75], v[104:107], v[184:187], v[72:75]
	v_mfma_f32_16x16x32_bf16 v[72:75], v[116:119], v[188:191], v[72:75]
	v_mfma_f32_16x16x32_bf16 v[76:79], v[100:103], v[188:191], v[76:79]
	v_mfma_f32_16x16x32_bf16 v[76:79], v[96:99], v[184:187], v[76:79]
	s_setprio 0
	s_barrier
; #define PG8_STAGE(bufoff, gbase, voff) do { _Pragma("unroll") for (int _i = 0; _i < 2; ++_i) \
;         __builtin_amdgcn_global_load_lds((const unsigned*)((const char*)(gbase) + (voff)[_i]), (LAS unsigned*)(lds + (bufoff) + ldsw + _i * 8192), 16, 0, 0); } while (0)
; #define PG8_LDA(dst, b, h) do { _Pragma("unroll") for (int m = 0; m < 4; ++m) _Pragma("unroll") for (int k = 0; k < 2; ++k) dst[m][k] = *(const LAS bf16x8*)(lds + PG8_SA(b, h) + aoff + m * 2048 + k * 1024); } while (0)
; #define PG8_MMA(ai, bj, At, Bt) do { __builtin_amdgcn_s_setprio(1); _Pragma("unroll") for (int m = 0; m < 4; ++m) _Pragma("unroll") for (int n = 0; n < 2; ++n) _Pragma("unroll") for (int k = 0; k < 2; ++k) \
;         acc[ai][bj][m][n] = __builtin_amdgcn_mfma_f32_16x16x32_bf16(Bt[n][k], At[m][k], acc[ai][bj][m][n], 0, 0, 0); __builtin_amdgcn_s_setprio(0); } while (0)
; #define PG8_WAIT_V(n) asm volatile("s_waitcnt vmcnt(" #n ")" ::: "memory")
; #define PG8_WAIT_L(n) asm volatile("s_waitcnt lgkmcnt(" #n ")" ::: "memory")
; #define PG8_BAR __builtin_amdgcn_s_barrier()
; #define PG8_SCHED __builtin_amdgcn_sched_barrier(0)
; template <class Epi>
; __device__ __forceinline__ void gemm_phase(LAS unsigned char* lds, const Gemm g, const StaticOrder& S, const Epi& E) {
;     ...
;             PG8_LDA(At, 1, 1); PG8_STAGE(PG8_SB(1, 0), b3, voffB); PG8_STAGE(PG8_SB(1, 1), b3 + hstepB, voffB); PG8_STAGE(PG8_SA(1, 0), a3, voffA);
;             PG8_WAIT_V(8); PG8_WAIT_L(0); PG8_BAR; PG8_MMA(1, 0, At, B0); PG8_MMA(1, 1, At, B1); PG8_BAR; PG8_SCHED;
;         }
	s_add_i32 s26, s57, s30
	v_lshl_add_u64 v[192:193], v[192:193], 0, s[10:11]
	s_mov_b32 m0, s26
	ds_read_b128 v[160:163], v232 offset:49152
	ds_read_b128 v[164:167], v232 offset:50176
	ds_read_b128 v[168:171], v232 offset:51200
	ds_read_b128 v[172:175], v232 offset:52224
	ds_read_b128 v[176:179], v232 offset:53248
	ds_read_b128 v[180:183], v232 offset:54272
	ds_read_b128 v[184:187], v232 offset:55296
	ds_read_b128 v[188:191], v232 offset:56320
	global_load_lds_dwordx4 v[192:193], off
	s_add_i32 m0, s26, 0x2000
	s_add_u32 s24, s24, 0x40080
	v_lshl_add_u64 v[192:193], v[194:195], 0, s[10:11]
	s_addc_u32 s25, s25, 0
	s_add_i32 s26, s58, s30
	global_load_lds_dwordx4 v[192:193], off
	v_lshl_add_u64 v[192:193], s[24:25], 0, v[210:211]
	s_mov_b32 m0, s26
	s_nop 0
	global_load_lds_dwordx4 v[192:193], off
	v_lshl_add_u64 v[192:193], s[24:25], 0, v[214:215]
	s_add_i32 m0, s26, 0x2000
	s_nop 0
	global_load_lds_dwordx4 v[192:193], off
	v_lshl_add_u64 v[192:193], v[196:197], 0, s[10:11]
	s_mov_b32 m0, s40
	s_nop 0
	global_load_lds_dwordx4 v[192:193], off
	v_lshl_add_u64 v[192:193], v[198:199], 0, s[10:11]
	s_mov_b32 m0, s41
	s_nop 0
	global_load_lds_dwordx4 v[192:193], off
	s_waitcnt vmcnt(8)
	s_waitcnt lgkmcnt(0)
	s_barrier
	s_setprio 1
	s_waitcnt lgkmcnt(0)
	v_mfma_f32_16x16x32_bf16 v[60:63], v[96:99], v[160:163], v[60:63]
	v_mfma_f32_16x16x32_bf16 v[60:63], v[100:103], v[164:167], v[60:63]
	v_mfma_f32_16x16x32_bf16 v[56:59], v[116:119], v[164:167], v[56:59]
	v_mfma_f32_16x16x32_bf16 v[56:59], v[104:107], v[160:163], v[56:59]
	v_mfma_f32_16x16x32_bf16 v[52:55], v[120:123], v[160:163], v[52:55]
	v_mfma_f32_16x16x32_bf16 v[52:55], v[124:127], v[164:167], v[52:55]
	v_mfma_f32_16x16x32_bf16 v[48:51], v[148:151], v[164:167], v[48:51]
	v_mfma_f32_16x16x32_bf16 v[48:51], v[136:139], v[160:163], v[48:51]
	v_mfma_f32_16x16x32_bf16 v[32:35], v[136:139], v[168:171], v[32:35]
	v_mfma_f32_16x16x32_bf16 v[32:35], v[148:151], v[172:175], v[32:35]
	v_mfma_f32_16x16x32_bf16 v[36:39], v[124:127], v[172:175], v[36:39]
	v_mfma_f32_16x16x32_bf16 v[36:39], v[120:123], v[168:171], v[36:39]
	v_mfma_f32_16x16x32_bf16 v[40:43], v[104:107], v[168:171], v[40:43]
	v_mfma_f32_16x16x32_bf16 v[40:43], v[116:119], v[172:175], v[40:43]
	v_mfma_f32_16x16x32_bf16 v[44:47], v[100:103], v[172:175], v[44:47]
	v_mfma_f32_16x16x32_bf16 v[44:47], v[96:99], v[168:171], v[44:47]
	s_setprio 0
	s_setprio 1
	v_mfma_f32_16x16x32_bf16 v[28:31], v[96:99], v[176:179], v[28:31]
	v_mfma_f32_16x16x32_bf16 v[28:31], v[100:103], v[180:183], v[28:31]
	v_mfma_f32_16x16x32_bf16 v[24:27], v[116:119], v[180:183], v[24:27]
	v_mfma_f32_16x16x32_bf16 v[24:27], v[104:107], v[176:179], v[24:27]
	v_mfma_f32_16x16x32_bf16 v[20:23], v[120:123], v[176:179], v[20:23]
	v_mfma_f32_16x16x32_bf16 v[20:23], v[124:127], v[180:183], v[20:23]
	v_mfma_f32_16x16x32_bf16 v[16:19], v[148:151], v[180:183], v[16:19]
	v_mfma_f32_16x16x32_bf16 v[16:19], v[136:139], v[176:179], v[16:19]
	v_mfma_f32_16x16x32_bf16 v[0:3], v[136:139], v[184:187], v[0:3]
	v_mfma_f32_16x16x32_bf16 v[0:3], v[148:151], v[188:191], v[0:3]
	v_mfma_f32_16x16x32_bf16 v[4:7], v[124:127], v[188:191], v[4:7]
	v_mfma_f32_16x16x32_bf16 v[4:7], v[120:123], v[184:187], v[4:7]
	v_mfma_f32_16x16x32_bf16 v[8:11], v[104:107], v[184:187], v[8:11]
	v_mfma_f32_16x16x32_bf16 v[8:11], v[116:119], v[188:191], v[8:11]
	v_mfma_f32_16x16x32_bf16 v[12:15], v[100:103], v[188:191], v[12:15]
	v_mfma_f32_16x16x32_bf16 v[12:15], v[96:99], v[184:187], v[12:15]
	s_add_u32 s4, s4, 0x100
	s_addc_u32 s5, s5, 0
	s_add_u32 s54, s54, 0x100
	s_addc_u32 s55, s55, 0
	s_cmp_ge_i32 s56, s39
	s_mov_b32 s24, s56
	s_setprio 0
	s_barrier
	s_cbranch_scc0 .LBB0_912

; #define PG8_STAGE(bufoff, gbase, voff) do { _Pragma("unroll") for (int _i = 0; _i < 2; ++_i) \
;         __builtin_amdgcn_global_load_lds((const unsigned*)((const char*)(gbase) + (voff)[_i]), (LAS unsigned*)(lds + (bufoff) + ldsw + _i * 8192), 16, 0, 0); } while (0)
; #define PG8_LDA(dst, b, h) do { _Pragma("unroll") for (int m = 0; m < 4; ++m) _Pragma("unroll") for (int k = 0; k < 2; ++k) dst[m][k] = *(const LAS bf16x8*)(lds + PG8_SA(b, h) + aoff + m * 2048 + k * 1024); } while (0)
; #define PG8_LDB(dst, b, h) do { _Pragma("unroll") for (int n = 0; n < 2; ++n) _Pragma("unroll") for (int k = 0; k < 2; ++k) dst[n][k] = *(const LAS bf16x8*)(lds + PG8_SB(b, h) + boff + n * 2048 + k * 1024); } while (0)
; #define PG8_MMA(ai, bj, At, Bt) do { __builtin_amdgcn_s_setprio(1); _Pragma("unroll") for (int m = 0; m < 4; ++m) _Pragma("unroll") for (int n = 0; n < 2; ++n) _Pragma("unroll") for (int k = 0; k < 2; ++k) \
;         acc[ai][bj][m][n] = __builtin_amdgcn_mfma_f32_16x16x32_bf16(Bt[n][k], At[m][k], acc[ai][bj][m][n], 0, 0, 0); __builtin_amdgcn_s_setprio(0); } while (0)
; #define PG8_WAIT_V(n) asm volatile("s_waitcnt vmcnt(" #n ")" ::: "memory")
; #define PG8_WAIT_L(n) asm volatile("s_waitcnt lgkmcnt(" #n ")" ::: "memory")
; #define PG8_BAR __builtin_amdgcn_s_barrier()
; #define PG8_SCHED __builtin_amdgcn_sched_barrier(0)
; template <class Epi>
; __device__ __forceinline__ void gemm_phase(LAS unsigned char* lds, const Gemm g, const StaticOrder& S, const Epi& E) {
;     ...
;         for (int t = 0; t < nt; t += 2) {
;             const bool last = (t == nt - 2);
;             const char* a1 = cA + (size_t)(t + 1) * kstep;
;             const char* a2 = last ? nA : cA + (size_t)(t + 2) * kstep; const char* b2 = last ? nB : cB + (size_t)(t + 2) * kstep;
;             const char* a3 = a2 + kstep; const char* b3 = b2 + kstep;
;             PG8_LDB(B0, 0, 0); PG8_LDB(B1, 0, 1); PG8_SCHED; PG8_LDA(At, 0, 0); PG8_STAGE(PG8_SA(1, 1), a1 + hstepA, voffA);
;             PG8_WAIT_V(8); PG8_WAIT_L(0); PG8_BAR; PG8_MMA(0, 0, At, B0); PG8_MMA(0, 1, At, B1); PG8_BAR; PG8_SCHED;
;             PG8_LDA(At, 0, 1); PG8_STAGE(PG8_SB(0, 0), b2, voffB); PG8_STAGE(PG8_SB(0, 1), b2 + hstepB, voffB); PG8_STAGE(PG8_SA(0, 0), a2, voffA);
.LBB0_1046:
	ds_read_b128 v[128:131], v185
	ds_read_b128 v[132:135], v185 offset:1024
	ds_read_b128 v[136:139], v185 offset:2048
	ds_read_b128 v[140:143], v185 offset:3072
	ds_read_b128 v[144:147], v186
	ds_read_b128 v[148:151], v186 offset:1024
	ds_read_b128 v[152:155], v186 offset:2048
	ds_read_b128 v[156:159], v186 offset:3072
	s_add_i32 s73, s46, 2
	s_add_u32 s47, s12, 0xfff80080
	s_addc_u32 s48, s13, -1
	s_cmp_eq_u32 s62, s46
	s_cselect_b32 s46, s41, s71
	s_cselect_b32 s49, s1, s48
	s_cselect_b32 s48, s33, s47
	s_cselect_b32 s47, s39, s72
	v_lshl_add_u64 v[182:183], s[12:13], 0, v[174:175]
	s_add_i32 m0, s5, 0xc000
	ds_read_b128 v[190:193], v187
	ds_read_b128 v[194:197], v187 offset:1024
	ds_read_b128 v[198:201], v187 offset:2048
	ds_read_b128 v[208:211], v187 offset:3072
	ds_read_b128 v[212:215], v187 offset:4096
	ds_read_b128 v[216:219], v187 offset:5120
	ds_read_b128 v[220:223], v187 offset:6144
	ds_read_b128 v[224:227], v187 offset:7168
	global_load_lds_dwordx4 v[182:183], off
	v_lshl_add_u64 v[182:183], s[12:13], 0, v[176:177]
	s_add_i32 m0, s5, 0xe000
	s_nop 0
	global_load_lds_dwordx4 v[182:183], off
	s_waitcnt vmcnt(8)
	s_waitcnt lgkmcnt(0)
	s_barrier
	s_setprio 1
	s_waitcnt lgkmcnt(0)
	v_mfma_f32_16x16x32_bf16 v[120:123], v[128:131], v[190:193], v[120:123]
	v_mfma_f32_16x16x32_bf16 v[120:123], v[132:135], v[194:197], v[120:123]
	v_mfma_f32_16x16x32_bf16 v[124:127], v[140:143], v[194:197], v[124:127]
	v_mfma_f32_16x16x32_bf16 v[124:127], v[136:139], v[190:193], v[124:127]
	v_mfma_f32_16x16x32_bf16 v[116:119], v[144:147], v[190:193], v[116:119]
	v_mfma_f32_16x16x32_bf16 v[116:119], v[148:151], v[194:197], v[116:119]
	v_mfma_f32_16x16x32_bf16 v[112:115], v[156:159], v[194:197], v[112:115]
	v_mfma_f32_16x16x32_bf16 v[112:115], v[152:155], v[190:193], v[112:115]
	v_mfma_f32_16x16x32_bf16 v[96:99], v[152:155], v[198:201], v[96:99]
	v_mfma_f32_16x16x32_bf16 v[96:99], v[156:159], v[208:211], v[96:99]
	v_mfma_f32_16x16x32_bf16 v[100:103], v[148:151], v[208:211], v[100:103]
	v_mfma_f32_16x16x32_bf16 v[100:103], v[144:147], v[198:201], v[100:103]
	v_mfma_f32_16x16x32_bf16 v[104:107], v[136:139], v[198:201], v[104:107]
	v_mfma_f32_16x16x32_bf16 v[104:107], v[140:143], v[208:211], v[104:107]
	v_mfma_f32_16x16x32_bf16 v[108:111], v[132:135], v[208:211], v[108:111]
	v_mfma_f32_16x16x32_bf16 v[108:111], v[128:131], v[198:201], v[108:111]
	s_setprio 0
	s_setprio 1
	v_mfma_f32_16x16x32_bf16 v[92:95], v[128:131], v[212:215], v[92:95]
	v_mfma_f32_16x16x32_bf16 v[92:95], v[132:135], v[216:219], v[92:95]
	v_mfma_f32_16x16x32_bf16 v[88:91], v[140:143], v[216:219], v[88:91]
	v_mfma_f32_16x16x32_bf16 v[88:91], v[136:139], v[212:215], v[88:91]
	v_mfma_f32_16x16x32_bf16 v[84:87], v[144:147], v[212:215], v[84:87]
	v_mfma_f32_16x16x32_bf16 v[84:87], v[148:151], v[216:219], v[84:87]
	v_mfma_f32_16x16x32_bf16 v[80:83], v[156:159], v[216:219], v[80:83]
	v_mfma_f32_16x16x32_bf16 v[80:83], v[152:155], v[212:215], v[80:83]
	v_mfma_f32_16x16x32_bf16 v[64:67], v[152:155], v[220:223], v[64:67]
	v_mfma_f32_16x16x32_bf16 v[64:67], v[156:159], v[224:227], v[64:67]
	v_mfma_f32_16x16x32_bf16 v[68:71], v[148:151], v[224:227], v[68:71]
	v_mfma_f32_16x16x32_bf16 v[68:71], v[144:147], v[220:223], v[68:71]
	v_mfma_f32_16x16x32_bf16 v[72:75], v[136:139], v[220:223], v[72:75]
	v_mfma_f32_16x16x32_bf16 v[72:75], v[140:143], v[224:227], v[72:75]
	v_mfma_f32_16x16x32_bf16 v[76:79], v[132:135], v[224:227], v[76:79]
	v_mfma_f32_16x16x32_bf16 v[76:79], v[128:131], v[220:223], v[76:79]
	s_setprio 0
	s_barrier
	s_add_i32 s76, s65, s54
	v_lshl_add_u64 v[182:183], s[46:47], 0, v[162:163]
	s_mov_b32 m0, s76
	ds_read_b128 v[190:193], v187 offset:16384
	ds_read_b128 v[194:197], v187 offset:17408
	ds_read_b128 v[198:201], v187 offset:18432
	ds_read_b128 v[208:211], v187 offset:19456
	ds_read_b128 v[212:215], v187 offset:20480
	ds_read_b128 v[216:219], v187 offset:21504
	ds_read_b128 v[220:223], v187 offset:22528
	ds_read_b128 v[224:227], v187 offset:23552
	global_load_lds_dwordx4 v[182:183], off
	s_add_i32 m0, s76, 0x2000
	s_add_u32 s76, s46, 0x80000
	v_lshl_add_u64 v[202:203], s[46:47], 0, v[166:167]
	s_addc_u32 s77, s47, 0
	s_add_i32 s78, s66, s54
	global_load_lds_dwordx4 v[202:203], off
	v_lshl_add_u64 v[230:231], s[76:77], 0, v[162:163]
	s_mov_b32 m0, s78
	v_lshl_add_u64 v[232:233], s[48:49], 0, v[164:165]
	global_load_lds_dwordx4 v[230:231], off
	v_lshl_add_u64 v[230:231], s[76:77], 0, v[166:167]
	s_add_i32 m0, s78, 0x2000
	s_nop 0
	global_load_lds_dwordx4 v[230:231], off
	v_lshl_add_u64 v[230:231], s[48:49], 0, v[160:161]
	s_mov_b32 m0, s5
	s_nop 0
	global_load_lds_dwordx4 v[230:231], off
	s_mov_b32 m0, s55
	s_nop 0
	global_load_lds_dwordx4 v[232:233], off
	s_waitcnt vmcnt(8)
	s_waitcnt lgkmcnt(0)
	s_barrier
; #define PG8_STAGE(bufoff, gbase, voff) do { _Pragma("unroll") for (int _i = 0; _i < 2; ++_i) \
;         __builtin_amdgcn_global_load_lds((const unsigned*)((const char*)(gbase) + (voff)[_i]), (LAS unsigned*)(lds + (bufoff) + ldsw + _i * 8192), 16, 0, 0); } while (0)
; #define PG8_LDA(dst, b, h) do { _Pragma("unroll") for (int m = 0; m < 4; ++m) _Pragma("unroll") for (int k = 0; k < 2; ++k) dst[m][k] = *(const LAS bf16x8*)(lds + PG8_SA(b, h) + aoff + m * 2048 + k * 1024); } while (0)
; #define PG8_LDB(dst, b, h) do { _Pragma("unroll") for (int n = 0; n < 2; ++n) _Pragma("unroll") for (int k = 0; k < 2; ++k) dst[n][k] = *(const LAS bf16x8*)(lds + PG8_SB(b, h) + boff + n * 2048 + k * 1024); } while (0)
; #define PG8_MMA(ai, bj, At, Bt) do { __builtin_amdgcn_s_setprio(1); _Pragma("unroll") for (int m = 0; m < 4; ++m) _Pragma("unroll") for (int n = 0; n < 2; ++n) _Pragma("unroll") for (int k = 0; k < 2; ++k) \
;         acc[ai][bj][m][n] = __builtin_amdgcn_mfma_f32_16x16x32_bf16(Bt[n][k], At[m][k], acc[ai][bj][m][n], 0, 0, 0); __builtin_amdgcn_s_setprio(0); } while (0)
; #define PG8_WAIT_V(n) asm volatile("s_waitcnt vmcnt(" #n ")" ::: "memory")
; #define PG8_WAIT_L(n) asm volatile("s_waitcnt lgkmcnt(" #n ")" ::: "memory")
; #define PG8_BAR __builtin_amdgcn_s_barrier()
; #define PG8_SCHED __builtin_amdgcn_sched_barrier(0)
; template <class Epi>
; __device__ __forceinline__ void gemm_phase(LAS unsigned char* lds, const Gemm g, const StaticOrder& S, const Epi& E) {
;     ...
;             PG8_WAIT_V(8); PG8_WAIT_L(0); PG8_BAR; PG8_MMA(1, 0, At, B0); PG8_MMA(1, 1, At, B1); PG8_BAR; PG8_SCHED;
;             PG8_LDB(B0, 1, 0); PG8_LDB(B1, 1, 1); PG8_SCHED; PG8_LDA(At, 1, 0); PG8_STAGE(PG8_SA(0, 1), a2 + hstepA, voffA);
;             PG8_WAIT_V(8); PG8_WAIT_L(0); PG8_BAR; PG8_MMA(0, 0, At, B0); PG8_MMA(0, 1, At, B1); PG8_BAR; PG8_SCHED;
	s_setprio 1
	s_waitcnt lgkmcnt(0)
	v_mfma_f32_16x16x32_bf16 v[60:63], v[128:131], v[190:193], v[60:63]
	v_mfma_f32_16x16x32_bf16 v[60:63], v[132:135], v[194:197], v[60:63]
	v_mfma_f32_16x16x32_bf16 v[56:59], v[140:143], v[194:197], v[56:59]
	v_mfma_f32_16x16x32_bf16 v[56:59], v[136:139], v[190:193], v[56:59]
	v_mfma_f32_16x16x32_bf16 v[52:55], v[144:147], v[190:193], v[52:55]
	v_mfma_f32_16x16x32_bf16 v[52:55], v[148:151], v[194:197], v[52:55]
	v_mfma_f32_16x16x32_bf16 v[48:51], v[156:159], v[194:197], v[48:51]
	v_mfma_f32_16x16x32_bf16 v[48:51], v[152:155], v[190:193], v[48:51]
	v_mfma_f32_16x16x32_bf16 v[32:35], v[152:155], v[198:201], v[32:35]
	v_mfma_f32_16x16x32_bf16 v[32:35], v[156:159], v[208:211], v[32:35]
	v_mfma_f32_16x16x32_bf16 v[36:39], v[148:151], v[208:211], v[36:39]
	v_mfma_f32_16x16x32_bf16 v[36:39], v[144:147], v[198:201], v[36:39]
	v_mfma_f32_16x16x32_bf16 v[40:43], v[136:139], v[198:201], v[40:43]
	v_mfma_f32_16x16x32_bf16 v[40:43], v[140:143], v[208:211], v[40:43]
	v_mfma_f32_16x16x32_bf16 v[44:47], v[132:135], v[208:211], v[44:47]
	v_mfma_f32_16x16x32_bf16 v[44:47], v[128:131], v[198:201], v[44:47]
	s_setprio 0
	s_setprio 1
	v_mfma_f32_16x16x32_bf16 v[28:31], v[128:131], v[212:215], v[28:31]
	v_mfma_f32_16x16x32_bf16 v[28:31], v[132:135], v[216:219], v[28:31]
	v_mfma_f32_16x16x32_bf16 v[24:27], v[140:143], v[216:219], v[24:27]
	v_mfma_f32_16x16x32_bf16 v[24:27], v[136:139], v[212:215], v[24:27]
	v_mfma_f32_16x16x32_bf16 v[20:23], v[144:147], v[212:215], v[20:23]
	v_mfma_f32_16x16x32_bf16 v[20:23], v[148:151], v[216:219], v[20:23]
	v_mfma_f32_16x16x32_bf16 v[16:19], v[156:159], v[216:219], v[16:19]
	v_mfma_f32_16x16x32_bf16 v[16:19], v[152:155], v[212:215], v[16:19]
	v_mfma_f32_16x16x32_bf16 v[0:3], v[152:155], v[220:223], v[0:3]
	v_mfma_f32_16x16x32_bf16 v[0:3], v[156:159], v[224:227], v[0:3]
	v_mfma_f32_16x16x32_bf16 v[4:7], v[148:151], v[224:227], v[4:7]
	v_mfma_f32_16x16x32_bf16 v[4:7], v[144:147], v[220:223], v[4:7]
	v_mfma_f32_16x16x32_bf16 v[8:11], v[136:139], v[220:223], v[8:11]
	v_mfma_f32_16x16x32_bf16 v[8:11], v[140:143], v[224:227], v[8:11]
	v_mfma_f32_16x16x32_bf16 v[12:15], v[132:135], v[224:227], v[12:15]
	v_mfma_f32_16x16x32_bf16 v[12:15], v[128:131], v[220:223], v[12:15]
	s_setprio 0
	s_barrier
	s_add_i32 s76, 0, 0x18000
	s_add_i32 s77, 0, 0x1c000
	v_add_u32_e32 v140, s76, v184
	v_add_u32_e32 v156, s77, v184
	ds_read_b128 v[128:131], v140
	ds_read_b128 v[132:135], v140 offset:1024
	ds_read_b128 v[136:139], v140 offset:2048
	ds_read_b128 v[140:143], v140 offset:3072
	ds_read_b128 v[144:147], v156
	ds_read_b128 v[148:151], v156 offset:1024
	ds_read_b128 v[152:155], v156 offset:2048
	ds_read_b128 v[156:159], v156 offset:3072
	s_add_u32 s48, s48, 0x80000
	s_addc_u32 s49, s49, 0
	s_mov_b32 m0, s56
	v_lshl_add_u64 v[234:235], s[48:49], 0, v[160:161]
	ds_read_b128 v[190:193], v187 offset:32768
	ds_read_b128 v[194:197], v187 offset:33792
	ds_read_b128 v[198:201], v187 offset:34816
	ds_read_b128 v[208:211], v187 offset:35840
	ds_read_b128 v[212:215], v187 offset:36864
	ds_read_b128 v[216:219], v187 offset:37888
	ds_read_b128 v[220:223], v187 offset:38912
	ds_read_b128 v[224:227], v187 offset:39936
	global_load_lds_dwordx4 v[234:235], off
	v_lshl_add_u64 v[234:235], s[48:49], 0, v[164:165]
	s_mov_b32 m0, s57
	s_nop 0
	global_load_lds_dwordx4 v[234:235], off
	s_waitcnt vmcnt(8)
	s_waitcnt lgkmcnt(0)
	s_barrier
	s_setprio 1
	s_waitcnt lgkmcnt(0)
	v_mfma_f32_16x16x32_bf16 v[120:123], v[128:131], v[190:193], v[120:123]
	v_mfma_f32_16x16x32_bf16 v[120:123], v[132:135], v[194:197], v[120:123]
	v_mfma_f32_16x16x32_bf16 v[124:127], v[140:143], v[194:197], v[124:127]
	v_mfma_f32_16x16x32_bf16 v[124:127], v[136:139], v[190:193], v[124:127]
	v_mfma_f32_16x16x32_bf16 v[116:119], v[144:147], v[190:193], v[116:119]
	v_mfma_f32_16x16x32_bf16 v[116:119], v[148:151], v[194:197], v[116:119]
	v_mfma_f32_16x16x32_bf16 v[112:115], v[156:159], v[194:197], v[112:115]
	v_mfma_f32_16x16x32_bf16 v[112:115], v[152:155], v[190:193], v[112:115]
	v_mfma_f32_16x16x32_bf16 v[96:99], v[152:155], v[198:201], v[96:99]
	v_mfma_f32_16x16x32_bf16 v[96:99], v[156:159], v[208:211], v[96:99]
	v_mfma_f32_16x16x32_bf16 v[100:103], v[148:151], v[208:211], v[100:103]
	v_mfma_f32_16x16x32_bf16 v[100:103], v[144:147], v[198:201], v[100:103]
	v_mfma_f32_16x16x32_bf16 v[104:107], v[136:139], v[198:201], v[104:107]
	v_mfma_f32_16x16x32_bf16 v[104:107], v[140:143], v[208:211], v[104:107]
	v_mfma_f32_16x16x32_bf16 v[108:111], v[132:135], v[208:211], v[108:111]
	v_mfma_f32_16x16x32_bf16 v[108:111], v[128:131], v[198:201], v[108:111]
	s_setprio 0
	s_setprio 1
	v_mfma_f32_16x16x32_bf16 v[92:95], v[128:131], v[212:215], v[92:95]
	v_mfma_f32_16x16x32_bf16 v[92:95], v[132:135], v[216:219], v[92:95]
	v_mfma_f32_16x16x32_bf16 v[88:91], v[140:143], v[216:219], v[88:91]
	v_mfma_f32_16x16x32_bf16 v[88:91], v[136:139], v[212:215], v[88:91]
	v_mfma_f32_16x16x32_bf16 v[84:87], v[144:147], v[212:215], v[84:87]
	v_mfma_f32_16x16x32_bf16 v[84:87], v[148:151], v[216:219], v[84:87]
	v_mfma_f32_16x16x32_bf16 v[80:83], v[156:159], v[216:219], v[80:83]
	v_mfma_f32_16x16x32_bf16 v[80:83], v[152:155], v[212:215], v[80:83]
	v_mfma_f32_16x16x32_bf16 v[64:67], v[152:155], v[220:223], v[64:67]
	v_mfma_f32_16x16x32_bf16 v[64:67], v[156:159], v[224:227], v[64:67]
	v_mfma_f32_16x16x32_bf16 v[68:71], v[148:151], v[224:227], v[68:71]
	v_mfma_f32_16x16x32_bf16 v[68:71], v[144:147], v[220:223], v[68:71]
	v_mfma_f32_16x16x32_bf16 v[72:75], v[136:139], v[220:223], v[72:75]
	v_mfma_f32_16x16x32_bf16 v[72:75], v[140:143], v[224:227], v[72:75]
	v_mfma_f32_16x16x32_bf16 v[76:79], v[132:135], v[224:227], v[76:79]
	v_mfma_f32_16x16x32_bf16 v[76:79], v[128:131], v[220:223], v[76:79]
	s_setprio 0
	s_barrier
; #define PG8_STAGE(bufoff, gbase, voff) do { _Pragma("unroll") for (int _i = 0; _i < 2; ++_i) \
;         __builtin_amdgcn_global_load_lds((const unsigned*)((const char*)(gbase) + (voff)[_i]), (LAS unsigned*)(lds + (bufoff) + ldsw + _i * 8192), 16, 0, 0); } while (0)
; #define PG8_LDA(dst, b, h) do { _Pragma("unroll") for (int m = 0; m < 4; ++m) _Pragma("unroll") for (int k = 0; k < 2; ++k) dst[m][k] = *(const LAS bf16x8*)(lds + PG8_SA(b, h) + aoff + m * 2048 + k * 1024); } while (0)
; #define PG8_MMA(ai, bj, At, Bt) do { __builtin_amdgcn_s_setprio(1); _Pragma("unroll") for (int m = 0; m < 4; ++m) _Pragma("unroll") for (int n = 0; n < 2; ++n) _Pragma("unroll") for (int k = 0; k < 2; ++k) \
;         acc[ai][bj][m][n] = __builtin_amdgcn_mfma_f32_16x16x32_bf16(Bt[n][k], At[m][k], acc[ai][bj][m][n], 0, 0, 0); __builtin_amdgcn_s_setprio(0); } while (0)
; #define PG8_WAIT_V(n) asm volatile("s_waitcnt vmcnt(" #n ")" ::: "memory")
; #define PG8_WAIT_L(n) asm volatile("s_waitcnt lgkmcnt(" #n ")" ::: "memory")
; #define PG8_BAR __builtin_amdgcn_s_barrier()
; #define PG8_SCHED __builtin_amdgcn_sched_barrier(0)
; template <class Epi>
; __device__ __forceinline__ void gemm_phase(LAS unsigned char* lds, const Gemm g, const StaticOrder& S, const Epi& E) {
;     ...
;             PG8_LDA(At, 1, 1); PG8_STAGE(PG8_SB(1, 0), b3, voffB); PG8_STAGE(PG8_SB(1, 1), b3 + hstepB, voffB); PG8_STAGE(PG8_SA(1, 0), a3, voffA);
;             PG8_WAIT_V(8); PG8_WAIT_L(0); PG8_BAR; PG8_MMA(1, 0, At, B0); PG8_MMA(1, 1, At, B1); PG8_BAR; PG8_SCHED;
;         }
	s_add_i32 s48, s76, s54
	v_lshl_add_u64 v[182:183], v[182:183], 0, s[16:17]
	s_mov_b32 m0, s48
	ds_read_b128 v[190:193], v187 offset:49152
	ds_read_b128 v[194:197], v187 offset:50176
	ds_read_b128 v[198:201], v187 offset:51200
	ds_read_b128 v[208:211], v187 offset:52224
	ds_read_b128 v[212:215], v187 offset:53248
	ds_read_b128 v[216:219], v187 offset:54272
	ds_read_b128 v[220:223], v187 offset:55296
	ds_read_b128 v[224:227], v187 offset:56320
	global_load_lds_dwordx4 v[182:183], off
	s_add_i32 m0, s48, 0x2000
	s_add_u32 s46, s46, 0x80080
	v_lshl_add_u64 v[182:183], v[202:203], 0, s[16:17]
	s_addc_u32 s47, s47, 0
	s_add_i32 s48, s77, s54
	global_load_lds_dwordx4 v[182:183], off
	v_lshl_add_u64 v[182:183], s[46:47], 0, v[162:163]
	s_mov_b32 m0, s48
	s_nop 0
	global_load_lds_dwordx4 v[182:183], off
	v_lshl_add_u64 v[182:183], s[46:47], 0, v[166:167]
	s_add_i32 m0, s48, 0x2000
	s_nop 0
	global_load_lds_dwordx4 v[182:183], off
	v_lshl_add_u64 v[182:183], v[230:231], 0, s[16:17]
	s_mov_b32 m0, s60
	s_nop 0
	global_load_lds_dwordx4 v[182:183], off
	v_lshl_add_u64 v[182:183], v[232:233], 0, s[16:17]
	s_mov_b32 m0, s61
	s_nop 0
	global_load_lds_dwordx4 v[182:183], off
	s_waitcnt vmcnt(8)
	s_waitcnt lgkmcnt(0)
	s_barrier
	s_setprio 1
	s_waitcnt lgkmcnt(0)
	v_mfma_f32_16x16x32_bf16 v[60:63], v[128:131], v[190:193], v[60:63]
	v_mfma_f32_16x16x32_bf16 v[60:63], v[132:135], v[194:197], v[60:63]
	v_mfma_f32_16x16x32_bf16 v[56:59], v[140:143], v[194:197], v[56:59]
	v_mfma_f32_16x16x32_bf16 v[56:59], v[136:139], v[190:193], v[56:59]
	v_mfma_f32_16x16x32_bf16 v[52:55], v[144:147], v[190:193], v[52:55]
	v_mfma_f32_16x16x32_bf16 v[52:55], v[148:151], v[194:197], v[52:55]
	v_mfma_f32_16x16x32_bf16 v[48:51], v[156:159], v[194:197], v[48:51]
	v_mfma_f32_16x16x32_bf16 v[48:51], v[152:155], v[190:193], v[48:51]
	v_mfma_f32_16x16x32_bf16 v[32:35], v[152:155], v[198:201], v[32:35]
	v_mfma_f32_16x16x32_bf16 v[32:35], v[156:159], v[208:211], v[32:35]
	v_mfma_f32_16x16x32_bf16 v[36:39], v[148:151], v[208:211], v[36:39]
	v_mfma_f32_16x16x32_bf16 v[36:39], v[144:147], v[198:201], v[36:39]
	v_mfma_f32_16x16x32_bf16 v[40:43], v[136:139], v[198:201], v[40:43]
	v_mfma_f32_16x16x32_bf16 v[40:43], v[140:143], v[208:211], v[40:43]
	v_mfma_f32_16x16x32_bf16 v[44:47], v[132:135], v[208:211], v[44:47]
	v_mfma_f32_16x16x32_bf16 v[44:47], v[128:131], v[198:201], v[44:47]
	s_setprio 0
	s_setprio 1
	v_mfma_f32_16x16x32_bf16 v[28:31], v[128:131], v[212:215], v[28:31]
	v_mfma_f32_16x16x32_bf16 v[28:31], v[132:135], v[216:219], v[28:31]
	v_mfma_f32_16x16x32_bf16 v[24:27], v[140:143], v[216:219], v[24:27]
	v_mfma_f32_16x16x32_bf16 v[24:27], v[136:139], v[212:215], v[24:27]
	v_mfma_f32_16x16x32_bf16 v[20:23], v[144:147], v[212:215], v[20:23]
	v_mfma_f32_16x16x32_bf16 v[20:23], v[148:151], v[216:219], v[20:23]
	v_mfma_f32_16x16x32_bf16 v[16:19], v[156:159], v[216:219], v[16:19]
	v_mfma_f32_16x16x32_bf16 v[16:19], v[152:155], v[212:215], v[16:19]
	v_mfma_f32_16x16x32_bf16 v[0:3], v[152:155], v[220:223], v[0:3]
	v_mfma_f32_16x16x32_bf16 v[0:3], v[156:159], v[224:227], v[0:3]
	v_mfma_f32_16x16x32_bf16 v[4:7], v[148:151], v[224:227], v[4:7]
	v_mfma_f32_16x16x32_bf16 v[4:7], v[144:147], v[220:223], v[4:7]
	v_mfma_f32_16x16x32_bf16 v[8:11], v[136:139], v[220:223], v[8:11]
	v_mfma_f32_16x16x32_bf16 v[8:11], v[140:143], v[224:227], v[8:11]
	v_mfma_f32_16x16x32_bf16 v[12:15], v[132:135], v[224:227], v[12:15]
	v_mfma_f32_16x16x32_bf16 v[12:15], v[128:131], v[220:223], v[12:15]
	s_add_u32 s12, s12, 0x100
	s_addc_u32 s13, s13, 0
	s_add_u32 s71, s71, 0x100
	s_addc_u32 s72, s72, 0
	s_cmp_ge_i32 s73, s59
	s_mov_b32 s46, s73
	s_setprio 0
	s_barrier
	s_cbranch_scc0 .LBB0_1046

; #define PG8_STAGE(bufoff, gbase, voff) do { _Pragma("unroll") for (int _i = 0; _i < 2; ++_i) \
;         __builtin_amdgcn_global_load_lds((const unsigned*)((const char*)(gbase) + (voff)[_i]), (LAS unsigned*)(lds + (bufoff) + ldsw + _i * 8192), 16, 0, 0); } while (0)
; #define PG8_LDA(dst, b, h) do { _Pragma("unroll") for (int m = 0; m < 4; ++m) _Pragma("unroll") for (int k = 0; k < 2; ++k) dst[m][k] = *(const LAS bf16x8*)(lds + PG8_SA(b, h) + aoff + m * 2048 + k * 1024); } while (0)
; #define PG8_LDB(dst, b, h) do { _Pragma("unroll") for (int n = 0; n < 2; ++n) _Pragma("unroll") for (int k = 0; k < 2; ++k) dst[n][k] = *(const LAS bf16x8*)(lds + PG8_SB(b, h) + boff + n * 2048 + k * 1024); } while (0)
; #define PG8_MMA(ai, bj, At, Bt) do { __builtin_amdgcn_s_setprio(1); _Pragma("unroll") for (int m = 0; m < 4; ++m) _Pragma("unroll") for (int n = 0; n < 2; ++n) _Pragma("unroll") for (int k = 0; k < 2; ++k) \
;         acc[ai][bj][m][n] = __builtin_amdgcn_mfma_f32_16x16x32_bf16(Bt[n][k], At[m][k], acc[ai][bj][m][n], 0, 0, 0); __builtin_amdgcn_s_setprio(0); } while (0)
; #define PG8_WAIT_V(n) asm volatile("s_waitcnt vmcnt(" #n ")" ::: "memory")
; #define PG8_WAIT_L(n) asm volatile("s_waitcnt lgkmcnt(" #n ")" ::: "memory")
; #define PG8_BAR __builtin_amdgcn_s_barrier()
; #define PG8_SCHED __builtin_amdgcn_sched_barrier(0)
; template <class Epi>
; __device__ __forceinline__ void gemm_phase(LAS unsigned char* lds, const Gemm g, const StaticOrder& S, const Epi& E) {
;     ...
;         for (int t = 0; t < nt; t += 2) {
;             const bool last = (t == nt - 2);
;             const char* a1 = cA + (size_t)(t + 1) * kstep;
;             const char* a2 = last ? nA : cA + (size_t)(t + 2) * kstep; const char* b2 = last ? nB : cB + (size_t)(t + 2) * kstep;
;             const char* a3 = a2 + kstep; const char* b3 = b2 + kstep;
;             PG8_LDB(B0, 0, 0); PG8_LDB(B1, 0, 1); PG8_SCHED; PG8_LDA(At, 0, 0); PG8_STAGE(PG8_SA(1, 1), a1 + hstepA, voffA);
;             PG8_WAIT_V(8); PG8_WAIT_L(0); PG8_BAR; PG8_MMA(0, 0, At, B0); PG8_MMA(0, 1, At, B1); PG8_BAR; PG8_SCHED;
;             PG8_LDA(At, 0, 1); PG8_STAGE(PG8_SB(0, 0), b2, voffB); PG8_STAGE(PG8_SB(0, 1), b2 + hstepB, voffB); PG8_STAGE(PG8_SA(0, 0), a2, voffA);
.LBB0_1131:
	ds_read_b128 v[164:167], v182
	ds_read_b128 v[168:171], v182 offset:1024
	ds_read_b128 v[172:175], v182 offset:2048
	ds_read_b128 v[176:179], v182 offset:3072
	ds_read_b128 v[186:189], v183
	ds_read_b128 v[190:193], v183 offset:1024
	ds_read_b128 v[194:197], v183 offset:2048
	ds_read_b128 v[198:201], v183 offset:3072
	s_add_i32 s22, s12, 2
	s_add_u32 s13, s10, 0xfff80080
	s_addc_u32 s14, s11, -1
	s_cmp_eq_u32 s58, s12
	s_cselect_b32 s12, s19, s20
	s_cselect_b32 s15, s16, s14
	s_cselect_b32 s14, s17, s13
	s_cselect_b32 s13, s18, s21
	v_lshl_add_u64 v[202:203], s[10:11], 0, v[140:141]
	s_add_i32 m0, s33, 0xc000
	ds_read_b128 v[208:211], v184
	ds_read_b128 v[212:215], v184 offset:1024
	ds_read_b128 v[216:219], v184 offset:2048
	ds_read_b128 v[220:223], v184 offset:3072
	ds_read_b128 v[224:227], v184 offset:4096
	ds_read_b128 v[230:233], v184 offset:5120
	ds_read_b128 v[234:237], v184 offset:6144
	ds_read_b128 v[238:241], v184 offset:7168
	global_load_lds_dwordx4 v[202:203], off
	v_lshl_add_u64 v[202:203], s[10:11], 0, v[142:143]
	s_add_i32 m0, s33, 0xe000
	s_nop 0
	global_load_lds_dwordx4 v[202:203], off
	s_waitcnt vmcnt(8)
	s_waitcnt lgkmcnt(0)
	s_barrier
	s_setprio 1
	s_waitcnt lgkmcnt(0)
	v_mfma_f32_16x16x32_bf16 v[120:123], v[164:167], v[208:211], v[120:123]
	v_mfma_f32_16x16x32_bf16 v[120:123], v[168:171], v[212:215], v[120:123]
	v_mfma_f32_16x16x32_bf16 v[116:119], v[176:179], v[212:215], v[116:119]
	v_mfma_f32_16x16x32_bf16 v[116:119], v[172:175], v[208:211], v[116:119]
	v_mfma_f32_16x16x32_bf16 v[124:127], v[186:189], v[208:211], v[124:127]
	v_mfma_f32_16x16x32_bf16 v[124:127], v[190:193], v[212:215], v[124:127]
	v_mfma_f32_16x16x32_bf16 v[112:115], v[198:201], v[212:215], v[112:115]
	v_mfma_f32_16x16x32_bf16 v[112:115], v[194:197], v[208:211], v[112:115]
	v_mfma_f32_16x16x32_bf16 v[96:99], v[194:197], v[216:219], v[96:99]
	v_mfma_f32_16x16x32_bf16 v[96:99], v[198:201], v[220:223], v[96:99]
	v_mfma_f32_16x16x32_bf16 v[104:107], v[190:193], v[220:223], v[104:107]
	v_mfma_f32_16x16x32_bf16 v[104:107], v[186:189], v[216:219], v[104:107]
	v_mfma_f32_16x16x32_bf16 v[100:103], v[172:175], v[216:219], v[100:103]
	v_mfma_f32_16x16x32_bf16 v[100:103], v[176:179], v[220:223], v[100:103]
	v_mfma_f32_16x16x32_bf16 v[108:111], v[168:171], v[220:223], v[108:111]
	v_mfma_f32_16x16x32_bf16 v[108:111], v[164:167], v[216:219], v[108:111]
	s_setprio 0
	s_setprio 1
	v_mfma_f32_16x16x32_bf16 v[92:95], v[164:167], v[224:227], v[92:95]
	v_mfma_f32_16x16x32_bf16 v[92:95], v[168:171], v[230:233], v[92:95]
	v_mfma_f32_16x16x32_bf16 v[84:87], v[176:179], v[230:233], v[84:87]
	v_mfma_f32_16x16x32_bf16 v[84:87], v[172:175], v[224:227], v[84:87]
	v_mfma_f32_16x16x32_bf16 v[88:91], v[186:189], v[224:227], v[88:91]
	v_mfma_f32_16x16x32_bf16 v[88:91], v[190:193], v[230:233], v[88:91]
	v_mfma_f32_16x16x32_bf16 v[80:83], v[198:201], v[230:233], v[80:83]
	v_mfma_f32_16x16x32_bf16 v[80:83], v[194:197], v[224:227], v[80:83]
	v_mfma_f32_16x16x32_bf16 v[64:67], v[194:197], v[234:237], v[64:67]
	v_mfma_f32_16x16x32_bf16 v[64:67], v[198:201], v[238:241], v[64:67]
	v_mfma_f32_16x16x32_bf16 v[72:75], v[190:193], v[238:241], v[72:75]
	v_mfma_f32_16x16x32_bf16 v[72:75], v[186:189], v[234:237], v[72:75]
	v_mfma_f32_16x16x32_bf16 v[68:71], v[172:175], v[234:237], v[68:71]
	v_mfma_f32_16x16x32_bf16 v[68:71], v[176:179], v[238:241], v[68:71]
	v_mfma_f32_16x16x32_bf16 v[76:79], v[168:171], v[238:241], v[76:79]
	v_mfma_f32_16x16x32_bf16 v[76:79], v[164:167], v[234:237], v[76:79]
	s_setprio 0
	s_barrier
	s_add_i32 s23, s62, s37
	v_lshl_add_u64 v[202:203], s[12:13], 0, v[132:133]
	s_mov_b32 m0, s23
	ds_read_b128 v[208:211], v184 offset:16384
	ds_read_b128 v[212:215], v184 offset:17408
	ds_read_b128 v[216:219], v184 offset:18432
	ds_read_b128 v[220:223], v184 offset:19456
	ds_read_b128 v[224:227], v184 offset:20480
	ds_read_b128 v[230:233], v184 offset:21504
	ds_read_b128 v[234:237], v184 offset:22528
	ds_read_b128 v[238:241], v184 offset:23552
	global_load_lds_dwordx4 v[202:203], off
	s_add_i32 m0, s23, 0x2000
	s_add_u32 s50, s12, 0x80000
	v_lshl_add_u64 v[242:243], s[12:13], 0, v[128:129]
	s_addc_u32 s51, s13, 0
	s_add_i32 s23, s63, s37
	global_load_lds_dwordx4 v[242:243], off
	v_lshl_add_u64 v[244:245], s[50:51], 0, v[132:133]
	s_mov_b32 m0, s23
	v_lshl_add_u64 v[246:247], s[14:15], 0, v[130:131]
	global_load_lds_dwordx4 v[244:245], off
	v_lshl_add_u64 v[244:245], s[50:51], 0, v[128:129]
	s_add_i32 m0, s23, 0x2000
	s_nop 0
	global_load_lds_dwordx4 v[244:245], off
	v_lshl_add_u64 v[244:245], s[14:15], 0, v[134:135]
	s_mov_b32 m0, s33
	s_nop 0
	global_load_lds_dwordx4 v[244:245], off
	s_mov_b32 m0, s52
	s_nop 0
	global_load_lds_dwordx4 v[246:247], off
	s_waitcnt vmcnt(8)
	s_waitcnt lgkmcnt(0)
	s_barrier
; #define PG8_STAGE(bufoff, gbase, voff) do { _Pragma("unroll") for (int _i = 0; _i < 2; ++_i) \
;         __builtin_amdgcn_global_load_lds((const unsigned*)((const char*)(gbase) + (voff)[_i]), (LAS unsigned*)(lds + (bufoff) + ldsw + _i * 8192), 16, 0, 0); } while (0)
; #define PG8_LDA(dst, b, h) do { _Pragma("unroll") for (int m = 0; m < 4; ++m) _Pragma("unroll") for (int k = 0; k < 2; ++k) dst[m][k] = *(const LAS bf16x8*)(lds + PG8_SA(b, h) + aoff + m * 2048 + k * 1024); } while (0)
; #define PG8_LDB(dst, b, h) do { _Pragma("unroll") for (int n = 0; n < 2; ++n) _Pragma("unroll") for (int k = 0; k < 2; ++k) dst[n][k] = *(const LAS bf16x8*)(lds + PG8_SB(b, h) + boff + n * 2048 + k * 1024); } while (0)
; #define PG8_MMA(ai, bj, At, Bt) do { __builtin_amdgcn_s_setprio(1); _Pragma("unroll") for (int m = 0; m < 4; ++m) _Pragma("unroll") for (int n = 0; n < 2; ++n) _Pragma("unroll") for (int k = 0; k < 2; ++k) \
;         acc[ai][bj][m][n] = __builtin_amdgcn_mfma_f32_16x16x32_bf16(Bt[n][k], At[m][k], acc[ai][bj][m][n], 0, 0, 0); __builtin_amdgcn_s_setprio(0); } while (0)
; #define PG8_WAIT_V(n) asm volatile("s_waitcnt vmcnt(" #n ")" ::: "memory")
; #define PG8_WAIT_L(n) asm volatile("s_waitcnt lgkmcnt(" #n ")" ::: "memory")
; #define PG8_BAR __builtin_amdgcn_s_barrier()
; #define PG8_SCHED __builtin_amdgcn_sched_barrier(0)
; template <class Epi>
; __device__ __forceinline__ void gemm_phase(LAS unsigned char* lds, const Gemm g, const StaticOrder& S, const Epi& E) {
;     ...
;             PG8_WAIT_V(8); PG8_WAIT_L(0); PG8_BAR; PG8_MMA(1, 0, At, B0); PG8_MMA(1, 1, At, B1); PG8_BAR; PG8_SCHED;
;             PG8_LDB(B0, 1, 0); PG8_LDB(B1, 1, 1); PG8_SCHED; PG8_LDA(At, 1, 0); PG8_STAGE(PG8_SA(0, 1), a2 + hstepA, voffA);
;             PG8_WAIT_V(8); PG8_WAIT_L(0); PG8_BAR; PG8_MMA(0, 0, At, B0); PG8_MMA(0, 1, At, B1); PG8_BAR; PG8_SCHED;
	s_setprio 1
	s_waitcnt lgkmcnt(0)
	v_mfma_f32_16x16x32_bf16 v[60:63], v[164:167], v[208:211], v[60:63]
	v_mfma_f32_16x16x32_bf16 v[60:63], v[168:171], v[212:215], v[60:63]
	v_mfma_f32_16x16x32_bf16 v[52:55], v[176:179], v[212:215], v[52:55]
	v_mfma_f32_16x16x32_bf16 v[52:55], v[172:175], v[208:211], v[52:55]
	v_mfma_f32_16x16x32_bf16 v[56:59], v[186:189], v[208:211], v[56:59]
	v_mfma_f32_16x16x32_bf16 v[56:59], v[190:193], v[212:215], v[56:59]
	v_mfma_f32_16x16x32_bf16 v[48:51], v[198:201], v[212:215], v[48:51]
	v_mfma_f32_16x16x32_bf16 v[48:51], v[194:197], v[208:211], v[48:51]
	v_mfma_f32_16x16x32_bf16 v[32:35], v[194:197], v[216:219], v[32:35]
	v_mfma_f32_16x16x32_bf16 v[32:35], v[198:201], v[220:223], v[32:35]
	v_mfma_f32_16x16x32_bf16 v[40:43], v[190:193], v[220:223], v[40:43]
	v_mfma_f32_16x16x32_bf16 v[40:43], v[186:189], v[216:219], v[40:43]
	v_mfma_f32_16x16x32_bf16 v[36:39], v[172:175], v[216:219], v[36:39]
	v_mfma_f32_16x16x32_bf16 v[36:39], v[176:179], v[220:223], v[36:39]
	v_mfma_f32_16x16x32_bf16 v[44:47], v[168:171], v[220:223], v[44:47]
	v_mfma_f32_16x16x32_bf16 v[44:47], v[164:167], v[216:219], v[44:47]
	s_setprio 0
	s_setprio 1
	v_mfma_f32_16x16x32_bf16 v[28:31], v[164:167], v[224:227], v[28:31]
	v_mfma_f32_16x16x32_bf16 v[28:31], v[168:171], v[230:233], v[28:31]
	v_mfma_f32_16x16x32_bf16 v[20:23], v[176:179], v[230:233], v[20:23]
	v_mfma_f32_16x16x32_bf16 v[20:23], v[172:175], v[224:227], v[20:23]
	v_mfma_f32_16x16x32_bf16 v[24:27], v[186:189], v[224:227], v[24:27]
	v_mfma_f32_16x16x32_bf16 v[24:27], v[190:193], v[230:233], v[24:27]
	v_mfma_f32_16x16x32_bf16 v[16:19], v[198:201], v[230:233], v[16:19]
	v_mfma_f32_16x16x32_bf16 v[16:19], v[194:197], v[224:227], v[16:19]
	v_mfma_f32_16x16x32_bf16 v[0:3], v[194:197], v[234:237], v[0:3]
	v_mfma_f32_16x16x32_bf16 v[0:3], v[198:201], v[238:241], v[0:3]
	v_mfma_f32_16x16x32_bf16 v[8:11], v[190:193], v[238:241], v[8:11]
	v_mfma_f32_16x16x32_bf16 v[8:11], v[186:189], v[234:237], v[8:11]
	v_mfma_f32_16x16x32_bf16 v[4:7], v[172:175], v[234:237], v[4:7]
	v_mfma_f32_16x16x32_bf16 v[4:7], v[176:179], v[238:241], v[4:7]
	v_mfma_f32_16x16x32_bf16 v[12:15], v[168:171], v[238:241], v[12:15]
	v_mfma_f32_16x16x32_bf16 v[12:15], v[164:167], v[234:237], v[12:15]
	s_setprio 0
	s_barrier
	s_add_i32 s23, 0, 0x18000
	s_add_i32 s25, 0, 0x1c000
	v_add_u32_e32 v176, s23, v180
	v_add_u32_e32 v185, s25, v180
	ds_read_b128 v[164:167], v176
	ds_read_b128 v[168:171], v176 offset:1024
	ds_read_b128 v[172:175], v176 offset:2048
	ds_read_b128 v[176:179], v176 offset:3072
	ds_read_b128 v[186:189], v185
	ds_read_b128 v[190:193], v185 offset:1024
	ds_read_b128 v[194:197], v185 offset:2048
	ds_read_b128 v[198:201], v185 offset:3072
	s_add_u32 s14, s14, 0x80000
	s_addc_u32 s15, s15, 0
	s_mov_b32 m0, s53
	v_lshl_add_u64 v[248:249], s[14:15], 0, v[134:135]
	ds_read_b128 v[208:211], v184 offset:32768
	ds_read_b128 v[212:215], v184 offset:33792
	ds_read_b128 v[216:219], v184 offset:34816
	ds_read_b128 v[220:223], v184 offset:35840
	ds_read_b128 v[224:227], v184 offset:36864
	ds_read_b128 v[230:233], v184 offset:37888
	ds_read_b128 v[234:237], v184 offset:38912
	ds_read_b128 v[238:241], v184 offset:39936
	global_load_lds_dwordx4 v[248:249], off
	v_lshl_add_u64 v[248:249], s[14:15], 0, v[130:131]
	s_mov_b32 m0, s54
	s_nop 0
	global_load_lds_dwordx4 v[248:249], off
	s_waitcnt vmcnt(8)
	s_waitcnt lgkmcnt(0)
	s_barrier
	s_setprio 1
	s_waitcnt lgkmcnt(0)
	v_mfma_f32_16x16x32_bf16 v[120:123], v[164:167], v[208:211], v[120:123]
	v_mfma_f32_16x16x32_bf16 v[120:123], v[168:171], v[212:215], v[120:123]
	v_mfma_f32_16x16x32_bf16 v[116:119], v[176:179], v[212:215], v[116:119]
	v_mfma_f32_16x16x32_bf16 v[116:119], v[172:175], v[208:211], v[116:119]
	v_mfma_f32_16x16x32_bf16 v[124:127], v[186:189], v[208:211], v[124:127]
	v_mfma_f32_16x16x32_bf16 v[124:127], v[190:193], v[212:215], v[124:127]
	v_mfma_f32_16x16x32_bf16 v[112:115], v[198:201], v[212:215], v[112:115]
	v_mfma_f32_16x16x32_bf16 v[112:115], v[194:197], v[208:211], v[112:115]
	v_mfma_f32_16x16x32_bf16 v[96:99], v[194:197], v[216:219], v[96:99]
	v_mfma_f32_16x16x32_bf16 v[96:99], v[198:201], v[220:223], v[96:99]
	v_mfma_f32_16x16x32_bf16 v[104:107], v[190:193], v[220:223], v[104:107]
	v_mfma_f32_16x16x32_bf16 v[104:107], v[186:189], v[216:219], v[104:107]
	v_mfma_f32_16x16x32_bf16 v[100:103], v[172:175], v[216:219], v[100:103]
	v_mfma_f32_16x16x32_bf16 v[100:103], v[176:179], v[220:223], v[100:103]
	v_mfma_f32_16x16x32_bf16 v[108:111], v[168:171], v[220:223], v[108:111]
	v_mfma_f32_16x16x32_bf16 v[108:111], v[164:167], v[216:219], v[108:111]
	s_setprio 0
	s_setprio 1
	v_mfma_f32_16x16x32_bf16 v[92:95], v[164:167], v[224:227], v[92:95]
	v_mfma_f32_16x16x32_bf16 v[92:95], v[168:171], v[230:233], v[92:95]
	v_mfma_f32_16x16x32_bf16 v[84:87], v[176:179], v[230:233], v[84:87]
	v_mfma_f32_16x16x32_bf16 v[84:87], v[172:175], v[224:227], v[84:87]
	v_mfma_f32_16x16x32_bf16 v[88:91], v[186:189], v[224:227], v[88:91]
	v_mfma_f32_16x16x32_bf16 v[88:91], v[190:193], v[230:233], v[88:91]
	v_mfma_f32_16x16x32_bf16 v[80:83], v[198:201], v[230:233], v[80:83]
	v_mfma_f32_16x16x32_bf16 v[80:83], v[194:197], v[224:227], v[80:83]
	v_mfma_f32_16x16x32_bf16 v[64:67], v[194:197], v[234:237], v[64:67]
	v_mfma_f32_16x16x32_bf16 v[64:67], v[198:201], v[238:241], v[64:67]
	v_mfma_f32_16x16x32_bf16 v[72:75], v[190:193], v[238:241], v[72:75]
	v_mfma_f32_16x16x32_bf16 v[72:75], v[186:189], v[234:237], v[72:75]
	v_mfma_f32_16x16x32_bf16 v[68:71], v[172:175], v[234:237], v[68:71]
	v_mfma_f32_16x16x32_bf16 v[68:71], v[176:179], v[238:241], v[68:71]
	v_mfma_f32_16x16x32_bf16 v[76:79], v[168:171], v[238:241], v[76:79]
	v_mfma_f32_16x16x32_bf16 v[76:79], v[164:167], v[234:237], v[76:79]
	s_setprio 0
	s_barrier
; #define PG8_STAGE(bufoff, gbase, voff) do { _Pragma("unroll") for (int _i = 0; _i < 2; ++_i) \
;         __builtin_amdgcn_global_load_lds((const unsigned*)((const char*)(gbase) + (voff)[_i]), (LAS unsigned*)(lds + (bufoff) + ldsw + _i * 8192), 16, 0, 0); } while (0)
; #define PG8_LDA(dst, b, h) do { _Pragma("unroll") for (int m = 0; m < 4; ++m) _Pragma("unroll") for (int k = 0; k < 2; ++k) dst[m][k] = *(const LAS bf16x8*)(lds + PG8_SA(b, h) + aoff + m * 2048 + k * 1024); } while (0)
; #define PG8_MMA(ai, bj, At, Bt) do { __builtin_amdgcn_s_setprio(1); _Pragma("unroll") for (int m = 0; m < 4; ++m) _Pragma("unroll") for (int n = 0; n < 2; ++n) _Pragma("unroll") for (int k = 0; k < 2; ++k) \
;         acc[ai][bj][m][n] = __builtin_amdgcn_mfma_f32_16x16x32_bf16(Bt[n][k], At[m][k], acc[ai][bj][m][n], 0, 0, 0); __builtin_amdgcn_s_setprio(0); } while (0)
; #define PG8_WAIT_V(n) asm volatile("s_waitcnt vmcnt(" #n ")" ::: "memory")
; #define PG8_WAIT_L(n) asm volatile("s_waitcnt lgkmcnt(" #n ")" ::: "memory")
; #define PG8_BAR __builtin_amdgcn_s_barrier()
; #define PG8_SCHED __builtin_amdgcn_sched_barrier(0)
; template <class Epi>
; __device__ __forceinline__ void gemm_phase(LAS unsigned char* lds, const Gemm g, const StaticOrder& S, const Epi& E) {
;     ...
;             PG8_LDA(At, 1, 1); PG8_STAGE(PG8_SB(1, 0), b3, voffB); PG8_STAGE(PG8_SB(1, 1), b3 + hstepB, voffB); PG8_STAGE(PG8_SA(1, 0), a3, voffA);
;             PG8_WAIT_V(8); PG8_WAIT_L(0); PG8_BAR; PG8_MMA(1, 0, At, B0); PG8_MMA(1, 1, At, B1); PG8_BAR; PG8_SCHED;
;         }
	s_add_i32 s14, s23, s37
	v_lshl_add_u64 v[202:203], v[202:203], 0, s[4:5]
	s_mov_b32 m0, s14
	ds_read_b128 v[208:211], v184 offset:49152
	ds_read_b128 v[212:215], v184 offset:50176
	ds_read_b128 v[216:219], v184 offset:51200
	ds_read_b128 v[220:223], v184 offset:52224
	ds_read_b128 v[224:227], v184 offset:53248
	ds_read_b128 v[230:233], v184 offset:54272
	ds_read_b128 v[234:237], v184 offset:55296
	ds_read_b128 v[238:241], v184 offset:56320
	global_load_lds_dwordx4 v[202:203], off
	s_add_i32 m0, s14, 0x2000
	s_add_u32 s12, s12, 0x80080
	v_lshl_add_u64 v[202:203], v[242:243], 0, s[4:5]
	s_addc_u32 s13, s13, 0
	s_add_i32 s14, s25, s37
	global_load_lds_dwordx4 v[202:203], off
	v_lshl_add_u64 v[202:203], s[12:13], 0, v[132:133]
	s_mov_b32 m0, s14
	s_nop 0
	global_load_lds_dwordx4 v[202:203], off
	v_lshl_add_u64 v[202:203], s[12:13], 0, v[128:129]
	s_add_i32 m0, s14, 0x2000
	s_nop 0
	global_load_lds_dwordx4 v[202:203], off
	v_lshl_add_u64 v[202:203], v[244:245], 0, s[4:5]
	s_mov_b32 m0, s56
	s_nop 0
	global_load_lds_dwordx4 v[202:203], off
	v_lshl_add_u64 v[202:203], v[246:247], 0, s[4:5]
	s_mov_b32 m0, s57
	s_nop 0
	global_load_lds_dwordx4 v[202:203], off
	s_waitcnt vmcnt(8)
	s_waitcnt lgkmcnt(0)
	s_barrier
	s_setprio 1
	s_waitcnt lgkmcnt(0)
	v_mfma_f32_16x16x32_bf16 v[60:63], v[164:167], v[208:211], v[60:63]
	v_mfma_f32_16x16x32_bf16 v[60:63], v[168:171], v[212:215], v[60:63]
	v_mfma_f32_16x16x32_bf16 v[52:55], v[176:179], v[212:215], v[52:55]
	v_mfma_f32_16x16x32_bf16 v[52:55], v[172:175], v[208:211], v[52:55]
	v_mfma_f32_16x16x32_bf16 v[56:59], v[186:189], v[208:211], v[56:59]
	v_mfma_f32_16x16x32_bf16 v[56:59], v[190:193], v[212:215], v[56:59]
	v_mfma_f32_16x16x32_bf16 v[48:51], v[198:201], v[212:215], v[48:51]
	v_mfma_f32_16x16x32_bf16 v[48:51], v[194:197], v[208:211], v[48:51]
	v_mfma_f32_16x16x32_bf16 v[32:35], v[194:197], v[216:219], v[32:35]
	v_mfma_f32_16x16x32_bf16 v[32:35], v[198:201], v[220:223], v[32:35]
	v_mfma_f32_16x16x32_bf16 v[40:43], v[190:193], v[220:223], v[40:43]
	v_mfma_f32_16x16x32_bf16 v[40:43], v[186:189], v[216:219], v[40:43]
	v_mfma_f32_16x16x32_bf16 v[36:39], v[172:175], v[216:219], v[36:39]
	v_mfma_f32_16x16x32_bf16 v[36:39], v[176:179], v[220:223], v[36:39]
	v_mfma_f32_16x16x32_bf16 v[44:47], v[168:171], v[220:223], v[44:47]
	v_mfma_f32_16x16x32_bf16 v[44:47], v[164:167], v[216:219], v[44:47]
	s_setprio 0
	s_setprio 1
	v_mfma_f32_16x16x32_bf16 v[28:31], v[164:167], v[224:227], v[28:31]
	v_mfma_f32_16x16x32_bf16 v[28:31], v[168:171], v[230:233], v[28:31]
	v_mfma_f32_16x16x32_bf16 v[20:23], v[176:179], v[230:233], v[20:23]
	v_mfma_f32_16x16x32_bf16 v[20:23], v[172:175], v[224:227], v[20:23]
	v_mfma_f32_16x16x32_bf16 v[24:27], v[186:189], v[224:227], v[24:27]
	v_mfma_f32_16x16x32_bf16 v[24:27], v[190:193], v[230:233], v[24:27]
	v_mfma_f32_16x16x32_bf16 v[16:19], v[198:201], v[230:233], v[16:19]
	v_mfma_f32_16x16x32_bf16 v[16:19], v[194:197], v[224:227], v[16:19]
	v_mfma_f32_16x16x32_bf16 v[0:3], v[194:197], v[234:237], v[0:3]
	v_mfma_f32_16x16x32_bf16 v[0:3], v[198:201], v[238:241], v[0:3]
	v_mfma_f32_16x16x32_bf16 v[8:11], v[190:193], v[238:241], v[8:11]
	v_mfma_f32_16x16x32_bf16 v[8:11], v[186:189], v[234:237], v[8:11]
	v_mfma_f32_16x16x32_bf16 v[4:7], v[172:175], v[234:237], v[4:7]
	v_mfma_f32_16x16x32_bf16 v[4:7], v[176:179], v[238:241], v[4:7]
	v_mfma_f32_16x16x32_bf16 v[12:15], v[168:171], v[238:241], v[12:15]
	v_mfma_f32_16x16x32_bf16 v[12:15], v[164:167], v[234:237], v[12:15]
	s_add_u32 s10, s10, 0x100
	s_addc_u32 s11, s11, 0
	s_add_u32 s20, s20, 0x100
	s_addc_u32 s21, s21, 0
	s_cmp_ge_i32 s22, s55
	s_mov_b32 s12, s22
	s_setprio 0
	s_barrier
	s_cbranch_scc0 .LBB0_1131

; #define PG8_STAGE(bufoff, gbase, voff) do { _Pragma("unroll") for (int _i = 0; _i < 2; ++_i) \
;         __builtin_amdgcn_global_load_lds((const unsigned*)((const char*)(gbase) + (voff)[_i]), (LAS unsigned*)(lds + (bufoff) + ldsw + _i * 8192), 16, 0, 0); } while (0)
; #define PG8_LDA(dst, b, h) do { _Pragma("unroll") for (int m = 0; m < 4; ++m) _Pragma("unroll") for (int k = 0; k < 2; ++k) dst[m][k] = *(const LAS bf16x8*)(lds + PG8_SA(b, h) + aoff + m * 2048 + k * 1024); } while (0)
; #define PG8_LDB(dst, b, h) do { _Pragma("unroll") for (int n = 0; n < 2; ++n) _Pragma("unroll") for (int k = 0; k < 2; ++k) dst[n][k] = *(const LAS bf16x8*)(lds + PG8_SB(b, h) + boff + n * 2048 + k * 1024); } while (0)
; #define PG8_MMA(ai, bj, At, Bt) do { __builtin_amdgcn_s_setprio(1); _Pragma("unroll") for (int m = 0; m < 4; ++m) _Pragma("unroll") for (int n = 0; n < 2; ++n) _Pragma("unroll") for (int k = 0; k < 2; ++k) \
;         acc[ai][bj][m][n] = __builtin_amdgcn_mfma_f32_16x16x32_bf16(Bt[n][k], At[m][k], acc[ai][bj][m][n], 0, 0, 0); __builtin_amdgcn_s_setprio(0); } while (0)
; #define PG8_WAIT_V(n) asm volatile("s_waitcnt vmcnt(" #n ")" ::: "memory")
; #define PG8_WAIT_L(n) asm volatile("s_waitcnt lgkmcnt(" #n ")" ::: "memory")
; #define PG8_BAR __builtin_amdgcn_s_barrier()
; #define PG8_SCHED __builtin_amdgcn_sched_barrier(0)
; template <class Epi>
; __device__ __forceinline__ void gemm_phase(LAS unsigned char* lds, const Gemm g, const StaticOrder& S, const Epi& E) {
;     ...
;         for (int t = 0; t < nt; t += 2) {
;             const bool last = (t == nt - 2);
;             const char* a1 = cA + (size_t)(t + 1) * kstep;
;             const char* a2 = last ? nA : cA + (size_t)(t + 2) * kstep; const char* b2 = last ? nB : cB + (size_t)(t + 2) * kstep;
;             const char* a3 = a2 + kstep; const char* b3 = b2 + kstep;
;             PG8_LDB(B0, 0, 0); PG8_LDB(B1, 0, 1); PG8_SCHED; PG8_LDA(At, 0, 0); PG8_STAGE(PG8_SA(1, 1), a1 + hstepA, voffA);
;             PG8_WAIT_V(8); PG8_WAIT_L(0); PG8_BAR; PG8_MMA(0, 0, At, B0); PG8_MMA(0, 1, At, B1); PG8_BAR; PG8_SCHED;
;             PG8_LDA(At, 0, 1); PG8_STAGE(PG8_SB(0, 0), b2, voffB); PG8_STAGE(PG8_SB(0, 1), b2 + hstepB, voffB); PG8_STAGE(PG8_SA(0, 0), a2, voffA);
.LBB0_1161:
	ds_read_b128 v[152:155], v149
	ds_read_b128 v[156:159], v149 offset:1024
	ds_read_b128 v[160:163], v149 offset:2048
	ds_read_b128 v[164:167], v149 offset:3072
	ds_read_b128 v[168:171], v150
	ds_read_b128 v[172:175], v150 offset:1024
	ds_read_b128 v[176:179], v150 offset:2048
	ds_read_b128 v[180:183], v150 offset:3072
	s_add_i32 s83, s46, 2
	s_add_u32 s47, s44, 0xffff0080
	s_addc_u32 s48, s45, -1
	s_cmp_eq_u32 s65, s46
	s_cselect_b32 s46, s78, s79
	s_cselect_b32 s49, s35, s48
	s_cselect_b32 s48, s37, s47
	s_cselect_b32 s47, s39, s82
	v_lshl_add_u64 v[220:221], s[44:45], 0, v[140:141]
	s_add_i32 m0, s56, 0xc000
	ds_read_b128 v[184:187], v151
	ds_read_b128 v[188:191], v151 offset:1024
	ds_read_b128 v[192:195], v151 offset:2048
	ds_read_b128 v[196:199], v151 offset:3072
	ds_read_b128 v[200:203], v151 offset:4096
	ds_read_b128 v[208:211], v151 offset:5120
	ds_read_b128 v[212:215], v151 offset:6144
	ds_read_b128 v[216:219], v151 offset:7168
	global_load_lds_dwordx4 v[220:221], off
	v_lshl_add_u64 v[220:221], s[44:45], 0, v[142:143]
	s_add_i32 m0, s56, 0xe000
	s_nop 0
	global_load_lds_dwordx4 v[220:221], off
	s_waitcnt vmcnt(8)
	s_waitcnt lgkmcnt(0)
	s_barrier
	s_setprio 1
	s_waitcnt lgkmcnt(0)
	v_mfma_f32_16x16x32_bf16 v[120:123], v[152:155], v[184:187], v[120:123]
	v_mfma_f32_16x16x32_bf16 v[120:123], v[156:159], v[188:191], v[120:123]
	v_mfma_f32_16x16x32_bf16 v[124:127], v[164:167], v[188:191], v[124:127]
	v_mfma_f32_16x16x32_bf16 v[124:127], v[160:163], v[184:187], v[124:127]
	v_mfma_f32_16x16x32_bf16 v[116:119], v[168:171], v[184:187], v[116:119]
	v_mfma_f32_16x16x32_bf16 v[116:119], v[172:175], v[188:191], v[116:119]
	v_mfma_f32_16x16x32_bf16 v[112:115], v[180:183], v[188:191], v[112:115]
	v_mfma_f32_16x16x32_bf16 v[112:115], v[176:179], v[184:187], v[112:115]
	v_mfma_f32_16x16x32_bf16 v[96:99], v[176:179], v[192:195], v[96:99]
	v_mfma_f32_16x16x32_bf16 v[96:99], v[180:183], v[196:199], v[96:99]
	v_mfma_f32_16x16x32_bf16 v[100:103], v[172:175], v[196:199], v[100:103]
	v_mfma_f32_16x16x32_bf16 v[100:103], v[168:171], v[192:195], v[100:103]
	v_mfma_f32_16x16x32_bf16 v[104:107], v[160:163], v[192:195], v[104:107]
	v_mfma_f32_16x16x32_bf16 v[104:107], v[164:167], v[196:199], v[104:107]
	v_mfma_f32_16x16x32_bf16 v[108:111], v[156:159], v[196:199], v[108:111]
	v_mfma_f32_16x16x32_bf16 v[108:111], v[152:155], v[192:195], v[108:111]
	s_setprio 0
	s_setprio 1
	v_mfma_f32_16x16x32_bf16 v[92:95], v[152:155], v[200:203], v[92:95]
	v_mfma_f32_16x16x32_bf16 v[92:95], v[156:159], v[208:211], v[92:95]
	v_mfma_f32_16x16x32_bf16 v[88:91], v[164:167], v[208:211], v[88:91]
	v_mfma_f32_16x16x32_bf16 v[88:91], v[160:163], v[200:203], v[88:91]
	v_mfma_f32_16x16x32_bf16 v[84:87], v[168:171], v[200:203], v[84:87]
	v_mfma_f32_16x16x32_bf16 v[84:87], v[172:175], v[208:211], v[84:87]
	v_mfma_f32_16x16x32_bf16 v[80:83], v[180:183], v[208:211], v[80:83]
	v_mfma_f32_16x16x32_bf16 v[80:83], v[176:179], v[200:203], v[80:83]
	v_mfma_f32_16x16x32_bf16 v[64:67], v[176:179], v[212:215], v[64:67]
	v_mfma_f32_16x16x32_bf16 v[64:67], v[180:183], v[216:219], v[64:67]
	v_mfma_f32_16x16x32_bf16 v[68:71], v[172:175], v[216:219], v[68:71]
	v_mfma_f32_16x16x32_bf16 v[68:71], v[168:171], v[212:215], v[68:71]
	v_mfma_f32_16x16x32_bf16 v[72:75], v[160:163], v[212:215], v[72:75]
	v_mfma_f32_16x16x32_bf16 v[72:75], v[164:167], v[216:219], v[72:75]
	v_mfma_f32_16x16x32_bf16 v[76:79], v[156:159], v[216:219], v[76:79]
	v_mfma_f32_16x16x32_bf16 v[76:79], v[152:155], v[212:215], v[76:79]
	s_setprio 0
	s_barrier
	s_add_i32 s84, s67, s51
	v_lshl_add_u64 v[220:221], s[46:47], 0, v[130:131]
	s_mov_b32 m0, s84
	ds_read_b128 v[184:187], v151 offset:16384
	ds_read_b128 v[188:191], v151 offset:17408
	ds_read_b128 v[192:195], v151 offset:18432
	ds_read_b128 v[196:199], v151 offset:19456
	ds_read_b128 v[200:203], v151 offset:20480
	ds_read_b128 v[208:211], v151 offset:21504
	ds_read_b128 v[212:215], v151 offset:22528
	ds_read_b128 v[216:219], v151 offset:23552
	global_load_lds_dwordx4 v[220:221], off
	s_add_i32 m0, s84, 0x2000
	s_add_u32 s84, s46, 0x10000
	v_lshl_add_u64 v[222:223], s[46:47], 0, v[134:135]
	s_addc_u32 s85, s47, 0
	s_add_i32 s86, s68, s51
	global_load_lds_dwordx4 v[222:223], off
	v_lshl_add_u64 v[224:225], s[84:85], 0, v[130:131]
	s_mov_b32 m0, s86
	v_lshl_add_u64 v[226:227], s[48:49], 0, v[132:133]
	global_load_lds_dwordx4 v[224:225], off
	v_lshl_add_u64 v[224:225], s[84:85], 0, v[134:135]
	s_add_i32 m0, s86, 0x2000
	s_nop 0
	global_load_lds_dwordx4 v[224:225], off
	v_lshl_add_u64 v[224:225], s[48:49], 0, v[128:129]
	s_mov_b32 m0, s56
	s_nop 0
	global_load_lds_dwordx4 v[224:225], off
	s_mov_b32 m0, s57
	s_nop 0
	global_load_lds_dwordx4 v[226:227], off
	s_waitcnt vmcnt(8)
	s_waitcnt lgkmcnt(0)
	s_barrier
; #define PG8_STAGE(bufoff, gbase, voff) do { _Pragma("unroll") for (int _i = 0; _i < 2; ++_i) \
;         __builtin_amdgcn_global_load_lds((const unsigned*)((const char*)(gbase) + (voff)[_i]), (LAS unsigned*)(lds + (bufoff) + ldsw + _i * 8192), 16, 0, 0); } while (0)
; #define PG8_LDA(dst, b, h) do { _Pragma("unroll") for (int m = 0; m < 4; ++m) _Pragma("unroll") for (int k = 0; k < 2; ++k) dst[m][k] = *(const LAS bf16x8*)(lds + PG8_SA(b, h) + aoff + m * 2048 + k * 1024); } while (0)
; #define PG8_LDB(dst, b, h) do { _Pragma("unroll") for (int n = 0; n < 2; ++n) _Pragma("unroll") for (int k = 0; k < 2; ++k) dst[n][k] = *(const LAS bf16x8*)(lds + PG8_SB(b, h) + boff + n * 2048 + k * 1024); } while (0)
; #define PG8_MMA(ai, bj, At, Bt) do { __builtin_amdgcn_s_setprio(1); _Pragma("unroll") for (int m = 0; m < 4; ++m) _Pragma("unroll") for (int n = 0; n < 2; ++n) _Pragma("unroll") for (int k = 0; k < 2; ++k) \
;         acc[ai][bj][m][n] = __builtin_amdgcn_mfma_f32_16x16x32_bf16(Bt[n][k], At[m][k], acc[ai][bj][m][n], 0, 0, 0); __builtin_amdgcn_s_setprio(0); } while (0)
; #define PG8_WAIT_V(n) asm volatile("s_waitcnt vmcnt(" #n ")" ::: "memory")
; #define PG8_WAIT_L(n) asm volatile("s_waitcnt lgkmcnt(" #n ")" ::: "memory")
; #define PG8_BAR __builtin_amdgcn_s_barrier()
; #define PG8_SCHED __builtin_amdgcn_sched_barrier(0)
; template <class Epi>
; __device__ __forceinline__ void gemm_phase(LAS unsigned char* lds, const Gemm g, const StaticOrder& S, const Epi& E) {
;     ...
;             PG8_WAIT_V(8); PG8_WAIT_L(0); PG8_BAR; PG8_MMA(1, 0, At, B0); PG8_MMA(1, 1, At, B1); PG8_BAR; PG8_SCHED;
;             PG8_LDB(B0, 1, 0); PG8_LDB(B1, 1, 1); PG8_SCHED; PG8_LDA(At, 1, 0); PG8_STAGE(PG8_SA(0, 1), a2 + hstepA, voffA);
;             PG8_WAIT_V(8); PG8_WAIT_L(0); PG8_BAR; PG8_MMA(0, 0, At, B0); PG8_MMA(0, 1, At, B1); PG8_BAR; PG8_SCHED;
	s_setprio 1
	s_waitcnt lgkmcnt(0)
	v_mfma_f32_16x16x32_bf16 v[60:63], v[152:155], v[184:187], v[60:63]
	v_mfma_f32_16x16x32_bf16 v[60:63], v[156:159], v[188:191], v[60:63]
	v_mfma_f32_16x16x32_bf16 v[56:59], v[164:167], v[188:191], v[56:59]
	v_mfma_f32_16x16x32_bf16 v[56:59], v[160:163], v[184:187], v[56:59]
	v_mfma_f32_16x16x32_bf16 v[52:55], v[168:171], v[184:187], v[52:55]
	v_mfma_f32_16x16x32_bf16 v[52:55], v[172:175], v[188:191], v[52:55]
	v_mfma_f32_16x16x32_bf16 v[48:51], v[180:183], v[188:191], v[48:51]
	v_mfma_f32_16x16x32_bf16 v[48:51], v[176:179], v[184:187], v[48:51]
	v_mfma_f32_16x16x32_bf16 v[32:35], v[176:179], v[192:195], v[32:35]
	v_mfma_f32_16x16x32_bf16 v[32:35], v[180:183], v[196:199], v[32:35]
	v_mfma_f32_16x16x32_bf16 v[36:39], v[172:175], v[196:199], v[36:39]
	v_mfma_f32_16x16x32_bf16 v[36:39], v[168:171], v[192:195], v[36:39]
	v_mfma_f32_16x16x32_bf16 v[40:43], v[160:163], v[192:195], v[40:43]
	v_mfma_f32_16x16x32_bf16 v[40:43], v[164:167], v[196:199], v[40:43]
	v_mfma_f32_16x16x32_bf16 v[44:47], v[156:159], v[196:199], v[44:47]
	v_mfma_f32_16x16x32_bf16 v[44:47], v[152:155], v[192:195], v[44:47]
	s_setprio 0
	s_setprio 1
	v_mfma_f32_16x16x32_bf16 v[28:31], v[152:155], v[200:203], v[28:31]
	v_mfma_f32_16x16x32_bf16 v[28:31], v[156:159], v[208:211], v[28:31]
	v_mfma_f32_16x16x32_bf16 v[24:27], v[164:167], v[208:211], v[24:27]
	v_mfma_f32_16x16x32_bf16 v[24:27], v[160:163], v[200:203], v[24:27]
	v_mfma_f32_16x16x32_bf16 v[20:23], v[168:171], v[200:203], v[20:23]
	v_mfma_f32_16x16x32_bf16 v[20:23], v[172:175], v[208:211], v[20:23]
	v_mfma_f32_16x16x32_bf16 v[16:19], v[180:183], v[208:211], v[16:19]
	v_mfma_f32_16x16x32_bf16 v[16:19], v[176:179], v[200:203], v[16:19]
	v_mfma_f32_16x16x32_bf16 v[0:3], v[176:179], v[212:215], v[0:3]
	v_mfma_f32_16x16x32_bf16 v[0:3], v[180:183], v[216:219], v[0:3]
	v_mfma_f32_16x16x32_bf16 v[4:7], v[172:175], v[216:219], v[4:7]
	v_mfma_f32_16x16x32_bf16 v[4:7], v[168:171], v[212:215], v[4:7]
	v_mfma_f32_16x16x32_bf16 v[8:11], v[160:163], v[212:215], v[8:11]
	v_mfma_f32_16x16x32_bf16 v[8:11], v[164:167], v[216:219], v[8:11]
	v_mfma_f32_16x16x32_bf16 v[12:15], v[156:159], v[216:219], v[12:15]
	v_mfma_f32_16x16x32_bf16 v[12:15], v[152:155], v[212:215], v[12:15]
	s_setprio 0
	s_barrier
	s_add_i32 s84, 0, 0x18000
	s_add_i32 s85, 0, 0x1c000
	v_add_u32_e32 v164, s84, v148
	v_add_u32_e32 v180, s85, v148
	ds_read_b128 v[152:155], v164
	ds_read_b128 v[156:159], v164 offset:1024
	ds_read_b128 v[160:163], v164 offset:2048
	ds_read_b128 v[164:167], v164 offset:3072
	ds_read_b128 v[168:171], v180
	ds_read_b128 v[172:175], v180 offset:1024
	ds_read_b128 v[176:179], v180 offset:2048
	ds_read_b128 v[180:183], v180 offset:3072
	s_add_u32 s48, s48, 0x10000
	s_addc_u32 s49, s49, 0
	s_mov_b32 m0, s58
	v_lshl_add_u64 v[230:231], s[48:49], 0, v[128:129]
	ds_read_b128 v[184:187], v151 offset:32768
	ds_read_b128 v[188:191], v151 offset:33792
	ds_read_b128 v[192:195], v151 offset:34816
	ds_read_b128 v[196:199], v151 offset:35840
	ds_read_b128 v[200:203], v151 offset:36864
	ds_read_b128 v[208:211], v151 offset:37888
	ds_read_b128 v[212:215], v151 offset:38912
	ds_read_b128 v[216:219], v151 offset:39936
	global_load_lds_dwordx4 v[230:231], off
	v_lshl_add_u64 v[230:231], s[48:49], 0, v[132:133]
	s_mov_b32 m0, s59
	s_nop 0
	global_load_lds_dwordx4 v[230:231], off
	s_waitcnt vmcnt(8)
	s_waitcnt lgkmcnt(0)
	s_barrier
	s_setprio 1
	s_waitcnt lgkmcnt(0)
	v_mfma_f32_16x16x32_bf16 v[120:123], v[152:155], v[184:187], v[120:123]
	v_mfma_f32_16x16x32_bf16 v[120:123], v[156:159], v[188:191], v[120:123]
	v_mfma_f32_16x16x32_bf16 v[124:127], v[164:167], v[188:191], v[124:127]
	v_mfma_f32_16x16x32_bf16 v[124:127], v[160:163], v[184:187], v[124:127]
	v_mfma_f32_16x16x32_bf16 v[116:119], v[168:171], v[184:187], v[116:119]
	v_mfma_f32_16x16x32_bf16 v[116:119], v[172:175], v[188:191], v[116:119]
	v_mfma_f32_16x16x32_bf16 v[112:115], v[180:183], v[188:191], v[112:115]
	v_mfma_f32_16x16x32_bf16 v[112:115], v[176:179], v[184:187], v[112:115]
	v_mfma_f32_16x16x32_bf16 v[96:99], v[176:179], v[192:195], v[96:99]
	v_mfma_f32_16x16x32_bf16 v[96:99], v[180:183], v[196:199], v[96:99]
	v_mfma_f32_16x16x32_bf16 v[100:103], v[172:175], v[196:199], v[100:103]
	v_mfma_f32_16x16x32_bf16 v[100:103], v[168:171], v[192:195], v[100:103]
	v_mfma_f32_16x16x32_bf16 v[104:107], v[160:163], v[192:195], v[104:107]
	v_mfma_f32_16x16x32_bf16 v[104:107], v[164:167], v[196:199], v[104:107]
	v_mfma_f32_16x16x32_bf16 v[108:111], v[156:159], v[196:199], v[108:111]
	v_mfma_f32_16x16x32_bf16 v[108:111], v[152:155], v[192:195], v[108:111]
	s_setprio 0
	s_setprio 1
	v_mfma_f32_16x16x32_bf16 v[92:95], v[152:155], v[200:203], v[92:95]
	v_mfma_f32_16x16x32_bf16 v[92:95], v[156:159], v[208:211], v[92:95]
	v_mfma_f32_16x16x32_bf16 v[88:91], v[164:167], v[208:211], v[88:91]
	v_mfma_f32_16x16x32_bf16 v[88:91], v[160:163], v[200:203], v[88:91]
	v_mfma_f32_16x16x32_bf16 v[84:87], v[168:171], v[200:203], v[84:87]
	v_mfma_f32_16x16x32_bf16 v[84:87], v[172:175], v[208:211], v[84:87]
	v_mfma_f32_16x16x32_bf16 v[80:83], v[180:183], v[208:211], v[80:83]
	v_mfma_f32_16x16x32_bf16 v[80:83], v[176:179], v[200:203], v[80:83]
	v_mfma_f32_16x16x32_bf16 v[64:67], v[176:179], v[212:215], v[64:67]
	v_mfma_f32_16x16x32_bf16 v[64:67], v[180:183], v[216:219], v[64:67]
	v_mfma_f32_16x16x32_bf16 v[68:71], v[172:175], v[216:219], v[68:71]
	v_mfma_f32_16x16x32_bf16 v[68:71], v[168:171], v[212:215], v[68:71]
	v_mfma_f32_16x16x32_bf16 v[72:75], v[160:163], v[212:215], v[72:75]
	v_mfma_f32_16x16x32_bf16 v[72:75], v[164:167], v[216:219], v[72:75]
	v_mfma_f32_16x16x32_bf16 v[76:79], v[156:159], v[216:219], v[76:79]
	v_mfma_f32_16x16x32_bf16 v[76:79], v[152:155], v[212:215], v[76:79]
	s_setprio 0
	s_barrier
; #define PG8_STAGE(bufoff, gbase, voff) do { _Pragma("unroll") for (int _i = 0; _i < 2; ++_i) \
;         __builtin_amdgcn_global_load_lds((const unsigned*)((const char*)(gbase) + (voff)[_i]), (LAS unsigned*)(lds + (bufoff) + ldsw + _i * 8192), 16, 0, 0); } while (0)
; #define PG8_LDA(dst, b, h) do { _Pragma("unroll") for (int m = 0; m < 4; ++m) _Pragma("unroll") for (int k = 0; k < 2; ++k) dst[m][k] = *(const LAS bf16x8*)(lds + PG8_SA(b, h) + aoff + m * 2048 + k * 1024); } while (0)
; #define PG8_MMA(ai, bj, At, Bt) do { __builtin_amdgcn_s_setprio(1); _Pragma("unroll") for (int m = 0; m < 4; ++m) _Pragma("unroll") for (int n = 0; n < 2; ++n) _Pragma("unroll") for (int k = 0; k < 2; ++k) \
;         acc[ai][bj][m][n] = __builtin_amdgcn_mfma_f32_16x16x32_bf16(Bt[n][k], At[m][k], acc[ai][bj][m][n], 0, 0, 0); __builtin_amdgcn_s_setprio(0); } while (0)
; #define PG8_WAIT_V(n) asm volatile("s_waitcnt vmcnt(" #n ")" ::: "memory")
; #define PG8_WAIT_L(n) asm volatile("s_waitcnt lgkmcnt(" #n ")" ::: "memory")
; #define PG8_BAR __builtin_amdgcn_s_barrier()
; #define PG8_SCHED __builtin_amdgcn_sched_barrier(0)
; template <class Epi>
; __device__ __forceinline__ void gemm_phase(LAS unsigned char* lds, const Gemm g, const StaticOrder& S, const Epi& E) {
;     ...
;             PG8_LDA(At, 1, 1); PG8_STAGE(PG8_SB(1, 0), b3, voffB); PG8_STAGE(PG8_SB(1, 1), b3 + hstepB, voffB); PG8_STAGE(PG8_SA(1, 0), a3, voffA);
;             PG8_WAIT_V(8); PG8_WAIT_L(0); PG8_BAR; PG8_MMA(1, 0, At, B0); PG8_MMA(1, 1, At, B1); PG8_BAR; PG8_SCHED;
;         }
	s_add_i32 s48, s84, s51
	v_lshl_add_u64 v[220:221], v[220:221], 0, s[12:13]
	s_mov_b32 m0, s48
	ds_read_b128 v[184:187], v151 offset:49152
	ds_read_b128 v[188:191], v151 offset:50176
	ds_read_b128 v[192:195], v151 offset:51200
	ds_read_b128 v[196:199], v151 offset:52224
	ds_read_b128 v[200:203], v151 offset:53248
	ds_read_b128 v[208:211], v151 offset:54272
	ds_read_b128 v[212:215], v151 offset:55296
	ds_read_b128 v[216:219], v151 offset:56320
	global_load_lds_dwordx4 v[220:221], off
	s_add_i32 m0, s48, 0x2000
	s_add_u32 s46, s46, 0x10080
	v_lshl_add_u64 v[220:221], v[222:223], 0, s[12:13]
	s_addc_u32 s47, s47, 0
	s_add_i32 s48, s85, s51
	global_load_lds_dwordx4 v[220:221], off
	v_lshl_add_u64 v[220:221], s[46:47], 0, v[130:131]
	s_mov_b32 m0, s48
	s_nop 0
	global_load_lds_dwordx4 v[220:221], off
	v_lshl_add_u64 v[220:221], s[46:47], 0, v[134:135]
	s_add_i32 m0, s48, 0x2000
	s_nop 0
	global_load_lds_dwordx4 v[220:221], off
	v_lshl_add_u64 v[220:221], v[224:225], 0, s[12:13]
	s_mov_b32 m0, s63
	s_nop 0
	global_load_lds_dwordx4 v[220:221], off
	v_lshl_add_u64 v[220:221], v[226:227], 0, s[12:13]
	s_mov_b32 m0, s64
	s_nop 0
	global_load_lds_dwordx4 v[220:221], off
	s_waitcnt vmcnt(8)
	s_waitcnt lgkmcnt(0)
	s_barrier
	s_setprio 1
	s_waitcnt lgkmcnt(0)
	v_mfma_f32_16x16x32_bf16 v[60:63], v[152:155], v[184:187], v[60:63]
	v_mfma_f32_16x16x32_bf16 v[60:63], v[156:159], v[188:191], v[60:63]
	v_mfma_f32_16x16x32_bf16 v[56:59], v[164:167], v[188:191], v[56:59]
	v_mfma_f32_16x16x32_bf16 v[56:59], v[160:163], v[184:187], v[56:59]
	v_mfma_f32_16x16x32_bf16 v[52:55], v[168:171], v[184:187], v[52:55]
	v_mfma_f32_16x16x32_bf16 v[52:55], v[172:175], v[188:191], v[52:55]
	v_mfma_f32_16x16x32_bf16 v[48:51], v[180:183], v[188:191], v[48:51]
	v_mfma_f32_16x16x32_bf16 v[48:51], v[176:179], v[184:187], v[48:51]
	v_mfma_f32_16x16x32_bf16 v[32:35], v[176:179], v[192:195], v[32:35]
	v_mfma_f32_16x16x32_bf16 v[32:35], v[180:183], v[196:199], v[32:35]
	v_mfma_f32_16x16x32_bf16 v[36:39], v[172:175], v[196:199], v[36:39]
	v_mfma_f32_16x16x32_bf16 v[36:39], v[168:171], v[192:195], v[36:39]
	v_mfma_f32_16x16x32_bf16 v[40:43], v[160:163], v[192:195], v[40:43]
	v_mfma_f32_16x16x32_bf16 v[40:43], v[164:167], v[196:199], v[40:43]
	v_mfma_f32_16x16x32_bf16 v[44:47], v[156:159], v[196:199], v[44:47]
	v_mfma_f32_16x16x32_bf16 v[44:47], v[152:155], v[192:195], v[44:47]
	s_setprio 0
	s_setprio 1
	v_mfma_f32_16x16x32_bf16 v[28:31], v[152:155], v[200:203], v[28:31]
	v_mfma_f32_16x16x32_bf16 v[28:31], v[156:159], v[208:211], v[28:31]
	v_mfma_f32_16x16x32_bf16 v[24:27], v[164:167], v[208:211], v[24:27]
	v_mfma_f32_16x16x32_bf16 v[24:27], v[160:163], v[200:203], v[24:27]
	v_mfma_f32_16x16x32_bf16 v[20:23], v[168:171], v[200:203], v[20:23]
	v_mfma_f32_16x16x32_bf16 v[20:23], v[172:175], v[208:211], v[20:23]
	v_mfma_f32_16x16x32_bf16 v[16:19], v[180:183], v[208:211], v[16:19]
	v_mfma_f32_16x16x32_bf16 v[16:19], v[176:179], v[200:203], v[16:19]
	v_mfma_f32_16x16x32_bf16 v[0:3], v[176:179], v[212:215], v[0:3]
	v_mfma_f32_16x16x32_bf16 v[0:3], v[180:183], v[216:219], v[0:3]
	v_mfma_f32_16x16x32_bf16 v[4:7], v[172:175], v[216:219], v[4:7]
	v_mfma_f32_16x16x32_bf16 v[4:7], v[168:171], v[212:215], v[4:7]
	v_mfma_f32_16x16x32_bf16 v[8:11], v[160:163], v[212:215], v[8:11]
	v_mfma_f32_16x16x32_bf16 v[8:11], v[164:167], v[216:219], v[8:11]
	v_mfma_f32_16x16x32_bf16 v[12:15], v[156:159], v[216:219], v[12:15]
	v_mfma_f32_16x16x32_bf16 v[12:15], v[152:155], v[212:215], v[12:15]
	s_add_u32 s44, s44, 0x100
	s_addc_u32 s45, s45, 0
	s_add_u32 s79, s79, 0x100
	s_addc_u32 s82, s82, 0
	s_cmp_ge_i32 s83, s61
	s_mov_b32 s46, s83
	s_setprio 0
	s_barrier
	s_cbranch_scc0 .LBB0_1161

; #define PG8_STAGE(bufoff, gbase, voff) do { _Pragma("unroll") for (int _i = 0; _i < 2; ++_i) \
;         __builtin_amdgcn_global_load_lds((const unsigned*)((const char*)(gbase) + (voff)[_i]), (LAS unsigned*)(lds + (bufoff) + ldsw + _i * 8192), 16, 0, 0); } while (0)
; #define PG8_LDA(dst, b, h) do { _Pragma("unroll") for (int m = 0; m < 4; ++m) _Pragma("unroll") for (int k = 0; k < 2; ++k) dst[m][k] = *(const LAS bf16x8*)(lds + PG8_SA(b, h) + aoff + m * 2048 + k * 1024); } while (0)
; #define PG8_LDB(dst, b, h) do { _Pragma("unroll") for (int n = 0; n < 2; ++n) _Pragma("unroll") for (int k = 0; k < 2; ++k) dst[n][k] = *(const LAS bf16x8*)(lds + PG8_SB(b, h) + boff + n * 2048 + k * 1024); } while (0)
; #define PG8_MMA(ai, bj, At, Bt) do { __builtin_amdgcn_s_setprio(1); _Pragma("unroll") for (int m = 0; m < 4; ++m) _Pragma("unroll") for (int n = 0; n < 2; ++n) _Pragma("unroll") for (int k = 0; k < 2; ++k) \
;         acc[ai][bj][m][n] = __builtin_amdgcn_mfma_f32_16x16x32_bf16(Bt[n][k], At[m][k], acc[ai][bj][m][n], 0, 0, 0); __builtin_amdgcn_s_setprio(0); } while (0)
; #define PG8_WAIT_V(n) asm volatile("s_waitcnt vmcnt(" #n ")" ::: "memory")
; #define PG8_WAIT_L(n) asm volatile("s_waitcnt lgkmcnt(" #n ")" ::: "memory")
; #define PG8_BAR __builtin_amdgcn_s_barrier()
; #define PG8_SCHED __builtin_amdgcn_sched_barrier(0)
; template <class Epi>
; __device__ __forceinline__ void gemm_phase(LAS unsigned char* lds, const Gemm g, const StaticOrder& S, const Epi& E) {
;     ...
;         for (int t = 0; t < nt; t += 2) {
;             const bool last = (t == nt - 2);
;             const char* a1 = cA + (size_t)(t + 1) * kstep;
;             const char* a2 = last ? nA : cA + (size_t)(t + 2) * kstep; const char* b2 = last ? nB : cB + (size_t)(t + 2) * kstep;
;             const char* a3 = a2 + kstep; const char* b3 = b2 + kstep;
;             PG8_LDB(B0, 0, 0); PG8_LDB(B1, 0, 1); PG8_SCHED; PG8_LDA(At, 0, 0); PG8_STAGE(PG8_SA(1, 1), a1 + hstepA, voffA);
;             PG8_WAIT_V(8); PG8_WAIT_L(0); PG8_BAR; PG8_MMA(0, 0, At, B0); PG8_MMA(0, 1, At, B1); PG8_BAR; PG8_SCHED;
;             PG8_LDA(At, 0, 1); PG8_STAGE(PG8_SB(0, 0), b2, voffB); PG8_STAGE(PG8_SB(0, 1), b2 + hstepB, voffB); PG8_STAGE(PG8_SA(0, 0), a2, voffA);
.LBB0_1338:
	ds_read_b128 v[128:131], v173
	ds_read_b128 v[132:135], v173 offset:1024
	ds_read_b128 v[136:139], v173 offset:2048
	ds_read_b128 v[140:143], v173 offset:3072
	ds_read_b128 v[144:147], v175
	ds_read_b128 v[148:151], v175 offset:1024
	ds_read_b128 v[176:179], v175 offset:2048
	ds_read_b128 v[184:187], v175 offset:3072
	s_add_i32 s20, s10, 2
	s_add_u32 s11, s8, 0xfff80080
	s_addc_u32 s12, s9, -1
	s_cmp_eq_u32 s56, s10
	s_cselect_b32 s10, s17, s18
	s_cselect_b32 s13, s1, s12
	s_cselect_b32 s12, s15, s11
	s_cselect_b32 s11, s16, s19
	v_lshl_add_u64 v[224:225], s[8:9], 0, v[164:165]
	s_add_i32 m0, s47, 0xc000
	ds_read_b128 v[188:191], v181
	ds_read_b128 v[192:195], v181 offset:1024
	ds_read_b128 v[196:199], v181 offset:2048
	ds_read_b128 v[200:203], v181 offset:3072
	ds_read_b128 v[208:211], v181 offset:4096
	ds_read_b128 v[212:215], v181 offset:5120
	ds_read_b128 v[216:219], v181 offset:6144
	ds_read_b128 v[220:223], v181 offset:7168
	global_load_lds_dwordx4 v[224:225], off
	v_lshl_add_u64 v[224:225], s[8:9], 0, v[166:167]
	s_add_i32 m0, s47, 0xe000
	s_nop 0
	global_load_lds_dwordx4 v[224:225], off
	s_waitcnt vmcnt(8)
	s_waitcnt lgkmcnt(0)
	s_barrier
	s_setprio 1
	s_waitcnt lgkmcnt(0)
	v_mfma_f32_16x16x32_bf16 v[124:127], v[128:131], v[188:191], v[124:127]
	v_mfma_f32_16x16x32_bf16 v[124:127], v[132:135], v[192:195], v[124:127]
	v_mfma_f32_16x16x32_bf16 v[120:123], v[140:143], v[192:195], v[120:123]
	v_mfma_f32_16x16x32_bf16 v[120:123], v[136:139], v[188:191], v[120:123]
	v_mfma_f32_16x16x32_bf16 v[116:119], v[144:147], v[188:191], v[116:119]
	v_mfma_f32_16x16x32_bf16 v[116:119], v[148:151], v[192:195], v[116:119]
	v_mfma_f32_16x16x32_bf16 v[112:115], v[184:187], v[192:195], v[112:115]
	v_mfma_f32_16x16x32_bf16 v[112:115], v[176:179], v[188:191], v[112:115]
	v_mfma_f32_16x16x32_bf16 v[96:99], v[176:179], v[196:199], v[96:99]
	v_mfma_f32_16x16x32_bf16 v[96:99], v[184:187], v[200:203], v[96:99]
	v_mfma_f32_16x16x32_bf16 v[100:103], v[148:151], v[200:203], v[100:103]
	v_mfma_f32_16x16x32_bf16 v[100:103], v[144:147], v[196:199], v[100:103]
	v_mfma_f32_16x16x32_bf16 v[104:107], v[136:139], v[196:199], v[104:107]
	v_mfma_f32_16x16x32_bf16 v[104:107], v[140:143], v[200:203], v[104:107]
	v_mfma_f32_16x16x32_bf16 v[108:111], v[132:135], v[200:203], v[108:111]
	v_mfma_f32_16x16x32_bf16 v[108:111], v[128:131], v[196:199], v[108:111]
	s_setprio 0
	s_setprio 1
	v_mfma_f32_16x16x32_bf16 v[92:95], v[128:131], v[208:211], v[92:95]
	v_mfma_f32_16x16x32_bf16 v[92:95], v[132:135], v[212:215], v[92:95]
	v_mfma_f32_16x16x32_bf16 v[88:91], v[140:143], v[212:215], v[88:91]
	v_mfma_f32_16x16x32_bf16 v[88:91], v[136:139], v[208:211], v[88:91]
	v_mfma_f32_16x16x32_bf16 v[84:87], v[144:147], v[208:211], v[84:87]
	v_mfma_f32_16x16x32_bf16 v[84:87], v[148:151], v[212:215], v[84:87]
	v_mfma_f32_16x16x32_bf16 v[80:83], v[184:187], v[212:215], v[80:83]
	v_mfma_f32_16x16x32_bf16 v[80:83], v[176:179], v[208:211], v[80:83]
	v_mfma_f32_16x16x32_bf16 v[64:67], v[176:179], v[216:219], v[64:67]
	v_mfma_f32_16x16x32_bf16 v[64:67], v[184:187], v[220:223], v[64:67]
	v_mfma_f32_16x16x32_bf16 v[68:71], v[148:151], v[220:223], v[68:71]
	v_mfma_f32_16x16x32_bf16 v[68:71], v[144:147], v[216:219], v[68:71]
	v_mfma_f32_16x16x32_bf16 v[72:75], v[136:139], v[216:219], v[72:75]
	v_mfma_f32_16x16x32_bf16 v[72:75], v[140:143], v[220:223], v[72:75]
	v_mfma_f32_16x16x32_bf16 v[76:79], v[132:135], v[220:223], v[76:79]
	v_mfma_f32_16x16x32_bf16 v[76:79], v[128:131], v[216:219], v[76:79]
	s_setprio 0
	s_barrier
	s_add_i32 s21, s59, s46
	v_lshl_add_u64 v[224:225], s[10:11], 0, v[154:155]
	s_mov_b32 m0, s21
	ds_read_b128 v[188:191], v181 offset:16384
	ds_read_b128 v[192:195], v181 offset:17408
	ds_read_b128 v[196:199], v181 offset:18432
	ds_read_b128 v[200:203], v181 offset:19456
	ds_read_b128 v[208:211], v181 offset:20480
	ds_read_b128 v[212:215], v181 offset:21504
	ds_read_b128 v[216:219], v181 offset:22528
	ds_read_b128 v[220:223], v181 offset:23552
	global_load_lds_dwordx4 v[224:225], off
	s_add_i32 m0, s21, 0x2000
	s_add_u32 s68, s10, 0x80000
	v_lshl_add_u64 v[226:227], s[10:11], 0, v[158:159]
	s_addc_u32 s69, s11, 0
	s_add_i32 s21, s60, s46
	global_load_lds_dwordx4 v[226:227], off
	v_lshl_add_u64 v[230:231], s[68:69], 0, v[154:155]
	s_mov_b32 m0, s21
	v_lshl_add_u64 v[232:233], s[12:13], 0, v[156:157]
	global_load_lds_dwordx4 v[230:231], off
	v_lshl_add_u64 v[230:231], s[68:69], 0, v[158:159]
	s_add_i32 m0, s21, 0x2000
	s_nop 0
	global_load_lds_dwordx4 v[230:231], off
	v_lshl_add_u64 v[230:231], s[12:13], 0, v[152:153]
	s_mov_b32 m0, s47
	s_nop 0
	global_load_lds_dwordx4 v[230:231], off
	s_mov_b32 m0, s48
	s_nop 0
	global_load_lds_dwordx4 v[232:233], off
	s_waitcnt vmcnt(8)
	s_waitcnt lgkmcnt(0)
	s_barrier
; #define PG8_STAGE(bufoff, gbase, voff) do { _Pragma("unroll") for (int _i = 0; _i < 2; ++_i) \
;         __builtin_amdgcn_global_load_lds((const unsigned*)((const char*)(gbase) + (voff)[_i]), (LAS unsigned*)(lds + (bufoff) + ldsw + _i * 8192), 16, 0, 0); } while (0)
; #define PG8_LDA(dst, b, h) do { _Pragma("unroll") for (int m = 0; m < 4; ++m) _Pragma("unroll") for (int k = 0; k < 2; ++k) dst[m][k] = *(const LAS bf16x8*)(lds + PG8_SA(b, h) + aoff + m * 2048 + k * 1024); } while (0)
; #define PG8_LDB(dst, b, h) do { _Pragma("unroll") for (int n = 0; n < 2; ++n) _Pragma("unroll") for (int k = 0; k < 2; ++k) dst[n][k] = *(const LAS bf16x8*)(lds + PG8_SB(b, h) + boff + n * 2048 + k * 1024); } while (0)
; #define PG8_MMA(ai, bj, At, Bt) do { __builtin_amdgcn_s_setprio(1); _Pragma("unroll") for (int m = 0; m < 4; ++m) _Pragma("unroll") for (int n = 0; n < 2; ++n) _Pragma("unroll") for (int k = 0; k < 2; ++k) \
;         acc[ai][bj][m][n] = __builtin_amdgcn_mfma_f32_16x16x32_bf16(Bt[n][k], At[m][k], acc[ai][bj][m][n], 0, 0, 0); __builtin_amdgcn_s_setprio(0); } while (0)
; #define PG8_WAIT_V(n) asm volatile("s_waitcnt vmcnt(" #n ")" ::: "memory")
; #define PG8_WAIT_L(n) asm volatile("s_waitcnt lgkmcnt(" #n ")" ::: "memory")
; #define PG8_BAR __builtin_amdgcn_s_barrier()
; #define PG8_SCHED __builtin_amdgcn_sched_barrier(0)
; template <class Epi>
; __device__ __forceinline__ void gemm_phase(LAS unsigned char* lds, const Gemm g, const StaticOrder& S, const Epi& E) {
;     ...
;             PG8_WAIT_V(8); PG8_WAIT_L(0); PG8_BAR; PG8_MMA(1, 0, At, B0); PG8_MMA(1, 1, At, B1); PG8_BAR; PG8_SCHED;
;             PG8_LDB(B0, 1, 0); PG8_LDB(B1, 1, 1); PG8_SCHED; PG8_LDA(At, 1, 0); PG8_STAGE(PG8_SA(0, 1), a2 + hstepA, voffA);
;             PG8_WAIT_V(8); PG8_WAIT_L(0); PG8_BAR; PG8_MMA(0, 0, At, B0); PG8_MMA(0, 1, At, B1); PG8_BAR; PG8_SCHED;
	s_setprio 1
	s_waitcnt lgkmcnt(0)
	v_mfma_f32_16x16x32_bf16 v[60:63], v[128:131], v[188:191], v[60:63]
	v_mfma_f32_16x16x32_bf16 v[60:63], v[132:135], v[192:195], v[60:63]
	v_mfma_f32_16x16x32_bf16 v[56:59], v[140:143], v[192:195], v[56:59]
	v_mfma_f32_16x16x32_bf16 v[56:59], v[136:139], v[188:191], v[56:59]
	v_mfma_f32_16x16x32_bf16 v[52:55], v[144:147], v[188:191], v[52:55]
	v_mfma_f32_16x16x32_bf16 v[52:55], v[148:151], v[192:195], v[52:55]
	v_mfma_f32_16x16x32_bf16 v[48:51], v[184:187], v[192:195], v[48:51]
	v_mfma_f32_16x16x32_bf16 v[48:51], v[176:179], v[188:191], v[48:51]
	v_mfma_f32_16x16x32_bf16 v[32:35], v[176:179], v[196:199], v[32:35]
	v_mfma_f32_16x16x32_bf16 v[32:35], v[184:187], v[200:203], v[32:35]
	v_mfma_f32_16x16x32_bf16 v[36:39], v[148:151], v[200:203], v[36:39]
	v_mfma_f32_16x16x32_bf16 v[36:39], v[144:147], v[196:199], v[36:39]
	v_mfma_f32_16x16x32_bf16 v[40:43], v[136:139], v[196:199], v[40:43]
	v_mfma_f32_16x16x32_bf16 v[40:43], v[140:143], v[200:203], v[40:43]
	v_mfma_f32_16x16x32_bf16 v[44:47], v[132:135], v[200:203], v[44:47]
	v_mfma_f32_16x16x32_bf16 v[44:47], v[128:131], v[196:199], v[44:47]
	s_setprio 0
	s_setprio 1
	v_mfma_f32_16x16x32_bf16 v[28:31], v[128:131], v[208:211], v[28:31]
	v_mfma_f32_16x16x32_bf16 v[28:31], v[132:135], v[212:215], v[28:31]
	v_mfma_f32_16x16x32_bf16 v[24:27], v[140:143], v[212:215], v[24:27]
	v_mfma_f32_16x16x32_bf16 v[24:27], v[136:139], v[208:211], v[24:27]
	v_mfma_f32_16x16x32_bf16 v[20:23], v[144:147], v[208:211], v[20:23]
	v_mfma_f32_16x16x32_bf16 v[20:23], v[148:151], v[212:215], v[20:23]
	v_mfma_f32_16x16x32_bf16 v[16:19], v[184:187], v[212:215], v[16:19]
	v_mfma_f32_16x16x32_bf16 v[16:19], v[176:179], v[208:211], v[16:19]
	v_mfma_f32_16x16x32_bf16 v[0:3], v[176:179], v[216:219], v[0:3]
	v_mfma_f32_16x16x32_bf16 v[0:3], v[184:187], v[220:223], v[0:3]
	v_mfma_f32_16x16x32_bf16 v[4:7], v[148:151], v[220:223], v[4:7]
	v_mfma_f32_16x16x32_bf16 v[4:7], v[144:147], v[216:219], v[4:7]
	v_mfma_f32_16x16x32_bf16 v[8:11], v[136:139], v[216:219], v[8:11]
	v_mfma_f32_16x16x32_bf16 v[8:11], v[140:143], v[220:223], v[8:11]
	v_mfma_f32_16x16x32_bf16 v[12:15], v[132:135], v[220:223], v[12:15]
	v_mfma_f32_16x16x32_bf16 v[12:15], v[128:131], v[216:219], v[12:15]
	s_setprio 0
	s_barrier
	s_add_i32 s21, 0, 0x18000
	s_add_i32 s33, 0, 0x1c000
	v_add_u32_e32 v140, s21, v163
	v_add_u32_e32 v172, s33, v163
	ds_read_b128 v[128:131], v140
	ds_read_b128 v[132:135], v140 offset:1024
	ds_read_b128 v[136:139], v140 offset:2048
	ds_read_b128 v[140:143], v140 offset:3072
	ds_read_b128 v[144:147], v172
	ds_read_b128 v[148:151], v172 offset:1024
	ds_read_b128 v[176:179], v172 offset:2048
	ds_read_b128 v[184:187], v172 offset:3072
	s_add_u32 s12, s12, 0x80000
	s_addc_u32 s13, s13, 0
	s_mov_b32 m0, s49
	v_lshl_add_u64 v[234:235], s[12:13], 0, v[152:153]
	ds_read_b128 v[188:191], v181 offset:32768
	ds_read_b128 v[192:195], v181 offset:33792
	ds_read_b128 v[196:199], v181 offset:34816
	ds_read_b128 v[200:203], v181 offset:35840
	ds_read_b128 v[208:211], v181 offset:36864
	ds_read_b128 v[212:215], v181 offset:37888
	ds_read_b128 v[216:219], v181 offset:38912
	ds_read_b128 v[220:223], v181 offset:39936
	global_load_lds_dwordx4 v[234:235], off
	v_lshl_add_u64 v[234:235], s[12:13], 0, v[156:157]
	s_mov_b32 m0, s50
	s_nop 0
	global_load_lds_dwordx4 v[234:235], off
	s_waitcnt vmcnt(8)
	s_waitcnt lgkmcnt(0)
	s_barrier
	s_setprio 1
	s_waitcnt lgkmcnt(0)
	v_mfma_f32_16x16x32_bf16 v[124:127], v[128:131], v[188:191], v[124:127]
	v_mfma_f32_16x16x32_bf16 v[124:127], v[132:135], v[192:195], v[124:127]
	v_mfma_f32_16x16x32_bf16 v[120:123], v[140:143], v[192:195], v[120:123]
	v_mfma_f32_16x16x32_bf16 v[120:123], v[136:139], v[188:191], v[120:123]
	v_mfma_f32_16x16x32_bf16 v[116:119], v[144:147], v[188:191], v[116:119]
	v_mfma_f32_16x16x32_bf16 v[116:119], v[148:151], v[192:195], v[116:119]
	v_mfma_f32_16x16x32_bf16 v[112:115], v[184:187], v[192:195], v[112:115]
	v_mfma_f32_16x16x32_bf16 v[112:115], v[176:179], v[188:191], v[112:115]
	v_mfma_f32_16x16x32_bf16 v[96:99], v[176:179], v[196:199], v[96:99]
	v_mfma_f32_16x16x32_bf16 v[96:99], v[184:187], v[200:203], v[96:99]
	v_mfma_f32_16x16x32_bf16 v[100:103], v[148:151], v[200:203], v[100:103]
	v_mfma_f32_16x16x32_bf16 v[100:103], v[144:147], v[196:199], v[100:103]
	v_mfma_f32_16x16x32_bf16 v[104:107], v[136:139], v[196:199], v[104:107]
	v_mfma_f32_16x16x32_bf16 v[104:107], v[140:143], v[200:203], v[104:107]
	v_mfma_f32_16x16x32_bf16 v[108:111], v[132:135], v[200:203], v[108:111]
	v_mfma_f32_16x16x32_bf16 v[108:111], v[128:131], v[196:199], v[108:111]
	s_setprio 0
	s_setprio 1
	v_mfma_f32_16x16x32_bf16 v[92:95], v[128:131], v[208:211], v[92:95]
	v_mfma_f32_16x16x32_bf16 v[92:95], v[132:135], v[212:215], v[92:95]
	v_mfma_f32_16x16x32_bf16 v[88:91], v[140:143], v[212:215], v[88:91]
	v_mfma_f32_16x16x32_bf16 v[88:91], v[136:139], v[208:211], v[88:91]
	v_mfma_f32_16x16x32_bf16 v[84:87], v[144:147], v[208:211], v[84:87]
	v_mfma_f32_16x16x32_bf16 v[84:87], v[148:151], v[212:215], v[84:87]
	v_mfma_f32_16x16x32_bf16 v[80:83], v[184:187], v[212:215], v[80:83]
	v_mfma_f32_16x16x32_bf16 v[80:83], v[176:179], v[208:211], v[80:83]
	v_mfma_f32_16x16x32_bf16 v[64:67], v[176:179], v[216:219], v[64:67]
	v_mfma_f32_16x16x32_bf16 v[64:67], v[184:187], v[220:223], v[64:67]
	v_mfma_f32_16x16x32_bf16 v[68:71], v[148:151], v[220:223], v[68:71]
	v_mfma_f32_16x16x32_bf16 v[68:71], v[144:147], v[216:219], v[68:71]
	v_mfma_f32_16x16x32_bf16 v[72:75], v[136:139], v[216:219], v[72:75]
	v_mfma_f32_16x16x32_bf16 v[72:75], v[140:143], v[220:223], v[72:75]
	v_mfma_f32_16x16x32_bf16 v[76:79], v[132:135], v[220:223], v[76:79]
	v_mfma_f32_16x16x32_bf16 v[76:79], v[128:131], v[216:219], v[76:79]
	s_setprio 0
	s_barrier
; #define PG8_STAGE(bufoff, gbase, voff) do { _Pragma("unroll") for (int _i = 0; _i < 2; ++_i) \
;         __builtin_amdgcn_global_load_lds((const unsigned*)((const char*)(gbase) + (voff)[_i]), (LAS unsigned*)(lds + (bufoff) + ldsw + _i * 8192), 16, 0, 0); } while (0)
; #define PG8_LDA(dst, b, h) do { _Pragma("unroll") for (int m = 0; m < 4; ++m) _Pragma("unroll") for (int k = 0; k < 2; ++k) dst[m][k] = *(const LAS bf16x8*)(lds + PG8_SA(b, h) + aoff + m * 2048 + k * 1024); } while (0)
; #define PG8_MMA(ai, bj, At, Bt) do { __builtin_amdgcn_s_setprio(1); _Pragma("unroll") for (int m = 0; m < 4; ++m) _Pragma("unroll") for (int n = 0; n < 2; ++n) _Pragma("unroll") for (int k = 0; k < 2; ++k) \
;         acc[ai][bj][m][n] = __builtin_amdgcn_mfma_f32_16x16x32_bf16(Bt[n][k], At[m][k], acc[ai][bj][m][n], 0, 0, 0); __builtin_amdgcn_s_setprio(0); } while (0)
; #define PG8_WAIT_V(n) asm volatile("s_waitcnt vmcnt(" #n ")" ::: "memory")
; #define PG8_WAIT_L(n) asm volatile("s_waitcnt lgkmcnt(" #n ")" ::: "memory")
; #define PG8_BAR __builtin_amdgcn_s_barrier()
; #define PG8_SCHED __builtin_amdgcn_sched_barrier(0)
; template <class Epi>
; __device__ __forceinline__ void gemm_phase(LAS unsigned char* lds, const Gemm g, const StaticOrder& S, const Epi& E) {
;     ...
;             PG8_LDA(At, 1, 1); PG8_STAGE(PG8_SB(1, 0), b3, voffB); PG8_STAGE(PG8_SB(1, 1), b3 + hstepB, voffB); PG8_STAGE(PG8_SA(1, 0), a3, voffA);
;             PG8_WAIT_V(8); PG8_WAIT_L(0); PG8_BAR; PG8_MMA(1, 0, At, B0); PG8_MMA(1, 1, At, B1); PG8_BAR; PG8_SCHED;
;         }
	s_add_i32 s12, s21, s46
	v_lshl_add_u64 v[224:225], v[224:225], 0, s[28:29]
	s_mov_b32 m0, s12
	ds_read_b128 v[188:191], v181 offset:49152
	ds_read_b128 v[192:195], v181 offset:50176
	ds_read_b128 v[196:199], v181 offset:51200
	ds_read_b128 v[200:203], v181 offset:52224
	ds_read_b128 v[208:211], v181 offset:53248
	ds_read_b128 v[212:215], v181 offset:54272
	ds_read_b128 v[216:219], v181 offset:55296
	ds_read_b128 v[220:223], v181 offset:56320
	global_load_lds_dwordx4 v[224:225], off
	s_add_i32 m0, s12, 0x2000
	s_add_u32 s10, s10, 0x80080
	v_lshl_add_u64 v[224:225], v[226:227], 0, s[28:29]
	s_addc_u32 s11, s11, 0
	s_add_i32 s12, s33, s46
	global_load_lds_dwordx4 v[224:225], off
	v_lshl_add_u64 v[224:225], s[10:11], 0, v[154:155]
	s_mov_b32 m0, s12
	s_nop 0
	global_load_lds_dwordx4 v[224:225], off
	v_lshl_add_u64 v[224:225], s[10:11], 0, v[158:159]
	s_add_i32 m0, s12, 0x2000
	s_nop 0
	global_load_lds_dwordx4 v[224:225], off
	v_lshl_add_u64 v[224:225], v[230:231], 0, s[28:29]
	s_mov_b32 m0, s54
	s_nop 0
	global_load_lds_dwordx4 v[224:225], off
	v_lshl_add_u64 v[224:225], v[232:233], 0, s[28:29]
	s_mov_b32 m0, s55
	s_nop 0
	global_load_lds_dwordx4 v[224:225], off
	s_waitcnt vmcnt(8)
	s_waitcnt lgkmcnt(0)
	s_barrier
	s_setprio 1
	s_waitcnt lgkmcnt(0)
	v_mfma_f32_16x16x32_bf16 v[60:63], v[128:131], v[188:191], v[60:63]
	v_mfma_f32_16x16x32_bf16 v[60:63], v[132:135], v[192:195], v[60:63]
	v_mfma_f32_16x16x32_bf16 v[56:59], v[140:143], v[192:195], v[56:59]
	v_mfma_f32_16x16x32_bf16 v[56:59], v[136:139], v[188:191], v[56:59]
	v_mfma_f32_16x16x32_bf16 v[52:55], v[144:147], v[188:191], v[52:55]
	v_mfma_f32_16x16x32_bf16 v[52:55], v[148:151], v[192:195], v[52:55]
	v_mfma_f32_16x16x32_bf16 v[48:51], v[184:187], v[192:195], v[48:51]
	v_mfma_f32_16x16x32_bf16 v[48:51], v[176:179], v[188:191], v[48:51]
	v_mfma_f32_16x16x32_bf16 v[32:35], v[176:179], v[196:199], v[32:35]
	v_mfma_f32_16x16x32_bf16 v[32:35], v[184:187], v[200:203], v[32:35]
	v_mfma_f32_16x16x32_bf16 v[36:39], v[148:151], v[200:203], v[36:39]
	v_mfma_f32_16x16x32_bf16 v[36:39], v[144:147], v[196:199], v[36:39]
	v_mfma_f32_16x16x32_bf16 v[40:43], v[136:139], v[196:199], v[40:43]
	v_mfma_f32_16x16x32_bf16 v[40:43], v[140:143], v[200:203], v[40:43]
	v_mfma_f32_16x16x32_bf16 v[44:47], v[132:135], v[200:203], v[44:47]
	v_mfma_f32_16x16x32_bf16 v[44:47], v[128:131], v[196:199], v[44:47]
	s_setprio 0
	s_setprio 1
	v_mfma_f32_16x16x32_bf16 v[28:31], v[128:131], v[208:211], v[28:31]
	v_mfma_f32_16x16x32_bf16 v[28:31], v[132:135], v[212:215], v[28:31]
	v_mfma_f32_16x16x32_bf16 v[24:27], v[140:143], v[212:215], v[24:27]
	v_mfma_f32_16x16x32_bf16 v[24:27], v[136:139], v[208:211], v[24:27]
	v_mfma_f32_16x16x32_bf16 v[20:23], v[144:147], v[208:211], v[20:23]
	v_mfma_f32_16x16x32_bf16 v[20:23], v[148:151], v[212:215], v[20:23]
	v_mfma_f32_16x16x32_bf16 v[16:19], v[184:187], v[212:215], v[16:19]
	v_mfma_f32_16x16x32_bf16 v[16:19], v[176:179], v[208:211], v[16:19]
	v_mfma_f32_16x16x32_bf16 v[0:3], v[176:179], v[216:219], v[0:3]
	v_mfma_f32_16x16x32_bf16 v[0:3], v[184:187], v[220:223], v[0:3]
	v_mfma_f32_16x16x32_bf16 v[4:7], v[148:151], v[220:223], v[4:7]
	v_mfma_f32_16x16x32_bf16 v[4:7], v[144:147], v[216:219], v[4:7]
	v_mfma_f32_16x16x32_bf16 v[8:11], v[136:139], v[216:219], v[8:11]
	v_mfma_f32_16x16x32_bf16 v[8:11], v[140:143], v[220:223], v[8:11]
	v_mfma_f32_16x16x32_bf16 v[12:15], v[132:135], v[220:223], v[12:15]
	v_mfma_f32_16x16x32_bf16 v[12:15], v[128:131], v[216:219], v[12:15]
	s_add_u32 s8, s8, 0x100
	s_addc_u32 s9, s9, 0
	s_add_u32 s18, s18, 0x100
	s_addc_u32 s19, s19, 0
	s_cmp_ge_i32 s20, s53
	s_mov_b32 s10, s20
	s_setprio 0
	s_barrier
	s_cbranch_scc0 .LBB0_1338
